# GEMM main loops: the s_setprio 0 / s_setprio 1 flip in the middle of each 32-MFMA burst removed (priority stays raised over the whole burst)
# speedup vs baseline: 1.0057x; 1.0000x over previous
; #define PG8_STAGE(bufoff, gbase, voff) do { _Pragma("unroll") for (int _i = 0; _i < 2; ++_i) \
;         __builtin_amdgcn_global_load_lds((const unsigned*)((const char*)(gbase) + (voff)[_i]), (LAS unsigned*)(lds + (bufoff) + ldsw + _i * 8192), 16, 0, 0); } while (0)
; #define PG8_LDA(dst, b, h) do { _Pragma("unroll") for (int m = 0; m < 4; ++m) _Pragma("unroll") for (int k = 0; k < 2; ++k) dst[m][k] = *(const LAS bf16x8*)(lds + PG8_SA(b, h) + aoff + m * 2048 + k * 1024); } while (0)
; #define PG8_LDB(dst, b, h) do { _Pragma("unroll") for (int n = 0; n < 2; ++n) _Pragma("unroll") for (int k = 0; k < 2; ++k) dst[n][k] = *(const LAS bf16x8*)(lds + PG8_SB(b, h) + boff + n * 2048 + k * 1024); } while (0)
; #define PG8_MMA(ai, bj, At, Bt) do { __builtin_amdgcn_s_setprio(1); _Pragma("unroll") for (int m = 0; m < 4; ++m) _Pragma("unroll") for (int n = 0; n < 2; ++n) _Pragma("unroll") for (int k = 0; k < 2; ++k) \
;         acc[ai][bj][m][n] = __builtin_amdgcn_mfma_f32_16x16x32_bf16(Bt[n][k], At[m][k], acc[ai][bj][m][n], 0, 0, 0); __builtin_amdgcn_s_setprio(0); } while (0)
; #define PG8_WAIT_V(n) asm volatile("s_waitcnt vmcnt(" #n ")" ::: "memory")
; #define PG8_WAIT_L(n) asm volatile("s_waitcnt lgkmcnt(" #n ")" ::: "memory")
; #define PG8_BAR __builtin_amdgcn_s_barrier()
; #define PG8_SCHED __builtin_amdgcn_sched_barrier(0)
; template <class Epi>
; __device__ __forceinline__ void gemm_phase(LAS unsigned char* lds, const Gemm g, const Sched& S, const Epi& E) {
;     ...
;             const bool last = (t == nt - 2);
;             const char* a1 = cA + (size_t)(t + 1) * kstep;
;             const char* a2 = last ? nA : cA + (size_t)(t + 2) * kstep; const char* b2 = last ? nB : cB + (size_t)(t + 2) * kstep;
;             const char* a3 = a2 + kstep; const char* b3 = b2 + kstep;
;             PG8_LDB(B0, 0, 0); PG8_LDB(B1, 0, 1); PG8_SCHED; PG8_LDA(At, 0, 0); PG8_STAGE(PG8_SA(1, 1), a1 + hstepA, voffA);
;             PG8_WAIT_V(8); PG8_WAIT_L(0); PG8_BAR; PG8_MMA(0, 0, At, B0); PG8_MMA(0, 1, At, B1); PG8_BAR; PG8_SCHED;
;             PG8_LDA(At, 0, 1); PG8_STAGE(PG8_SB(0, 0), b2, voffB); PG8_STAGE(PG8_SB(0, 1), b2 + hstepB, voffB); PG8_STAGE(PG8_SA(0, 0), a2, voffA);
;             PG8_WAIT_V(8); PG8_WAIT_L(0); PG8_BAR; PG8_MMA(1, 0, At, B0); PG8_MMA(1, 1, At, B1); PG8_BAR; PG8_SCHED;
.LBB0_163:
	ds_read_b128 v[148:151], v145
	ds_read_b128 v[152:155], v145 offset:1024
	ds_read_b128 v[156:159], v145 offset:2048
	ds_read_b128 v[160:163], v145 offset:3072
	ds_read_b128 v[164:167], v146
	ds_read_b128 v[168:171], v146 offset:1024
	ds_read_b128 v[172:175], v146 offset:2048
	ds_read_b128 v[176:179], v146 offset:3072
	s_add_u32 s44, s40, 0xfffc0080
	s_addc_u32 s45, s41, -1
	s_cmp_eq_u32 s67, 12
	s_cselect_b32 s47, s21, s45
	s_cselect_b32 s46, s27, s44
	s_cselect_b32 s45, s15, s66
	s_cselect_b32 s44, s64, s65
	v_lshl_add_u64 v[140:141], s[40:41], 0, v[136:137]
	s_add_i32 m0, s29, 0xc000
	ds_read_b128 v[180:183], v147
	ds_read_b128 v[184:187], v147 offset:1024
	ds_read_b128 v[188:191], v147 offset:2048
	ds_read_b128 v[192:195], v147 offset:3072
	ds_read_b128 v[196:199], v147 offset:4096
	ds_read_b128 v[204:207], v147 offset:5120
	ds_read_b128 v[208:211], v147 offset:6144
	ds_read_b128 v[212:215], v147 offset:7168
	global_load_lds_dwordx4 v[140:141], off
	v_lshl_add_u64 v[140:141], s[40:41], 0, v[138:139]
	s_add_i32 m0, s29, 0xe000
	s_nop 0
	global_load_lds_dwordx4 v[140:141], off
	s_waitcnt vmcnt(8)
	s_waitcnt lgkmcnt(0)
	s_barrier
	s_setprio 1
	s_waitcnt lgkmcnt(0)
	v_mfma_f32_16x16x32_bf16 v[116:119], v[148:151], v[180:183], v[116:119]
	v_mfma_f32_16x16x32_bf16 v[124:127], v[156:159], v[180:183], v[124:127]
	v_mfma_f32_16x16x32_bf16 v[100:103], v[148:151], v[188:191], v[100:103]
	v_mfma_f32_16x16x32_bf16 v[108:111], v[156:159], v[188:191], v[108:111]
	v_mfma_f32_16x16x32_bf16 v[84:87], v[148:151], v[196:199], v[84:87]
	v_mfma_f32_16x16x32_bf16 v[92:95], v[156:159], v[196:199], v[92:95]
	v_mfma_f32_16x16x32_bf16 v[68:71], v[148:151], v[208:211], v[68:71]
	v_mfma_f32_16x16x32_bf16 v[76:79], v[156:159], v[208:211], v[76:79]
	v_mfma_f32_16x16x32_bf16 v[116:119], v[152:155], v[184:187], v[116:119]
	v_mfma_f32_16x16x32_bf16 v[124:127], v[160:163], v[184:187], v[124:127]
	v_mfma_f32_16x16x32_bf16 v[100:103], v[152:155], v[192:195], v[100:103]
	v_mfma_f32_16x16x32_bf16 v[108:111], v[160:163], v[192:195], v[108:111]
	v_mfma_f32_16x16x32_bf16 v[84:87], v[152:155], v[204:207], v[84:87]
	v_mfma_f32_16x16x32_bf16 v[92:95], v[160:163], v[204:207], v[92:95]
	v_mfma_f32_16x16x32_bf16 v[68:71], v[152:155], v[212:215], v[68:71]
	v_mfma_f32_16x16x32_bf16 v[76:79], v[160:163], v[212:215], v[76:79]
	v_mfma_f32_16x16x32_bf16 v[112:115], v[164:167], v[180:183], v[112:115]
	v_mfma_f32_16x16x32_bf16 v[120:123], v[172:175], v[180:183], v[120:123]
	v_mfma_f32_16x16x32_bf16 v[96:99], v[164:167], v[188:191], v[96:99]
	v_mfma_f32_16x16x32_bf16 v[104:107], v[172:175], v[188:191], v[104:107]
	v_mfma_f32_16x16x32_bf16 v[80:83], v[164:167], v[196:199], v[80:83]
	v_mfma_f32_16x16x32_bf16 v[88:91], v[172:175], v[196:199], v[88:91]
	v_mfma_f32_16x16x32_bf16 v[64:67], v[164:167], v[208:211], v[64:67]
	v_mfma_f32_16x16x32_bf16 v[72:75], v[172:175], v[208:211], v[72:75]
	v_mfma_f32_16x16x32_bf16 v[112:115], v[168:171], v[184:187], v[112:115]
	v_mfma_f32_16x16x32_bf16 v[120:123], v[176:179], v[184:187], v[120:123]
	v_mfma_f32_16x16x32_bf16 v[96:99], v[168:171], v[192:195], v[96:99]
	v_mfma_f32_16x16x32_bf16 v[104:107], v[176:179], v[192:195], v[104:107]
	v_mfma_f32_16x16x32_bf16 v[80:83], v[168:171], v[204:207], v[80:83]
	v_mfma_f32_16x16x32_bf16 v[88:91], v[176:179], v[204:207], v[88:91]
	v_mfma_f32_16x16x32_bf16 v[64:67], v[168:171], v[212:215], v[64:67]
	v_mfma_f32_16x16x32_bf16 v[72:75], v[176:179], v[212:215], v[72:75]
	s_setprio 0
	s_barrier
	s_add_i32 s78, s60, s53
	v_lshl_add_u64 v[140:141], s[44:45], 0, v[130:131]
	s_mov_b32 m0, s78
	ds_read_b128 v[180:183], v147 offset:16384
	ds_read_b128 v[184:187], v147 offset:17408
	ds_read_b128 v[188:191], v147 offset:18432
	ds_read_b128 v[192:195], v147 offset:19456
	ds_read_b128 v[196:199], v147 offset:20480
	ds_read_b128 v[204:207], v147 offset:21504
	ds_read_b128 v[208:211], v147 offset:22528
	ds_read_b128 v[212:215], v147 offset:23552
	global_load_lds_dwordx4 v[140:141], off
	s_add_i32 m0, s78, 0x2000
	s_add_u32 s78, s44, 0x40000
	v_lshl_add_u64 v[200:201], s[44:45], 0, v[134:135]
	s_addc_u32 s79, s45, 0
	s_add_i32 s82, s61, s53
	global_load_lds_dwordx4 v[200:201], off
	v_lshl_add_u64 v[216:217], s[78:79], 0, v[130:131]
	s_mov_b32 m0, s82
	v_lshl_add_u64 v[218:219], s[46:47], 0, v[132:133]
	global_load_lds_dwordx4 v[216:217], off
	v_lshl_add_u64 v[216:217], s[78:79], 0, v[134:135]
	s_add_i32 m0, s82, 0x2000
	s_nop 0
	global_load_lds_dwordx4 v[216:217], off
	v_lshl_add_u64 v[216:217], s[46:47], 0, v[128:129]
	s_mov_b32 m0, s29
	s_nop 0
	global_load_lds_dwordx4 v[216:217], off
	s_mov_b32 m0, s54
	s_nop 0
	global_load_lds_dwordx4 v[218:219], off
	s_waitcnt vmcnt(8)
	s_waitcnt lgkmcnt(0)
	s_barrier
; #define PG8_STAGE(bufoff, gbase, voff) do { _Pragma("unroll") for (int _i = 0; _i < 2; ++_i) \
;         __builtin_amdgcn_global_load_lds((const unsigned*)((const char*)(gbase) + (voff)[_i]), (LAS unsigned*)(lds + (bufoff) + ldsw + _i * 8192), 16, 0, 0); } while (0)
; #define PG8_LDA(dst, b, h) do { _Pragma("unroll") for (int m = 0; m < 4; ++m) _Pragma("unroll") for (int k = 0; k < 2; ++k) dst[m][k] = *(const LAS bf16x8*)(lds + PG8_SA(b, h) + aoff + m * 2048 + k * 1024); } while (0)
; #define PG8_LDB(dst, b, h) do { _Pragma("unroll") for (int n = 0; n < 2; ++n) _Pragma("unroll") for (int k = 0; k < 2; ++k) dst[n][k] = *(const LAS bf16x8*)(lds + PG8_SB(b, h) + boff + n * 2048 + k * 1024); } while (0)
; #define PG8_MMA(ai, bj, At, Bt) do { __builtin_amdgcn_s_setprio(1); _Pragma("unroll") for (int m = 0; m < 4; ++m) _Pragma("unroll") for (int n = 0; n < 2; ++n) _Pragma("unroll") for (int k = 0; k < 2; ++k) \
;         acc[ai][bj][m][n] = __builtin_amdgcn_mfma_f32_16x16x32_bf16(Bt[n][k], At[m][k], acc[ai][bj][m][n], 0, 0, 0); __builtin_amdgcn_s_setprio(0); } while (0)
; #define PG8_WAIT_V(n) asm volatile("s_waitcnt vmcnt(" #n ")" ::: "memory")
; #define PG8_WAIT_L(n) asm volatile("s_waitcnt lgkmcnt(" #n ")" ::: "memory")
; #define PG8_BAR __builtin_amdgcn_s_barrier()
; #define PG8_SCHED __builtin_amdgcn_sched_barrier(0)
; template <class Epi>
; __device__ __forceinline__ void gemm_phase(LAS unsigned char* lds, const Gemm g, const Sched& S, const Epi& E) {
;     ...
;             PG8_WAIT_V(8); PG8_WAIT_L(0); PG8_BAR; PG8_MMA(1, 0, At, B0); PG8_MMA(1, 1, At, B1); PG8_BAR; PG8_SCHED;
;             PG8_LDB(B0, 1, 0); PG8_LDB(B1, 1, 1); PG8_SCHED; PG8_LDA(At, 1, 0); PG8_STAGE(PG8_SA(0, 1), a2 + hstepA, voffA);
;             PG8_WAIT_V(8); PG8_WAIT_L(0); PG8_BAR; PG8_MMA(0, 0, At, B0); PG8_MMA(0, 1, At, B1); PG8_BAR; PG8_SCHED;
	s_setprio 1
	s_waitcnt lgkmcnt(0)
	v_mfma_f32_16x16x32_bf16 v[52:55], v[148:151], v[180:183], v[52:55]
	v_mfma_f32_16x16x32_bf16 v[60:63], v[156:159], v[180:183], v[60:63]
	v_mfma_f32_16x16x32_bf16 v[36:39], v[148:151], v[188:191], v[36:39]
	v_mfma_f32_16x16x32_bf16 v[44:47], v[156:159], v[188:191], v[44:47]
	v_mfma_f32_16x16x32_bf16 v[20:23], v[148:151], v[196:199], v[20:23]
	v_mfma_f32_16x16x32_bf16 v[28:31], v[156:159], v[196:199], v[28:31]
	v_mfma_f32_16x16x32_bf16 v[4:7], v[148:151], v[208:211], v[4:7]
	v_mfma_f32_16x16x32_bf16 v[12:15], v[156:159], v[208:211], v[12:15]
	v_mfma_f32_16x16x32_bf16 v[52:55], v[152:155], v[184:187], v[52:55]
	v_mfma_f32_16x16x32_bf16 v[60:63], v[160:163], v[184:187], v[60:63]
	v_mfma_f32_16x16x32_bf16 v[36:39], v[152:155], v[192:195], v[36:39]
	v_mfma_f32_16x16x32_bf16 v[44:47], v[160:163], v[192:195], v[44:47]
	v_mfma_f32_16x16x32_bf16 v[20:23], v[152:155], v[204:207], v[20:23]
	v_mfma_f32_16x16x32_bf16 v[28:31], v[160:163], v[204:207], v[28:31]
	v_mfma_f32_16x16x32_bf16 v[4:7], v[152:155], v[212:215], v[4:7]
	v_mfma_f32_16x16x32_bf16 v[12:15], v[160:163], v[212:215], v[12:15]
	v_mfma_f32_16x16x32_bf16 v[48:51], v[164:167], v[180:183], v[48:51]
	v_mfma_f32_16x16x32_bf16 v[56:59], v[172:175], v[180:183], v[56:59]
	v_mfma_f32_16x16x32_bf16 v[32:35], v[164:167], v[188:191], v[32:35]
	v_mfma_f32_16x16x32_bf16 v[40:43], v[172:175], v[188:191], v[40:43]
	v_mfma_f32_16x16x32_bf16 v[16:19], v[164:167], v[196:199], v[16:19]
	v_mfma_f32_16x16x32_bf16 v[24:27], v[172:175], v[196:199], v[24:27]
	v_mfma_f32_16x16x32_bf16 v[0:3], v[164:167], v[208:211], v[0:3]
	v_mfma_f32_16x16x32_bf16 v[8:11], v[172:175], v[208:211], v[8:11]
	v_mfma_f32_16x16x32_bf16 v[48:51], v[168:171], v[184:187], v[48:51]
	v_mfma_f32_16x16x32_bf16 v[56:59], v[176:179], v[184:187], v[56:59]
	v_mfma_f32_16x16x32_bf16 v[32:35], v[168:171], v[192:195], v[32:35]
	v_mfma_f32_16x16x32_bf16 v[40:43], v[176:179], v[192:195], v[40:43]
	v_mfma_f32_16x16x32_bf16 v[16:19], v[168:171], v[204:207], v[16:19]
	v_mfma_f32_16x16x32_bf16 v[24:27], v[176:179], v[204:207], v[24:27]
	v_mfma_f32_16x16x32_bf16 v[0:3], v[168:171], v[212:215], v[0:3]
	v_mfma_f32_16x16x32_bf16 v[8:11], v[176:179], v[212:215], v[8:11]
	s_setprio 0
	s_barrier
	s_add_i32 s78, 0, 0x18000
	s_add_i32 s79, 0, 0x1c000
	v_add_u32_e32 v160, s78, v143
	v_add_u32_e32 v176, s79, v143
	ds_read_b128 v[148:151], v160
	ds_read_b128 v[152:155], v160 offset:1024
	ds_read_b128 v[156:159], v160 offset:2048
	ds_read_b128 v[160:163], v160 offset:3072
	ds_read_b128 v[164:167], v176
	ds_read_b128 v[168:171], v176 offset:1024
	ds_read_b128 v[172:175], v176 offset:2048
	ds_read_b128 v[176:179], v176 offset:3072
	s_add_u32 s46, s46, 0x40000
	s_addc_u32 s47, s47, 0
	s_mov_b32 m0, s55
	v_lshl_add_u64 v[220:221], s[46:47], 0, v[128:129]
	ds_read_b128 v[180:183], v147 offset:32768
	ds_read_b128 v[184:187], v147 offset:33792
	ds_read_b128 v[188:191], v147 offset:34816
	ds_read_b128 v[192:195], v147 offset:35840
	ds_read_b128 v[196:199], v147 offset:36864
	ds_read_b128 v[204:207], v147 offset:37888
	ds_read_b128 v[208:211], v147 offset:38912
	ds_read_b128 v[212:215], v147 offset:39936
	global_load_lds_dwordx4 v[220:221], off
	v_lshl_add_u64 v[220:221], s[46:47], 0, v[132:133]
	s_mov_b32 m0, s56
	s_nop 0
	global_load_lds_dwordx4 v[220:221], off
	s_waitcnt vmcnt(8)
	s_waitcnt lgkmcnt(0)
	s_barrier
	s_setprio 1
	s_waitcnt lgkmcnt(0)
	v_mfma_f32_16x16x32_bf16 v[116:119], v[148:151], v[180:183], v[116:119]
	v_mfma_f32_16x16x32_bf16 v[124:127], v[156:159], v[180:183], v[124:127]
	v_mfma_f32_16x16x32_bf16 v[100:103], v[148:151], v[188:191], v[100:103]
	v_mfma_f32_16x16x32_bf16 v[108:111], v[156:159], v[188:191], v[108:111]
	v_mfma_f32_16x16x32_bf16 v[84:87], v[148:151], v[196:199], v[84:87]
	v_mfma_f32_16x16x32_bf16 v[92:95], v[156:159], v[196:199], v[92:95]
	v_mfma_f32_16x16x32_bf16 v[68:71], v[148:151], v[208:211], v[68:71]
	v_mfma_f32_16x16x32_bf16 v[76:79], v[156:159], v[208:211], v[76:79]
	v_mfma_f32_16x16x32_bf16 v[116:119], v[152:155], v[184:187], v[116:119]
	v_mfma_f32_16x16x32_bf16 v[124:127], v[160:163], v[184:187], v[124:127]
	v_mfma_f32_16x16x32_bf16 v[100:103], v[152:155], v[192:195], v[100:103]
	v_mfma_f32_16x16x32_bf16 v[108:111], v[160:163], v[192:195], v[108:111]
	v_mfma_f32_16x16x32_bf16 v[84:87], v[152:155], v[204:207], v[84:87]
	v_mfma_f32_16x16x32_bf16 v[92:95], v[160:163], v[204:207], v[92:95]
	v_mfma_f32_16x16x32_bf16 v[68:71], v[152:155], v[212:215], v[68:71]
	v_mfma_f32_16x16x32_bf16 v[76:79], v[160:163], v[212:215], v[76:79]
	v_mfma_f32_16x16x32_bf16 v[112:115], v[164:167], v[180:183], v[112:115]
	v_mfma_f32_16x16x32_bf16 v[120:123], v[172:175], v[180:183], v[120:123]
	v_mfma_f32_16x16x32_bf16 v[96:99], v[164:167], v[188:191], v[96:99]
	v_mfma_f32_16x16x32_bf16 v[104:107], v[172:175], v[188:191], v[104:107]
	v_mfma_f32_16x16x32_bf16 v[80:83], v[164:167], v[196:199], v[80:83]
	v_mfma_f32_16x16x32_bf16 v[88:91], v[172:175], v[196:199], v[88:91]
	v_mfma_f32_16x16x32_bf16 v[64:67], v[164:167], v[208:211], v[64:67]
	v_mfma_f32_16x16x32_bf16 v[72:75], v[172:175], v[208:211], v[72:75]
	v_mfma_f32_16x16x32_bf16 v[112:115], v[168:171], v[184:187], v[112:115]
	v_mfma_f32_16x16x32_bf16 v[120:123], v[176:179], v[184:187], v[120:123]
	v_mfma_f32_16x16x32_bf16 v[96:99], v[168:171], v[192:195], v[96:99]
	v_mfma_f32_16x16x32_bf16 v[104:107], v[176:179], v[192:195], v[104:107]
	v_mfma_f32_16x16x32_bf16 v[80:83], v[168:171], v[204:207], v[80:83]
	v_mfma_f32_16x16x32_bf16 v[88:91], v[176:179], v[204:207], v[88:91]
	v_mfma_f32_16x16x32_bf16 v[64:67], v[168:171], v[212:215], v[64:67]
	v_mfma_f32_16x16x32_bf16 v[72:75], v[176:179], v[212:215], v[72:75]
	s_setprio 0
	s_barrier
; #define PG8_STAGE(bufoff, gbase, voff) do { _Pragma("unroll") for (int _i = 0; _i < 2; ++_i) \
;         __builtin_amdgcn_global_load_lds((const unsigned*)((const char*)(gbase) + (voff)[_i]), (LAS unsigned*)(lds + (bufoff) + ldsw + _i * 8192), 16, 0, 0); } while (0)
; #define PG8_LDA(dst, b, h) do { _Pragma("unroll") for (int m = 0; m < 4; ++m) _Pragma("unroll") for (int k = 0; k < 2; ++k) dst[m][k] = *(const LAS bf16x8*)(lds + PG8_SA(b, h) + aoff + m * 2048 + k * 1024); } while (0)
; #define PG8_MMA(ai, bj, At, Bt) do { __builtin_amdgcn_s_setprio(1); _Pragma("unroll") for (int m = 0; m < 4; ++m) _Pragma("unroll") for (int n = 0; n < 2; ++n) _Pragma("unroll") for (int k = 0; k < 2; ++k) \
;         acc[ai][bj][m][n] = __builtin_amdgcn_mfma_f32_16x16x32_bf16(Bt[n][k], At[m][k], acc[ai][bj][m][n], 0, 0, 0); __builtin_amdgcn_s_setprio(0); } while (0)
; #define PG8_WAIT_V(n) asm volatile("s_waitcnt vmcnt(" #n ")" ::: "memory")
; #define PG8_WAIT_L(n) asm volatile("s_waitcnt lgkmcnt(" #n ")" ::: "memory")
; #define PG8_BAR __builtin_amdgcn_s_barrier()
; #define PG8_SCHED __builtin_amdgcn_sched_barrier(0)
; template <class Epi>
; __device__ __forceinline__ void gemm_phase(LAS unsigned char* lds, const Gemm g, const Sched& S, const Epi& E) {
;     ...
;             PG8_LDA(At, 1, 1); PG8_STAGE(PG8_SB(1, 0), b3, voffB); PG8_STAGE(PG8_SB(1, 1), b3 + hstepB, voffB); PG8_STAGE(PG8_SA(1, 0), a3, voffA);
;             PG8_WAIT_V(8); PG8_WAIT_L(0); PG8_BAR; PG8_MMA(1, 0, At, B0); PG8_MMA(1, 1, At, B1); PG8_BAR; PG8_SCHED;
;         }
	s_add_i32 s46, s78, s53
	v_lshl_add_u64 v[140:141], v[140:141], 0, s[4:5]
	s_mov_b32 m0, s46
	ds_read_b128 v[180:183], v147 offset:49152
	ds_read_b128 v[184:187], v147 offset:50176
	ds_read_b128 v[188:191], v147 offset:51200
	ds_read_b128 v[192:195], v147 offset:52224
	ds_read_b128 v[196:199], v147 offset:53248
	ds_read_b128 v[204:207], v147 offset:54272
	ds_read_b128 v[208:211], v147 offset:55296
	ds_read_b128 v[212:215], v147 offset:56320
	global_load_lds_dwordx4 v[140:141], off
	s_add_i32 m0, s46, 0x2000
	s_add_u32 s44, s44, 0x40080
	v_lshl_add_u64 v[140:141], v[200:201], 0, s[4:5]
	s_addc_u32 s45, s45, 0
	s_add_i32 s46, s79, s53
	global_load_lds_dwordx4 v[140:141], off
	v_lshl_add_u64 v[140:141], s[44:45], 0, v[130:131]
	s_mov_b32 m0, s46
	s_nop 0
	global_load_lds_dwordx4 v[140:141], off
	v_lshl_add_u64 v[140:141], s[44:45], 0, v[134:135]
	s_add_i32 m0, s46, 0x2000
	s_nop 0
	global_load_lds_dwordx4 v[140:141], off
	v_lshl_add_u64 v[140:141], v[216:217], 0, s[4:5]
	s_mov_b32 m0, s58
	s_nop 0
	global_load_lds_dwordx4 v[140:141], off
	v_lshl_add_u64 v[140:141], v[218:219], 0, s[4:5]
	s_mov_b32 m0, s59
	s_nop 0
	global_load_lds_dwordx4 v[140:141], off
	s_waitcnt vmcnt(8)
	s_waitcnt lgkmcnt(0)
	s_barrier
	s_setprio 1
	s_waitcnt lgkmcnt(0)
	v_mfma_f32_16x16x32_bf16 v[52:55], v[148:151], v[180:183], v[52:55]
	v_mfma_f32_16x16x32_bf16 v[60:63], v[156:159], v[180:183], v[60:63]
	v_mfma_f32_16x16x32_bf16 v[36:39], v[148:151], v[188:191], v[36:39]
	v_mfma_f32_16x16x32_bf16 v[44:47], v[156:159], v[188:191], v[44:47]
	v_mfma_f32_16x16x32_bf16 v[20:23], v[148:151], v[196:199], v[20:23]
	v_mfma_f32_16x16x32_bf16 v[28:31], v[156:159], v[196:199], v[28:31]
	v_mfma_f32_16x16x32_bf16 v[4:7], v[148:151], v[208:211], v[4:7]
	v_mfma_f32_16x16x32_bf16 v[12:15], v[156:159], v[208:211], v[12:15]
	v_mfma_f32_16x16x32_bf16 v[52:55], v[152:155], v[184:187], v[52:55]
	v_mfma_f32_16x16x32_bf16 v[60:63], v[160:163], v[184:187], v[60:63]
	v_mfma_f32_16x16x32_bf16 v[36:39], v[152:155], v[192:195], v[36:39]
	v_mfma_f32_16x16x32_bf16 v[44:47], v[160:163], v[192:195], v[44:47]
	v_mfma_f32_16x16x32_bf16 v[20:23], v[152:155], v[204:207], v[20:23]
	v_mfma_f32_16x16x32_bf16 v[28:31], v[160:163], v[204:207], v[28:31]
	v_mfma_f32_16x16x32_bf16 v[4:7], v[152:155], v[212:215], v[4:7]
	v_mfma_f32_16x16x32_bf16 v[12:15], v[160:163], v[212:215], v[12:15]
	v_mfma_f32_16x16x32_bf16 v[48:51], v[164:167], v[180:183], v[48:51]
	v_mfma_f32_16x16x32_bf16 v[56:59], v[172:175], v[180:183], v[56:59]
	v_mfma_f32_16x16x32_bf16 v[32:35], v[164:167], v[188:191], v[32:35]
	v_mfma_f32_16x16x32_bf16 v[40:43], v[172:175], v[188:191], v[40:43]
	v_mfma_f32_16x16x32_bf16 v[16:19], v[164:167], v[196:199], v[16:19]
	v_mfma_f32_16x16x32_bf16 v[24:27], v[172:175], v[196:199], v[24:27]
	v_mfma_f32_16x16x32_bf16 v[0:3], v[164:167], v[208:211], v[0:3]
	v_mfma_f32_16x16x32_bf16 v[8:11], v[172:175], v[208:211], v[8:11]
	v_mfma_f32_16x16x32_bf16 v[48:51], v[168:171], v[184:187], v[48:51]
	v_mfma_f32_16x16x32_bf16 v[56:59], v[176:179], v[184:187], v[56:59]
	v_mfma_f32_16x16x32_bf16 v[32:35], v[168:171], v[192:195], v[32:35]
	v_mfma_f32_16x16x32_bf16 v[40:43], v[176:179], v[192:195], v[40:43]
	v_mfma_f32_16x16x32_bf16 v[16:19], v[168:171], v[204:207], v[16:19]
	v_mfma_f32_16x16x32_bf16 v[24:27], v[176:179], v[204:207], v[24:27]
	v_mfma_f32_16x16x32_bf16 v[0:3], v[168:171], v[212:215], v[0:3]
	v_mfma_f32_16x16x32_bf16 v[8:11], v[176:179], v[212:215], v[8:11]
	s_setprio 0
	s_barrier
	s_add_i32 s67, s67, 2
	s_add_u32 s40, s40, 0x100
	s_addc_u32 s41, s41, 0
	s_add_u32 s65, s65, 0x100
	s_addc_u32 s66, s66, 0
	s_cmp_gt_u32 s67, 13
	s_cbranch_scc0 .LBB0_163
	s_and_b64 vcc, exec, s[6:7]
	s_cbranch_vccz .LBB0_166
	s_barrier

; #define PG8_STAGE(bufoff, gbase, voff) do { _Pragma("unroll") for (int _i = 0; _i < 2; ++_i) \
;         __builtin_amdgcn_global_load_lds((const unsigned*)((const char*)(gbase) + (voff)[_i]), (LAS unsigned*)(lds + (bufoff) + ldsw + _i * 8192), 16, 0, 0); } while (0)
; #define PG8_LDA(dst, b, h) do { _Pragma("unroll") for (int m = 0; m < 4; ++m) _Pragma("unroll") for (int k = 0; k < 2; ++k) dst[m][k] = *(const LAS bf16x8*)(lds + PG8_SA(b, h) + aoff + m * 2048 + k * 1024); } while (0)
; #define PG8_LDB(dst, b, h) do { _Pragma("unroll") for (int n = 0; n < 2; ++n) _Pragma("unroll") for (int k = 0; k < 2; ++k) dst[n][k] = *(const LAS bf16x8*)(lds + PG8_SB(b, h) + boff + n * 2048 + k * 1024); } while (0)
; #define PG8_MMA(ai, bj, At, Bt) do { __builtin_amdgcn_s_setprio(1); _Pragma("unroll") for (int m = 0; m < 4; ++m) _Pragma("unroll") for (int n = 0; n < 2; ++n) _Pragma("unroll") for (int k = 0; k < 2; ++k) \
;         acc[ai][bj][m][n] = __builtin_amdgcn_mfma_f32_16x16x32_bf16(Bt[n][k], At[m][k], acc[ai][bj][m][n], 0, 0, 0); __builtin_amdgcn_s_setprio(0); } while (0)
; #define PG8_WAIT_V(n) asm volatile("s_waitcnt vmcnt(" #n ")" ::: "memory")
; #define PG8_WAIT_L(n) asm volatile("s_waitcnt lgkmcnt(" #n ")" ::: "memory")
; #define PG8_BAR __builtin_amdgcn_s_barrier()
; #define PG8_SCHED __builtin_amdgcn_sched_barrier(0)
; template <class Epi>
; __device__ __forceinline__ void gemm_phase(LAS unsigned char* lds, const Gemm g, const Sched& S, const Epi& E) {
;     ...
;             const bool last = (t == nt - 2);
;             const char* a1 = cA + (size_t)(t + 1) * kstep;
;             const char* a2 = last ? nA : cA + (size_t)(t + 2) * kstep; const char* b2 = last ? nB : cB + (size_t)(t + 2) * kstep;
;             const char* a3 = a2 + kstep; const char* b3 = b2 + kstep;
;             PG8_LDB(B0, 0, 0); PG8_LDB(B1, 0, 1); PG8_SCHED; PG8_LDA(At, 0, 0); PG8_STAGE(PG8_SA(1, 1), a1 + hstepA, voffA);
;             PG8_WAIT_V(8); PG8_WAIT_L(0); PG8_BAR; PG8_MMA(0, 0, At, B0); PG8_MMA(0, 1, At, B1); PG8_BAR; PG8_SCHED;
;             PG8_LDA(At, 0, 1); PG8_STAGE(PG8_SB(0, 0), b2, voffB); PG8_STAGE(PG8_SB(0, 1), b2 + hstepB, voffB); PG8_STAGE(PG8_SA(0, 0), a2, voffA);
;             PG8_WAIT_V(8); PG8_WAIT_L(0); PG8_BAR; PG8_MMA(1, 0, At, B0); PG8_MMA(1, 1, At, B1); PG8_BAR; PG8_SCHED;
.LBB0_205:
	ds_read_b128 v[136:139], v145
	ds_read_b128 v[148:151], v145 offset:1024
	ds_read_b128 v[152:155], v145 offset:2048
	ds_read_b128 v[156:159], v145 offset:3072
	ds_read_b128 v[160:163], v146
	ds_read_b128 v[164:167], v146 offset:1024
	ds_read_b128 v[168:171], v146 offset:2048
	ds_read_b128 v[172:175], v146 offset:3072
	s_add_u32 s44, s40, 0xfffc0080
	s_addc_u32 s45, s41, -1
	s_cmp_eq_u32 s66, 12
	s_cselect_b32 s47, s15, s45
	s_cselect_b32 s46, s27, s44
	s_cselect_b32 s45, s21, s65
	s_cselect_b32 s44, s63, s64
	v_lshl_add_u64 v[140:141], s[40:41], 0, v[132:133]
	s_add_i32 m0, s29, 0xc000
	ds_read_b128 v[176:179], v147
	ds_read_b128 v[180:183], v147 offset:1024
	ds_read_b128 v[184:187], v147 offset:2048
	ds_read_b128 v[188:191], v147 offset:3072
	ds_read_b128 v[192:195], v147 offset:4096
	ds_read_b128 v[196:199], v147 offset:5120
	ds_read_b128 v[204:207], v147 offset:6144
	ds_read_b128 v[208:211], v147 offset:7168
	global_load_lds_dwordx4 v[140:141], off
	v_lshl_add_u64 v[140:141], s[40:41], 0, v[134:135]
	s_add_i32 m0, s29, 0xe000
	s_nop 0
	global_load_lds_dwordx4 v[140:141], off
	s_waitcnt vmcnt(8)
	s_waitcnt lgkmcnt(0)
	s_barrier
	s_setprio 1
	s_waitcnt lgkmcnt(0)
	v_mfma_f32_16x16x32_bf16 v[124:127], v[136:139], v[176:179], v[124:127]
	v_mfma_f32_16x16x32_bf16 v[120:123], v[152:155], v[176:179], v[120:123]
	v_mfma_f32_16x16x32_bf16 v[108:111], v[136:139], v[184:187], v[108:111]
	v_mfma_f32_16x16x32_bf16 v[104:107], v[152:155], v[184:187], v[104:107]
	v_mfma_f32_16x16x32_bf16 v[92:95], v[136:139], v[192:195], v[92:95]
	v_mfma_f32_16x16x32_bf16 v[88:91], v[152:155], v[192:195], v[88:91]
	v_mfma_f32_16x16x32_bf16 v[76:79], v[136:139], v[204:207], v[76:79]
	v_mfma_f32_16x16x32_bf16 v[72:75], v[152:155], v[204:207], v[72:75]
	v_mfma_f32_16x16x32_bf16 v[124:127], v[148:151], v[180:183], v[124:127]
	v_mfma_f32_16x16x32_bf16 v[120:123], v[156:159], v[180:183], v[120:123]
	v_mfma_f32_16x16x32_bf16 v[108:111], v[148:151], v[188:191], v[108:111]
	v_mfma_f32_16x16x32_bf16 v[104:107], v[156:159], v[188:191], v[104:107]
	v_mfma_f32_16x16x32_bf16 v[92:95], v[148:151], v[196:199], v[92:95]
	v_mfma_f32_16x16x32_bf16 v[88:91], v[156:159], v[196:199], v[88:91]
	v_mfma_f32_16x16x32_bf16 v[76:79], v[148:151], v[208:211], v[76:79]
	v_mfma_f32_16x16x32_bf16 v[72:75], v[156:159], v[208:211], v[72:75]
	v_mfma_f32_16x16x32_bf16 v[116:119], v[160:163], v[176:179], v[116:119]
	v_mfma_f32_16x16x32_bf16 v[112:115], v[168:171], v[176:179], v[112:115]
	v_mfma_f32_16x16x32_bf16 v[100:103], v[160:163], v[184:187], v[100:103]
	v_mfma_f32_16x16x32_bf16 v[96:99], v[168:171], v[184:187], v[96:99]
	v_mfma_f32_16x16x32_bf16 v[84:87], v[160:163], v[192:195], v[84:87]
	v_mfma_f32_16x16x32_bf16 v[80:83], v[168:171], v[192:195], v[80:83]
	v_mfma_f32_16x16x32_bf16 v[68:71], v[160:163], v[204:207], v[68:71]
	v_mfma_f32_16x16x32_bf16 v[64:67], v[168:171], v[204:207], v[64:67]
	v_mfma_f32_16x16x32_bf16 v[116:119], v[164:167], v[180:183], v[116:119]
	v_mfma_f32_16x16x32_bf16 v[112:115], v[172:175], v[180:183], v[112:115]
	v_mfma_f32_16x16x32_bf16 v[100:103], v[164:167], v[188:191], v[100:103]
	v_mfma_f32_16x16x32_bf16 v[96:99], v[172:175], v[188:191], v[96:99]
	v_mfma_f32_16x16x32_bf16 v[84:87], v[164:167], v[196:199], v[84:87]
	v_mfma_f32_16x16x32_bf16 v[80:83], v[172:175], v[196:199], v[80:83]
	v_mfma_f32_16x16x32_bf16 v[68:71], v[164:167], v[208:211], v[68:71]
	v_mfma_f32_16x16x32_bf16 v[64:67], v[172:175], v[208:211], v[64:67]
	s_setprio 0
	s_barrier
	s_add_i32 s67, s61, s52
	v_lshl_add_u64 v[140:141], s[44:45], 0, v[128:129]
	s_mov_b32 m0, s67
	ds_read_b128 v[176:179], v147 offset:16384
	ds_read_b128 v[180:183], v147 offset:17408
	ds_read_b128 v[184:187], v147 offset:18432
	ds_read_b128 v[188:191], v147 offset:19456
	ds_read_b128 v[192:195], v147 offset:20480
	ds_read_b128 v[196:199], v147 offset:21504
	ds_read_b128 v[204:207], v147 offset:22528
	ds_read_b128 v[208:211], v147 offset:23552
	global_load_lds_dwordx4 v[140:141], off
	s_add_i32 m0, s67, 0x2000
	s_add_u32 s78, s44, 0x40000
	v_lshl_add_u64 v[200:201], s[44:45], 0, v[130:131]
	s_addc_u32 s79, s45, 0
	s_add_i32 s67, s62, s52
	global_load_lds_dwordx4 v[200:201], off
	v_lshl_add_u64 v[212:213], s[78:79], 0, v[128:129]
	s_mov_b32 m0, s67
	v_lshl_add_u64 v[214:215], s[46:47], 0, v[130:131]
	global_load_lds_dwordx4 v[212:213], off
	v_lshl_add_u64 v[212:213], s[78:79], 0, v[130:131]
	s_add_i32 m0, s67, 0x2000
	s_nop 0
	global_load_lds_dwordx4 v[212:213], off
	v_lshl_add_u64 v[212:213], s[46:47], 0, v[128:129]
	s_mov_b32 m0, s29
	s_nop 0
	global_load_lds_dwordx4 v[212:213], off
	s_mov_b32 m0, s55
	s_nop 0
	global_load_lds_dwordx4 v[214:215], off
	s_waitcnt vmcnt(8)
	s_waitcnt lgkmcnt(0)
	s_barrier
; #define PG8_STAGE(bufoff, gbase, voff) do { _Pragma("unroll") for (int _i = 0; _i < 2; ++_i) \
;         __builtin_amdgcn_global_load_lds((const unsigned*)((const char*)(gbase) + (voff)[_i]), (LAS unsigned*)(lds + (bufoff) + ldsw + _i * 8192), 16, 0, 0); } while (0)
; #define PG8_LDA(dst, b, h) do { _Pragma("unroll") for (int m = 0; m < 4; ++m) _Pragma("unroll") for (int k = 0; k < 2; ++k) dst[m][k] = *(const LAS bf16x8*)(lds + PG8_SA(b, h) + aoff + m * 2048 + k * 1024); } while (0)
; #define PG8_LDB(dst, b, h) do { _Pragma("unroll") for (int n = 0; n < 2; ++n) _Pragma("unroll") for (int k = 0; k < 2; ++k) dst[n][k] = *(const LAS bf16x8*)(lds + PG8_SB(b, h) + boff + n * 2048 + k * 1024); } while (0)
; #define PG8_MMA(ai, bj, At, Bt) do { __builtin_amdgcn_s_setprio(1); _Pragma("unroll") for (int m = 0; m < 4; ++m) _Pragma("unroll") for (int n = 0; n < 2; ++n) _Pragma("unroll") for (int k = 0; k < 2; ++k) \
;         acc[ai][bj][m][n] = __builtin_amdgcn_mfma_f32_16x16x32_bf16(Bt[n][k], At[m][k], acc[ai][bj][m][n], 0, 0, 0); __builtin_amdgcn_s_setprio(0); } while (0)
; #define PG8_WAIT_V(n) asm volatile("s_waitcnt vmcnt(" #n ")" ::: "memory")
; #define PG8_WAIT_L(n) asm volatile("s_waitcnt lgkmcnt(" #n ")" ::: "memory")
; #define PG8_BAR __builtin_amdgcn_s_barrier()
; #define PG8_SCHED __builtin_amdgcn_sched_barrier(0)
; template <class Epi>
; __device__ __forceinline__ void gemm_phase(LAS unsigned char* lds, const Gemm g, const Sched& S, const Epi& E) {
;     ...
;             PG8_WAIT_V(8); PG8_WAIT_L(0); PG8_BAR; PG8_MMA(1, 0, At, B0); PG8_MMA(1, 1, At, B1); PG8_BAR; PG8_SCHED;
;             PG8_LDB(B0, 1, 0); PG8_LDB(B1, 1, 1); PG8_SCHED; PG8_LDA(At, 1, 0); PG8_STAGE(PG8_SA(0, 1), a2 + hstepA, voffA);
;             PG8_WAIT_V(8); PG8_WAIT_L(0); PG8_BAR; PG8_MMA(0, 0, At, B0); PG8_MMA(0, 1, At, B1); PG8_BAR; PG8_SCHED;
	s_setprio 1
	s_waitcnt lgkmcnt(0)
	v_mfma_f32_16x16x32_bf16 v[60:63], v[136:139], v[176:179], v[60:63]
	v_mfma_f32_16x16x32_bf16 v[56:59], v[152:155], v[176:179], v[56:59]
	v_mfma_f32_16x16x32_bf16 v[44:47], v[136:139], v[184:187], v[44:47]
	v_mfma_f32_16x16x32_bf16 v[40:43], v[152:155], v[184:187], v[40:43]
	v_mfma_f32_16x16x32_bf16 v[28:31], v[136:139], v[192:195], v[28:31]
	v_mfma_f32_16x16x32_bf16 v[24:27], v[152:155], v[192:195], v[24:27]
	v_mfma_f32_16x16x32_bf16 v[12:15], v[136:139], v[204:207], v[12:15]
	v_mfma_f32_16x16x32_bf16 v[8:11], v[152:155], v[204:207], v[8:11]
	v_mfma_f32_16x16x32_bf16 v[60:63], v[148:151], v[180:183], v[60:63]
	v_mfma_f32_16x16x32_bf16 v[56:59], v[156:159], v[180:183], v[56:59]
	v_mfma_f32_16x16x32_bf16 v[44:47], v[148:151], v[188:191], v[44:47]
	v_mfma_f32_16x16x32_bf16 v[40:43], v[156:159], v[188:191], v[40:43]
	v_mfma_f32_16x16x32_bf16 v[28:31], v[148:151], v[196:199], v[28:31]
	v_mfma_f32_16x16x32_bf16 v[24:27], v[156:159], v[196:199], v[24:27]
	v_mfma_f32_16x16x32_bf16 v[12:15], v[148:151], v[208:211], v[12:15]
	v_mfma_f32_16x16x32_bf16 v[8:11], v[156:159], v[208:211], v[8:11]
	v_mfma_f32_16x16x32_bf16 v[52:55], v[160:163], v[176:179], v[52:55]
	v_mfma_f32_16x16x32_bf16 v[48:51], v[168:171], v[176:179], v[48:51]
	v_mfma_f32_16x16x32_bf16 v[36:39], v[160:163], v[184:187], v[36:39]
	v_mfma_f32_16x16x32_bf16 v[32:35], v[168:171], v[184:187], v[32:35]
	v_mfma_f32_16x16x32_bf16 v[20:23], v[160:163], v[192:195], v[20:23]
	v_mfma_f32_16x16x32_bf16 v[16:19], v[168:171], v[192:195], v[16:19]
	v_mfma_f32_16x16x32_bf16 v[4:7], v[160:163], v[204:207], v[4:7]
	v_mfma_f32_16x16x32_bf16 v[0:3], v[168:171], v[204:207], v[0:3]
	v_mfma_f32_16x16x32_bf16 v[52:55], v[164:167], v[180:183], v[52:55]
	v_mfma_f32_16x16x32_bf16 v[48:51], v[172:175], v[180:183], v[48:51]
	v_mfma_f32_16x16x32_bf16 v[36:39], v[164:167], v[188:191], v[36:39]
	v_mfma_f32_16x16x32_bf16 v[32:35], v[172:175], v[188:191], v[32:35]
	v_mfma_f32_16x16x32_bf16 v[20:23], v[164:167], v[196:199], v[20:23]
	v_mfma_f32_16x16x32_bf16 v[16:19], v[172:175], v[196:199], v[16:19]
	v_mfma_f32_16x16x32_bf16 v[4:7], v[164:167], v[208:211], v[4:7]
	v_mfma_f32_16x16x32_bf16 v[0:3], v[172:175], v[208:211], v[0:3]
	s_setprio 0
	s_barrier
	s_add_i32 s67, 0, 0x18000
	s_add_i32 s78, 0, 0x1c000
	v_add_u32_e32 v156, s67, v143
	v_add_u32_e32 v172, s78, v143
	ds_read_b128 v[136:139], v156
	ds_read_b128 v[148:151], v156 offset:1024
	ds_read_b128 v[152:155], v156 offset:2048
	ds_read_b128 v[156:159], v156 offset:3072
	ds_read_b128 v[160:163], v172
	ds_read_b128 v[164:167], v172 offset:1024
	ds_read_b128 v[168:171], v172 offset:2048
	ds_read_b128 v[172:175], v172 offset:3072
	s_add_u32 s46, s46, 0x40000
	s_addc_u32 s47, s47, 0
	s_mov_b32 m0, s56
	v_lshl_add_u64 v[216:217], s[46:47], 0, v[128:129]
	ds_read_b128 v[176:179], v147 offset:32768
	ds_read_b128 v[180:183], v147 offset:33792
	ds_read_b128 v[184:187], v147 offset:34816
	ds_read_b128 v[188:191], v147 offset:35840
	ds_read_b128 v[192:195], v147 offset:36864
	ds_read_b128 v[196:199], v147 offset:37888
	ds_read_b128 v[204:207], v147 offset:38912
	ds_read_b128 v[208:211], v147 offset:39936
	global_load_lds_dwordx4 v[216:217], off
	v_lshl_add_u64 v[216:217], s[46:47], 0, v[130:131]
	s_mov_b32 m0, s57
	s_nop 0
	global_load_lds_dwordx4 v[216:217], off
	s_waitcnt vmcnt(8)
	s_waitcnt lgkmcnt(0)
	s_barrier
	s_setprio 1
	s_waitcnt lgkmcnt(0)
	v_mfma_f32_16x16x32_bf16 v[124:127], v[136:139], v[176:179], v[124:127]
	v_mfma_f32_16x16x32_bf16 v[120:123], v[152:155], v[176:179], v[120:123]
	v_mfma_f32_16x16x32_bf16 v[108:111], v[136:139], v[184:187], v[108:111]
	v_mfma_f32_16x16x32_bf16 v[104:107], v[152:155], v[184:187], v[104:107]
	v_mfma_f32_16x16x32_bf16 v[92:95], v[136:139], v[192:195], v[92:95]
	v_mfma_f32_16x16x32_bf16 v[88:91], v[152:155], v[192:195], v[88:91]
	v_mfma_f32_16x16x32_bf16 v[76:79], v[136:139], v[204:207], v[76:79]
	v_mfma_f32_16x16x32_bf16 v[72:75], v[152:155], v[204:207], v[72:75]
	v_mfma_f32_16x16x32_bf16 v[124:127], v[148:151], v[180:183], v[124:127]
	v_mfma_f32_16x16x32_bf16 v[120:123], v[156:159], v[180:183], v[120:123]
	v_mfma_f32_16x16x32_bf16 v[108:111], v[148:151], v[188:191], v[108:111]
	v_mfma_f32_16x16x32_bf16 v[104:107], v[156:159], v[188:191], v[104:107]
	v_mfma_f32_16x16x32_bf16 v[92:95], v[148:151], v[196:199], v[92:95]
	v_mfma_f32_16x16x32_bf16 v[88:91], v[156:159], v[196:199], v[88:91]
	v_mfma_f32_16x16x32_bf16 v[76:79], v[148:151], v[208:211], v[76:79]
	v_mfma_f32_16x16x32_bf16 v[72:75], v[156:159], v[208:211], v[72:75]
	v_mfma_f32_16x16x32_bf16 v[116:119], v[160:163], v[176:179], v[116:119]
	v_mfma_f32_16x16x32_bf16 v[112:115], v[168:171], v[176:179], v[112:115]
	v_mfma_f32_16x16x32_bf16 v[100:103], v[160:163], v[184:187], v[100:103]
	v_mfma_f32_16x16x32_bf16 v[96:99], v[168:171], v[184:187], v[96:99]
	v_mfma_f32_16x16x32_bf16 v[84:87], v[160:163], v[192:195], v[84:87]
	v_mfma_f32_16x16x32_bf16 v[80:83], v[168:171], v[192:195], v[80:83]
	v_mfma_f32_16x16x32_bf16 v[68:71], v[160:163], v[204:207], v[68:71]
	v_mfma_f32_16x16x32_bf16 v[64:67], v[168:171], v[204:207], v[64:67]
	v_mfma_f32_16x16x32_bf16 v[116:119], v[164:167], v[180:183], v[116:119]
	v_mfma_f32_16x16x32_bf16 v[112:115], v[172:175], v[180:183], v[112:115]
	v_mfma_f32_16x16x32_bf16 v[100:103], v[164:167], v[188:191], v[100:103]
	v_mfma_f32_16x16x32_bf16 v[96:99], v[172:175], v[188:191], v[96:99]
	v_mfma_f32_16x16x32_bf16 v[84:87], v[164:167], v[196:199], v[84:87]
	v_mfma_f32_16x16x32_bf16 v[80:83], v[172:175], v[196:199], v[80:83]
	v_mfma_f32_16x16x32_bf16 v[68:71], v[164:167], v[208:211], v[68:71]
	v_mfma_f32_16x16x32_bf16 v[64:67], v[172:175], v[208:211], v[64:67]
	s_setprio 0
	s_barrier
; #define PG8_STAGE(bufoff, gbase, voff) do { _Pragma("unroll") for (int _i = 0; _i < 2; ++_i) \
;         __builtin_amdgcn_global_load_lds((const unsigned*)((const char*)(gbase) + (voff)[_i]), (LAS unsigned*)(lds + (bufoff) + ldsw + _i * 8192), 16, 0, 0); } while (0)
; #define PG8_LDA(dst, b, h) do { _Pragma("unroll") for (int m = 0; m < 4; ++m) _Pragma("unroll") for (int k = 0; k < 2; ++k) dst[m][k] = *(const LAS bf16x8*)(lds + PG8_SA(b, h) + aoff + m * 2048 + k * 1024); } while (0)
; #define PG8_MMA(ai, bj, At, Bt) do { __builtin_amdgcn_s_setprio(1); _Pragma("unroll") for (int m = 0; m < 4; ++m) _Pragma("unroll") for (int n = 0; n < 2; ++n) _Pragma("unroll") for (int k = 0; k < 2; ++k) \
;         acc[ai][bj][m][n] = __builtin_amdgcn_mfma_f32_16x16x32_bf16(Bt[n][k], At[m][k], acc[ai][bj][m][n], 0, 0, 0); __builtin_amdgcn_s_setprio(0); } while (0)
; #define PG8_WAIT_V(n) asm volatile("s_waitcnt vmcnt(" #n ")" ::: "memory")
; #define PG8_WAIT_L(n) asm volatile("s_waitcnt lgkmcnt(" #n ")" ::: "memory")
; #define PG8_BAR __builtin_amdgcn_s_barrier()
; #define PG8_SCHED __builtin_amdgcn_sched_barrier(0)
; template <class Epi>
; __device__ __forceinline__ void gemm_phase(LAS unsigned char* lds, const Gemm g, const Sched& S, const Epi& E) {
;     ...
;             PG8_LDA(At, 1, 1); PG8_STAGE(PG8_SB(1, 0), b3, voffB); PG8_STAGE(PG8_SB(1, 1), b3 + hstepB, voffB); PG8_STAGE(PG8_SA(1, 0), a3, voffA);
;             PG8_WAIT_V(8); PG8_WAIT_L(0); PG8_BAR; PG8_MMA(1, 0, At, B0); PG8_MMA(1, 1, At, B1); PG8_BAR; PG8_SCHED;
;         }
	s_add_i32 s46, s67, s52
	v_lshl_add_u64 v[140:141], v[140:141], 0, s[4:5]
	s_mov_b32 m0, s46
	ds_read_b128 v[176:179], v147 offset:49152
	ds_read_b128 v[180:183], v147 offset:50176
	ds_read_b128 v[184:187], v147 offset:51200
	ds_read_b128 v[188:191], v147 offset:52224
	ds_read_b128 v[192:195], v147 offset:53248
	ds_read_b128 v[196:199], v147 offset:54272
	ds_read_b128 v[204:207], v147 offset:55296
	ds_read_b128 v[208:211], v147 offset:56320
	global_load_lds_dwordx4 v[140:141], off
	s_add_i32 m0, s46, 0x2000
	s_add_u32 s44, s44, 0x40080
	v_lshl_add_u64 v[140:141], v[200:201], 0, s[4:5]
	s_addc_u32 s45, s45, 0
	s_add_i32 s46, s78, s52
	global_load_lds_dwordx4 v[140:141], off
	v_lshl_add_u64 v[140:141], s[44:45], 0, v[128:129]
	s_mov_b32 m0, s46
	s_nop 0
	global_load_lds_dwordx4 v[140:141], off
	v_lshl_add_u64 v[140:141], s[44:45], 0, v[130:131]
	s_add_i32 m0, s46, 0x2000
	s_nop 0
	global_load_lds_dwordx4 v[140:141], off
	v_lshl_add_u64 v[140:141], v[212:213], 0, s[4:5]
	s_mov_b32 m0, s59
	s_nop 0
	global_load_lds_dwordx4 v[140:141], off
	v_lshl_add_u64 v[140:141], v[214:215], 0, s[4:5]
	s_mov_b32 m0, s60
	s_nop 0
	global_load_lds_dwordx4 v[140:141], off
	s_waitcnt vmcnt(8)
	s_waitcnt lgkmcnt(0)
	s_barrier
	s_setprio 1
	s_waitcnt lgkmcnt(0)
	v_mfma_f32_16x16x32_bf16 v[60:63], v[136:139], v[176:179], v[60:63]
	v_mfma_f32_16x16x32_bf16 v[56:59], v[152:155], v[176:179], v[56:59]
	v_mfma_f32_16x16x32_bf16 v[44:47], v[136:139], v[184:187], v[44:47]
	v_mfma_f32_16x16x32_bf16 v[40:43], v[152:155], v[184:187], v[40:43]
	v_mfma_f32_16x16x32_bf16 v[28:31], v[136:139], v[192:195], v[28:31]
	v_mfma_f32_16x16x32_bf16 v[24:27], v[152:155], v[192:195], v[24:27]
	v_mfma_f32_16x16x32_bf16 v[12:15], v[136:139], v[204:207], v[12:15]
	v_mfma_f32_16x16x32_bf16 v[8:11], v[152:155], v[204:207], v[8:11]
	v_mfma_f32_16x16x32_bf16 v[60:63], v[148:151], v[180:183], v[60:63]
	v_mfma_f32_16x16x32_bf16 v[56:59], v[156:159], v[180:183], v[56:59]
	v_mfma_f32_16x16x32_bf16 v[44:47], v[148:151], v[188:191], v[44:47]
	v_mfma_f32_16x16x32_bf16 v[40:43], v[156:159], v[188:191], v[40:43]
	v_mfma_f32_16x16x32_bf16 v[28:31], v[148:151], v[196:199], v[28:31]
	v_mfma_f32_16x16x32_bf16 v[24:27], v[156:159], v[196:199], v[24:27]
	v_mfma_f32_16x16x32_bf16 v[12:15], v[148:151], v[208:211], v[12:15]
	v_mfma_f32_16x16x32_bf16 v[8:11], v[156:159], v[208:211], v[8:11]
	v_mfma_f32_16x16x32_bf16 v[52:55], v[160:163], v[176:179], v[52:55]
	v_mfma_f32_16x16x32_bf16 v[48:51], v[168:171], v[176:179], v[48:51]
	v_mfma_f32_16x16x32_bf16 v[36:39], v[160:163], v[184:187], v[36:39]
	v_mfma_f32_16x16x32_bf16 v[32:35], v[168:171], v[184:187], v[32:35]
	v_mfma_f32_16x16x32_bf16 v[20:23], v[160:163], v[192:195], v[20:23]
	v_mfma_f32_16x16x32_bf16 v[16:19], v[168:171], v[192:195], v[16:19]
	v_mfma_f32_16x16x32_bf16 v[4:7], v[160:163], v[204:207], v[4:7]
	v_mfma_f32_16x16x32_bf16 v[0:3], v[168:171], v[204:207], v[0:3]
	v_mfma_f32_16x16x32_bf16 v[52:55], v[164:167], v[180:183], v[52:55]
	v_mfma_f32_16x16x32_bf16 v[48:51], v[172:175], v[180:183], v[48:51]
	v_mfma_f32_16x16x32_bf16 v[36:39], v[164:167], v[188:191], v[36:39]
	v_mfma_f32_16x16x32_bf16 v[32:35], v[172:175], v[188:191], v[32:35]
	v_mfma_f32_16x16x32_bf16 v[20:23], v[164:167], v[196:199], v[20:23]
	v_mfma_f32_16x16x32_bf16 v[16:19], v[172:175], v[196:199], v[16:19]
	v_mfma_f32_16x16x32_bf16 v[4:7], v[164:167], v[208:211], v[4:7]
	v_mfma_f32_16x16x32_bf16 v[0:3], v[172:175], v[208:211], v[0:3]
	s_setprio 0
	s_barrier
	s_add_i32 s66, s66, 2
	s_add_u32 s40, s40, 0x100
	s_addc_u32 s41, s41, 0
	s_add_u32 s64, s64, 0x100
	s_addc_u32 s65, s65, 0
	s_cmp_gt_u32 s66, 13
	s_cbranch_scc0 .LBB0_205
	s_and_b64 vcc, exec, s[6:7]
	s_cbranch_vccz .LBB0_208
	s_barrier

; #define PG8_STAGE(bufoff, gbase, voff) do { _Pragma("unroll") for (int _i = 0; _i < 2; ++_i) \
;         __builtin_amdgcn_global_load_lds((const unsigned*)((const char*)(gbase) + (voff)[_i]), (LAS unsigned*)(lds + (bufoff) + ldsw + _i * 8192), 16, 0, 0); } while (0)
; #define PG8_LDA(dst, b, h) do { _Pragma("unroll") for (int m = 0; m < 4; ++m) _Pragma("unroll") for (int k = 0; k < 2; ++k) dst[m][k] = *(const LAS bf16x8*)(lds + PG8_SA(b, h) + aoff + m * 2048 + k * 1024); } while (0)
; #define PG8_LDB(dst, b, h) do { _Pragma("unroll") for (int n = 0; n < 2; ++n) _Pragma("unroll") for (int k = 0; k < 2; ++k) dst[n][k] = *(const LAS bf16x8*)(lds + PG8_SB(b, h) + boff + n * 2048 + k * 1024); } while (0)
; #define PG8_MMA(ai, bj, At, Bt) do { __builtin_amdgcn_s_setprio(1); _Pragma("unroll") for (int m = 0; m < 4; ++m) _Pragma("unroll") for (int n = 0; n < 2; ++n) _Pragma("unroll") for (int k = 0; k < 2; ++k) \
;         acc[ai][bj][m][n] = __builtin_amdgcn_mfma_f32_16x16x32_bf16(Bt[n][k], At[m][k], acc[ai][bj][m][n], 0, 0, 0); __builtin_amdgcn_s_setprio(0); } while (0)
; #define PG8_WAIT_V(n) asm volatile("s_waitcnt vmcnt(" #n ")" ::: "memory")
; #define PG8_WAIT_L(n) asm volatile("s_waitcnt lgkmcnt(" #n ")" ::: "memory")
; #define PG8_BAR __builtin_amdgcn_s_barrier()
; #define PG8_SCHED __builtin_amdgcn_sched_barrier(0)
; template <class Epi>
; __device__ __forceinline__ void gemm_phase(LAS unsigned char* lds, const Gemm g, const Sched& S, const Epi& E) {
;     ...
;             const bool last = (t == nt - 2);
;             const char* a1 = cA + (size_t)(t + 1) * kstep;
;             const char* a2 = last ? nA : cA + (size_t)(t + 2) * kstep; const char* b2 = last ? nB : cB + (size_t)(t + 2) * kstep;
;             const char* a3 = a2 + kstep; const char* b3 = b2 + kstep;
;             PG8_LDB(B0, 0, 0); PG8_LDB(B1, 0, 1); PG8_SCHED; PG8_LDA(At, 0, 0); PG8_STAGE(PG8_SA(1, 1), a1 + hstepA, voffA);
;             PG8_WAIT_V(8); PG8_WAIT_L(0); PG8_BAR; PG8_MMA(0, 0, At, B0); PG8_MMA(0, 1, At, B1); PG8_BAR; PG8_SCHED;
;             PG8_LDA(At, 0, 1); PG8_STAGE(PG8_SB(0, 0), b2, voffB); PG8_STAGE(PG8_SB(0, 1), b2 + hstepB, voffB); PG8_STAGE(PG8_SA(0, 0), a2, voffA);
;             PG8_WAIT_V(8); PG8_WAIT_L(0); PG8_BAR; PG8_MMA(1, 0, At, B0); PG8_MMA(1, 1, At, B1); PG8_BAR; PG8_SCHED;
.LBB0_293:
	ds_read_b128 v[146:149], v143
	ds_read_b128 v[150:153], v143 offset:1024
	ds_read_b128 v[154:157], v143 offset:2048
	ds_read_b128 v[158:161], v143 offset:3072
	ds_read_b128 v[162:165], v144
	ds_read_b128 v[166:169], v144 offset:1024
	ds_read_b128 v[170:173], v144 offset:2048
	ds_read_b128 v[174:177], v144 offset:3072
	s_add_u32 s40, s28, 0xfffc0080
	s_addc_u32 s41, s29, -1
	s_cmp_eq_u32 s66, 12
	s_cselect_b32 s45, s23, s41
	s_cselect_b32 s44, s62, s40
	s_cselect_b32 s41, s15, s65
	s_cselect_b32 s40, s63, s64
	v_lshl_add_u64 v[212:213], s[28:29], 0, v[136:137]
	s_add_i32 m0, s21, 0xc000
	ds_read_b128 v[178:181], v145
	ds_read_b128 v[182:185], v145 offset:1024
	ds_read_b128 v[186:189], v145 offset:2048
	ds_read_b128 v[190:193], v145 offset:3072
	ds_read_b128 v[194:197], v145 offset:4096
	ds_read_b128 v[198:201], v145 offset:5120
	ds_read_b128 v[204:207], v145 offset:6144
	ds_read_b128 v[208:211], v145 offset:7168
	global_load_lds_dwordx4 v[212:213], off
	v_lshl_add_u64 v[212:213], s[28:29], 0, v[138:139]
	s_add_i32 m0, s21, 0xe000
	s_nop 0
	global_load_lds_dwordx4 v[212:213], off
	s_waitcnt vmcnt(8)
	s_waitcnt lgkmcnt(0)
	s_barrier
	s_setprio 1
	s_waitcnt lgkmcnt(0)
	v_mfma_f32_16x16x32_bf16 v[124:127], v[146:149], v[178:181], v[124:127]
	v_mfma_f32_16x16x32_bf16 v[120:123], v[154:157], v[178:181], v[120:123]
	v_mfma_f32_16x16x32_bf16 v[116:119], v[146:149], v[186:189], v[116:119]
	v_mfma_f32_16x16x32_bf16 v[112:115], v[154:157], v[186:189], v[112:115]
	v_mfma_f32_16x16x32_bf16 v[100:103], v[146:149], v[194:197], v[100:103]
	v_mfma_f32_16x16x32_bf16 v[96:99], v[154:157], v[194:197], v[96:99]
	v_mfma_f32_16x16x32_bf16 v[84:87], v[146:149], v[204:207], v[84:87]
	v_mfma_f32_16x16x32_bf16 v[80:83], v[154:157], v[204:207], v[80:83]
	v_mfma_f32_16x16x32_bf16 v[124:127], v[150:153], v[182:185], v[124:127]
	v_mfma_f32_16x16x32_bf16 v[120:123], v[158:161], v[182:185], v[120:123]
	v_mfma_f32_16x16x32_bf16 v[116:119], v[150:153], v[190:193], v[116:119]
	v_mfma_f32_16x16x32_bf16 v[112:115], v[158:161], v[190:193], v[112:115]
	v_mfma_f32_16x16x32_bf16 v[100:103], v[150:153], v[198:201], v[100:103]
	v_mfma_f32_16x16x32_bf16 v[96:99], v[158:161], v[198:201], v[96:99]
	v_mfma_f32_16x16x32_bf16 v[84:87], v[150:153], v[208:211], v[84:87]
	v_mfma_f32_16x16x32_bf16 v[80:83], v[158:161], v[208:211], v[80:83]
	v_mfma_f32_16x16x32_bf16 v[108:111], v[162:165], v[178:181], v[108:111]
	v_mfma_f32_16x16x32_bf16 v[104:107], v[170:173], v[178:181], v[104:107]
	v_mfma_f32_16x16x32_bf16 v[92:95], v[162:165], v[186:189], v[92:95]
	v_mfma_f32_16x16x32_bf16 v[88:91], v[170:173], v[186:189], v[88:91]
	v_mfma_f32_16x16x32_bf16 v[76:79], v[162:165], v[194:197], v[76:79]
	v_mfma_f32_16x16x32_bf16 v[72:75], v[170:173], v[194:197], v[72:75]
	v_mfma_f32_16x16x32_bf16 v[68:71], v[162:165], v[204:207], v[68:71]
	v_mfma_f32_16x16x32_bf16 v[64:67], v[170:173], v[204:207], v[64:67]
	v_mfma_f32_16x16x32_bf16 v[108:111], v[166:169], v[182:185], v[108:111]
	v_mfma_f32_16x16x32_bf16 v[104:107], v[174:177], v[182:185], v[104:107]
	v_mfma_f32_16x16x32_bf16 v[92:95], v[166:169], v[190:193], v[92:95]
	v_mfma_f32_16x16x32_bf16 v[88:91], v[174:177], v[190:193], v[88:91]
	v_mfma_f32_16x16x32_bf16 v[76:79], v[166:169], v[198:201], v[76:79]
	v_mfma_f32_16x16x32_bf16 v[72:75], v[174:177], v[198:201], v[72:75]
	v_mfma_f32_16x16x32_bf16 v[68:71], v[166:169], v[208:211], v[68:71]
	v_mfma_f32_16x16x32_bf16 v[64:67], v[174:177], v[208:211], v[64:67]
	s_setprio 0
	s_barrier
	s_add_i32 s67, s59, s52
	v_lshl_add_u64 v[212:213], s[40:41], 0, v[130:131]
	s_mov_b32 m0, s67
	ds_read_b128 v[178:181], v145 offset:16384
	ds_read_b128 v[182:185], v145 offset:17408
	ds_read_b128 v[186:189], v145 offset:18432
	ds_read_b128 v[190:193], v145 offset:19456
	ds_read_b128 v[194:197], v145 offset:20480
	ds_read_b128 v[198:201], v145 offset:21504
	ds_read_b128 v[204:207], v145 offset:22528
	ds_read_b128 v[208:211], v145 offset:23552
	global_load_lds_dwordx4 v[212:213], off
	s_add_i32 m0, s67, 0x2000
	s_add_u32 s78, s40, 0x40000
	v_lshl_add_u64 v[214:215], s[40:41], 0, v[134:135]
	s_addc_u32 s79, s41, 0
	s_add_i32 s67, s60, s52
	global_load_lds_dwordx4 v[214:215], off
	v_lshl_add_u64 v[216:217], s[78:79], 0, v[130:131]
	s_mov_b32 m0, s67
	v_lshl_add_u64 v[218:219], s[44:45], 0, v[132:133]
	global_load_lds_dwordx4 v[216:217], off
	v_lshl_add_u64 v[216:217], s[78:79], 0, v[134:135]
	s_add_i32 m0, s67, 0x2000
	s_nop 0
	global_load_lds_dwordx4 v[216:217], off
	v_lshl_add_u64 v[216:217], s[44:45], 0, v[128:129]
	s_mov_b32 m0, s21
	s_nop 0
	global_load_lds_dwordx4 v[216:217], off
	s_mov_b32 m0, s53
	s_nop 0
	global_load_lds_dwordx4 v[218:219], off
	s_waitcnt vmcnt(8)
	s_waitcnt lgkmcnt(0)
	s_barrier
; #define PG8_STAGE(bufoff, gbase, voff) do { _Pragma("unroll") for (int _i = 0; _i < 2; ++_i) \
;         __builtin_amdgcn_global_load_lds((const unsigned*)((const char*)(gbase) + (voff)[_i]), (LAS unsigned*)(lds + (bufoff) + ldsw + _i * 8192), 16, 0, 0); } while (0)
; #define PG8_LDA(dst, b, h) do { _Pragma("unroll") for (int m = 0; m < 4; ++m) _Pragma("unroll") for (int k = 0; k < 2; ++k) dst[m][k] = *(const LAS bf16x8*)(lds + PG8_SA(b, h) + aoff + m * 2048 + k * 1024); } while (0)
; #define PG8_LDB(dst, b, h) do { _Pragma("unroll") for (int n = 0; n < 2; ++n) _Pragma("unroll") for (int k = 0; k < 2; ++k) dst[n][k] = *(const LAS bf16x8*)(lds + PG8_SB(b, h) + boff + n * 2048 + k * 1024); } while (0)
; #define PG8_MMA(ai, bj, At, Bt) do { __builtin_amdgcn_s_setprio(1); _Pragma("unroll") for (int m = 0; m < 4; ++m) _Pragma("unroll") for (int n = 0; n < 2; ++n) _Pragma("unroll") for (int k = 0; k < 2; ++k) \
;         acc[ai][bj][m][n] = __builtin_amdgcn_mfma_f32_16x16x32_bf16(Bt[n][k], At[m][k], acc[ai][bj][m][n], 0, 0, 0); __builtin_amdgcn_s_setprio(0); } while (0)
; #define PG8_WAIT_V(n) asm volatile("s_waitcnt vmcnt(" #n ")" ::: "memory")
; #define PG8_WAIT_L(n) asm volatile("s_waitcnt lgkmcnt(" #n ")" ::: "memory")
; #define PG8_BAR __builtin_amdgcn_s_barrier()
; #define PG8_SCHED __builtin_amdgcn_sched_barrier(0)
; template <class Epi>
; __device__ __forceinline__ void gemm_phase(LAS unsigned char* lds, const Gemm g, const Sched& S, const Epi& E) {
;     ...
;             PG8_WAIT_V(8); PG8_WAIT_L(0); PG8_BAR; PG8_MMA(1, 0, At, B0); PG8_MMA(1, 1, At, B1); PG8_BAR; PG8_SCHED;
;             PG8_LDB(B0, 1, 0); PG8_LDB(B1, 1, 1); PG8_SCHED; PG8_LDA(At, 1, 0); PG8_STAGE(PG8_SA(0, 1), a2 + hstepA, voffA);
;             PG8_WAIT_V(8); PG8_WAIT_L(0); PG8_BAR; PG8_MMA(0, 0, At, B0); PG8_MMA(0, 1, At, B1); PG8_BAR; PG8_SCHED;
	s_setprio 1
	s_waitcnt lgkmcnt(0)
	v_mfma_f32_16x16x32_bf16 v[60:63], v[146:149], v[178:181], v[60:63]
	v_mfma_f32_16x16x32_bf16 v[56:59], v[154:157], v[178:181], v[56:59]
	v_mfma_f32_16x16x32_bf16 v[52:55], v[146:149], v[186:189], v[52:55]
	v_mfma_f32_16x16x32_bf16 v[48:51], v[154:157], v[186:189], v[48:51]
	v_mfma_f32_16x16x32_bf16 v[36:39], v[146:149], v[194:197], v[36:39]
	v_mfma_f32_16x16x32_bf16 v[32:35], v[154:157], v[194:197], v[32:35]
	v_mfma_f32_16x16x32_bf16 v[20:23], v[146:149], v[204:207], v[20:23]
	v_mfma_f32_16x16x32_bf16 v[16:19], v[154:157], v[204:207], v[16:19]
	v_mfma_f32_16x16x32_bf16 v[60:63], v[150:153], v[182:185], v[60:63]
	v_mfma_f32_16x16x32_bf16 v[56:59], v[158:161], v[182:185], v[56:59]
	v_mfma_f32_16x16x32_bf16 v[52:55], v[150:153], v[190:193], v[52:55]
	v_mfma_f32_16x16x32_bf16 v[48:51], v[158:161], v[190:193], v[48:51]
	v_mfma_f32_16x16x32_bf16 v[36:39], v[150:153], v[198:201], v[36:39]
	v_mfma_f32_16x16x32_bf16 v[32:35], v[158:161], v[198:201], v[32:35]
	v_mfma_f32_16x16x32_bf16 v[20:23], v[150:153], v[208:211], v[20:23]
	v_mfma_f32_16x16x32_bf16 v[16:19], v[158:161], v[208:211], v[16:19]
	v_mfma_f32_16x16x32_bf16 v[44:47], v[162:165], v[178:181], v[44:47]
	v_mfma_f32_16x16x32_bf16 v[40:43], v[170:173], v[178:181], v[40:43]
	v_mfma_f32_16x16x32_bf16 v[28:31], v[162:165], v[186:189], v[28:31]
	v_mfma_f32_16x16x32_bf16 v[24:27], v[170:173], v[186:189], v[24:27]
	v_mfma_f32_16x16x32_bf16 v[12:15], v[162:165], v[194:197], v[12:15]
	v_mfma_f32_16x16x32_bf16 v[8:11], v[170:173], v[194:197], v[8:11]
	v_mfma_f32_16x16x32_bf16 v[4:7], v[162:165], v[204:207], v[4:7]
	v_mfma_f32_16x16x32_bf16 v[0:3], v[170:173], v[204:207], v[0:3]
	v_mfma_f32_16x16x32_bf16 v[44:47], v[166:169], v[182:185], v[44:47]
	v_mfma_f32_16x16x32_bf16 v[40:43], v[174:177], v[182:185], v[40:43]
	v_mfma_f32_16x16x32_bf16 v[28:31], v[166:169], v[190:193], v[28:31]
	v_mfma_f32_16x16x32_bf16 v[24:27], v[174:177], v[190:193], v[24:27]
	v_mfma_f32_16x16x32_bf16 v[12:15], v[166:169], v[198:201], v[12:15]
	v_mfma_f32_16x16x32_bf16 v[8:11], v[174:177], v[198:201], v[8:11]
	v_mfma_f32_16x16x32_bf16 v[4:7], v[166:169], v[208:211], v[4:7]
	v_mfma_f32_16x16x32_bf16 v[0:3], v[174:177], v[208:211], v[0:3]
	s_setprio 0
	s_barrier
	s_add_i32 s67, 0, 0x18000
	s_add_i32 s78, 0, 0x1c000
	v_add_u32_e32 v158, s67, v141
	v_add_u32_e32 v174, s78, v141
	ds_read_b128 v[146:149], v158
	ds_read_b128 v[150:153], v158 offset:1024
	ds_read_b128 v[154:157], v158 offset:2048
	ds_read_b128 v[158:161], v158 offset:3072
	ds_read_b128 v[162:165], v174
	ds_read_b128 v[166:169], v174 offset:1024
	ds_read_b128 v[170:173], v174 offset:2048
	ds_read_b128 v[174:177], v174 offset:3072
	s_add_u32 s44, s44, 0x40000
	s_addc_u32 s45, s45, 0
	s_mov_b32 m0, s54
	v_lshl_add_u64 v[220:221], s[44:45], 0, v[128:129]
	ds_read_b128 v[178:181], v145 offset:32768
	ds_read_b128 v[182:185], v145 offset:33792
	ds_read_b128 v[186:189], v145 offset:34816
	ds_read_b128 v[190:193], v145 offset:35840
	ds_read_b128 v[194:197], v145 offset:36864
	ds_read_b128 v[198:201], v145 offset:37888
	ds_read_b128 v[204:207], v145 offset:38912
	ds_read_b128 v[208:211], v145 offset:39936
	global_load_lds_dwordx4 v[220:221], off
	v_lshl_add_u64 v[220:221], s[44:45], 0, v[132:133]
	s_mov_b32 m0, s55
	s_nop 0
	global_load_lds_dwordx4 v[220:221], off
	s_waitcnt vmcnt(8)
	s_waitcnt lgkmcnt(0)
	s_barrier
	s_setprio 1
	s_waitcnt lgkmcnt(0)
	v_mfma_f32_16x16x32_bf16 v[124:127], v[146:149], v[178:181], v[124:127]
	v_mfma_f32_16x16x32_bf16 v[120:123], v[154:157], v[178:181], v[120:123]
	v_mfma_f32_16x16x32_bf16 v[116:119], v[146:149], v[186:189], v[116:119]
	v_mfma_f32_16x16x32_bf16 v[112:115], v[154:157], v[186:189], v[112:115]
	v_mfma_f32_16x16x32_bf16 v[100:103], v[146:149], v[194:197], v[100:103]
	v_mfma_f32_16x16x32_bf16 v[96:99], v[154:157], v[194:197], v[96:99]
	v_mfma_f32_16x16x32_bf16 v[84:87], v[146:149], v[204:207], v[84:87]
	v_mfma_f32_16x16x32_bf16 v[80:83], v[154:157], v[204:207], v[80:83]
	v_mfma_f32_16x16x32_bf16 v[124:127], v[150:153], v[182:185], v[124:127]
	v_mfma_f32_16x16x32_bf16 v[120:123], v[158:161], v[182:185], v[120:123]
	v_mfma_f32_16x16x32_bf16 v[116:119], v[150:153], v[190:193], v[116:119]
	v_mfma_f32_16x16x32_bf16 v[112:115], v[158:161], v[190:193], v[112:115]
	v_mfma_f32_16x16x32_bf16 v[100:103], v[150:153], v[198:201], v[100:103]
	v_mfma_f32_16x16x32_bf16 v[96:99], v[158:161], v[198:201], v[96:99]
	v_mfma_f32_16x16x32_bf16 v[84:87], v[150:153], v[208:211], v[84:87]
	v_mfma_f32_16x16x32_bf16 v[80:83], v[158:161], v[208:211], v[80:83]
	v_mfma_f32_16x16x32_bf16 v[108:111], v[162:165], v[178:181], v[108:111]
	v_mfma_f32_16x16x32_bf16 v[104:107], v[170:173], v[178:181], v[104:107]
	v_mfma_f32_16x16x32_bf16 v[92:95], v[162:165], v[186:189], v[92:95]
	v_mfma_f32_16x16x32_bf16 v[88:91], v[170:173], v[186:189], v[88:91]
	v_mfma_f32_16x16x32_bf16 v[76:79], v[162:165], v[194:197], v[76:79]
	v_mfma_f32_16x16x32_bf16 v[72:75], v[170:173], v[194:197], v[72:75]
	v_mfma_f32_16x16x32_bf16 v[68:71], v[162:165], v[204:207], v[68:71]
	v_mfma_f32_16x16x32_bf16 v[64:67], v[170:173], v[204:207], v[64:67]
	v_mfma_f32_16x16x32_bf16 v[108:111], v[166:169], v[182:185], v[108:111]
	v_mfma_f32_16x16x32_bf16 v[104:107], v[174:177], v[182:185], v[104:107]
	v_mfma_f32_16x16x32_bf16 v[92:95], v[166:169], v[190:193], v[92:95]
	v_mfma_f32_16x16x32_bf16 v[88:91], v[174:177], v[190:193], v[88:91]
	v_mfma_f32_16x16x32_bf16 v[76:79], v[166:169], v[198:201], v[76:79]
	v_mfma_f32_16x16x32_bf16 v[72:75], v[174:177], v[198:201], v[72:75]
	v_mfma_f32_16x16x32_bf16 v[68:71], v[166:169], v[208:211], v[68:71]
	v_mfma_f32_16x16x32_bf16 v[64:67], v[174:177], v[208:211], v[64:67]
	s_setprio 0
	s_barrier
; #define PG8_STAGE(bufoff, gbase, voff) do { _Pragma("unroll") for (int _i = 0; _i < 2; ++_i) \
;         __builtin_amdgcn_global_load_lds((const unsigned*)((const char*)(gbase) + (voff)[_i]), (LAS unsigned*)(lds + (bufoff) + ldsw + _i * 8192), 16, 0, 0); } while (0)
; #define PG8_LDA(dst, b, h) do { _Pragma("unroll") for (int m = 0; m < 4; ++m) _Pragma("unroll") for (int k = 0; k < 2; ++k) dst[m][k] = *(const LAS bf16x8*)(lds + PG8_SA(b, h) + aoff + m * 2048 + k * 1024); } while (0)
; #define PG8_MMA(ai, bj, At, Bt) do { __builtin_amdgcn_s_setprio(1); _Pragma("unroll") for (int m = 0; m < 4; ++m) _Pragma("unroll") for (int n = 0; n < 2; ++n) _Pragma("unroll") for (int k = 0; k < 2; ++k) \
;         acc[ai][bj][m][n] = __builtin_amdgcn_mfma_f32_16x16x32_bf16(Bt[n][k], At[m][k], acc[ai][bj][m][n], 0, 0, 0); __builtin_amdgcn_s_setprio(0); } while (0)
; #define PG8_WAIT_V(n) asm volatile("s_waitcnt vmcnt(" #n ")" ::: "memory")
; #define PG8_WAIT_L(n) asm volatile("s_waitcnt lgkmcnt(" #n ")" ::: "memory")
; #define PG8_BAR __builtin_amdgcn_s_barrier()
; #define PG8_SCHED __builtin_amdgcn_sched_barrier(0)
; template <class Epi>
; __device__ __forceinline__ void gemm_phase(LAS unsigned char* lds, const Gemm g, const Sched& S, const Epi& E) {
;     ...
;             PG8_LDA(At, 1, 1); PG8_STAGE(PG8_SB(1, 0), b3, voffB); PG8_STAGE(PG8_SB(1, 1), b3 + hstepB, voffB); PG8_STAGE(PG8_SA(1, 0), a3, voffA);
;             PG8_WAIT_V(8); PG8_WAIT_L(0); PG8_BAR; PG8_MMA(1, 0, At, B0); PG8_MMA(1, 1, At, B1); PG8_BAR; PG8_SCHED;
;         }
	s_add_i32 s44, s67, s52
	v_lshl_add_u64 v[212:213], v[212:213], 0, s[4:5]
	s_mov_b32 m0, s44
	ds_read_b128 v[178:181], v145 offset:49152
	ds_read_b128 v[182:185], v145 offset:50176
	ds_read_b128 v[186:189], v145 offset:51200
	ds_read_b128 v[190:193], v145 offset:52224
	ds_read_b128 v[194:197], v145 offset:53248
	ds_read_b128 v[198:201], v145 offset:54272
	ds_read_b128 v[204:207], v145 offset:55296
	ds_read_b128 v[208:211], v145 offset:56320
	global_load_lds_dwordx4 v[212:213], off
	s_add_i32 m0, s44, 0x2000
	s_add_u32 s40, s40, 0x40080
	v_lshl_add_u64 v[212:213], v[214:215], 0, s[4:5]
	s_addc_u32 s41, s41, 0
	s_add_i32 s44, s78, s52
	global_load_lds_dwordx4 v[212:213], off
	v_lshl_add_u64 v[212:213], s[40:41], 0, v[130:131]
	s_mov_b32 m0, s44
	s_nop 0
	global_load_lds_dwordx4 v[212:213], off
	v_lshl_add_u64 v[212:213], s[40:41], 0, v[134:135]
	s_add_i32 m0, s44, 0x2000
	s_nop 0
	global_load_lds_dwordx4 v[212:213], off
	v_lshl_add_u64 v[212:213], v[216:217], 0, s[4:5]
	s_mov_b32 m0, s57
	s_nop 0
	global_load_lds_dwordx4 v[212:213], off
	v_lshl_add_u64 v[212:213], v[218:219], 0, s[4:5]
	s_mov_b32 m0, s58
	s_nop 0
	global_load_lds_dwordx4 v[212:213], off
	s_waitcnt vmcnt(8)
	s_waitcnt lgkmcnt(0)
	s_barrier
	s_setprio 1
	s_waitcnt lgkmcnt(0)
	v_mfma_f32_16x16x32_bf16 v[60:63], v[146:149], v[178:181], v[60:63]
	v_mfma_f32_16x16x32_bf16 v[56:59], v[154:157], v[178:181], v[56:59]
	v_mfma_f32_16x16x32_bf16 v[52:55], v[146:149], v[186:189], v[52:55]
	v_mfma_f32_16x16x32_bf16 v[48:51], v[154:157], v[186:189], v[48:51]
	v_mfma_f32_16x16x32_bf16 v[36:39], v[146:149], v[194:197], v[36:39]
	v_mfma_f32_16x16x32_bf16 v[32:35], v[154:157], v[194:197], v[32:35]
	v_mfma_f32_16x16x32_bf16 v[20:23], v[146:149], v[204:207], v[20:23]
	v_mfma_f32_16x16x32_bf16 v[16:19], v[154:157], v[204:207], v[16:19]
	v_mfma_f32_16x16x32_bf16 v[60:63], v[150:153], v[182:185], v[60:63]
	v_mfma_f32_16x16x32_bf16 v[56:59], v[158:161], v[182:185], v[56:59]
	v_mfma_f32_16x16x32_bf16 v[52:55], v[150:153], v[190:193], v[52:55]
	v_mfma_f32_16x16x32_bf16 v[48:51], v[158:161], v[190:193], v[48:51]
	v_mfma_f32_16x16x32_bf16 v[36:39], v[150:153], v[198:201], v[36:39]
	v_mfma_f32_16x16x32_bf16 v[32:35], v[158:161], v[198:201], v[32:35]
	v_mfma_f32_16x16x32_bf16 v[20:23], v[150:153], v[208:211], v[20:23]
	v_mfma_f32_16x16x32_bf16 v[16:19], v[158:161], v[208:211], v[16:19]
	v_mfma_f32_16x16x32_bf16 v[44:47], v[162:165], v[178:181], v[44:47]
	v_mfma_f32_16x16x32_bf16 v[40:43], v[170:173], v[178:181], v[40:43]
	v_mfma_f32_16x16x32_bf16 v[28:31], v[162:165], v[186:189], v[28:31]
	v_mfma_f32_16x16x32_bf16 v[24:27], v[170:173], v[186:189], v[24:27]
	v_mfma_f32_16x16x32_bf16 v[12:15], v[162:165], v[194:197], v[12:15]
	v_mfma_f32_16x16x32_bf16 v[8:11], v[170:173], v[194:197], v[8:11]
	v_mfma_f32_16x16x32_bf16 v[4:7], v[162:165], v[204:207], v[4:7]
	v_mfma_f32_16x16x32_bf16 v[0:3], v[170:173], v[204:207], v[0:3]
	v_mfma_f32_16x16x32_bf16 v[44:47], v[166:169], v[182:185], v[44:47]
	v_mfma_f32_16x16x32_bf16 v[40:43], v[174:177], v[182:185], v[40:43]
	v_mfma_f32_16x16x32_bf16 v[28:31], v[166:169], v[190:193], v[28:31]
	v_mfma_f32_16x16x32_bf16 v[24:27], v[174:177], v[190:193], v[24:27]
	v_mfma_f32_16x16x32_bf16 v[12:15], v[166:169], v[198:201], v[12:15]
	v_mfma_f32_16x16x32_bf16 v[8:11], v[174:177], v[198:201], v[8:11]
	v_mfma_f32_16x16x32_bf16 v[4:7], v[166:169], v[208:211], v[4:7]
	v_mfma_f32_16x16x32_bf16 v[0:3], v[174:177], v[208:211], v[0:3]
	s_setprio 0
	s_barrier
	s_add_i32 s66, s66, 2
	s_add_u32 s28, s28, 0x100
	s_addc_u32 s29, s29, 0
	s_add_u32 s64, s64, 0x100
	s_addc_u32 s65, s65, 0
	s_cmp_gt_u32 s66, 13
	s_cbranch_scc0 .LBB0_293
	s_and_b64 vcc, exec, s[6:7]
	s_cbranch_vccz .LBB0_296
	s_barrier

; #define PG8_STAGE(bufoff, gbase, voff) do { _Pragma("unroll") for (int _i = 0; _i < 2; ++_i) \
;         __builtin_amdgcn_global_load_lds((const unsigned*)((const char*)(gbase) + (voff)[_i]), (LAS unsigned*)(lds + (bufoff) + ldsw + _i * 8192), 16, 0, 0); } while (0)
; #define PG8_LDA(dst, b, h) do { _Pragma("unroll") for (int m = 0; m < 4; ++m) _Pragma("unroll") for (int k = 0; k < 2; ++k) dst[m][k] = *(const LAS bf16x8*)(lds + PG8_SA(b, h) + aoff + m * 2048 + k * 1024); } while (0)
; #define PG8_LDB(dst, b, h) do { _Pragma("unroll") for (int n = 0; n < 2; ++n) _Pragma("unroll") for (int k = 0; k < 2; ++k) dst[n][k] = *(const LAS bf16x8*)(lds + PG8_SB(b, h) + boff + n * 2048 + k * 1024); } while (0)
; #define PG8_MMA(ai, bj, At, Bt) do { __builtin_amdgcn_s_setprio(1); _Pragma("unroll") for (int m = 0; m < 4; ++m) _Pragma("unroll") for (int n = 0; n < 2; ++n) _Pragma("unroll") for (int k = 0; k < 2; ++k) \
;         acc[ai][bj][m][n] = __builtin_amdgcn_mfma_f32_16x16x32_bf16(Bt[n][k], At[m][k], acc[ai][bj][m][n], 0, 0, 0); __builtin_amdgcn_s_setprio(0); } while (0)
; #define PG8_WAIT_V(n) asm volatile("s_waitcnt vmcnt(" #n ")" ::: "memory")
; #define PG8_WAIT_L(n) asm volatile("s_waitcnt lgkmcnt(" #n ")" ::: "memory")
; #define PG8_BAR __builtin_amdgcn_s_barrier()
; #define PG8_SCHED __builtin_amdgcn_sched_barrier(0)
; template <class Epi>
; __device__ __forceinline__ void gemm_phase(LAS unsigned char* lds, const Gemm g, const Sched& S, const Epi& E) {
;     ...
;             const bool last = (t == nt - 2);
;             const char* a1 = cA + (size_t)(t + 1) * kstep;
;             const char* a2 = last ? nA : cA + (size_t)(t + 2) * kstep; const char* b2 = last ? nB : cB + (size_t)(t + 2) * kstep;
;             const char* a3 = a2 + kstep; const char* b3 = b2 + kstep;
;             PG8_LDB(B0, 0, 0); PG8_LDB(B1, 0, 1); PG8_SCHED; PG8_LDA(At, 0, 0); PG8_STAGE(PG8_SA(1, 1), a1 + hstepA, voffA);
;             PG8_WAIT_V(8); PG8_WAIT_L(0); PG8_BAR; PG8_MMA(0, 0, At, B0); PG8_MMA(0, 1, At, B1); PG8_BAR; PG8_SCHED;
;             PG8_LDA(At, 0, 1); PG8_STAGE(PG8_SB(0, 0), b2, voffB); PG8_STAGE(PG8_SB(0, 1), b2 + hstepB, voffB); PG8_STAGE(PG8_SA(0, 0), a2, voffA);
;             PG8_WAIT_V(8); PG8_WAIT_L(0); PG8_BAR; PG8_MMA(1, 0, At, B0); PG8_MMA(1, 1, At, B1); PG8_BAR; PG8_SCHED;
.LBB0_374:
	v_add_u32_e32 v158, s64, v144
	v_add_u32_e32 v174, s65, v144
	s_add_u32 s40, s26, s28
	ds_read_b128 v[146:149], v158
	ds_read_b128 v[150:153], v158 offset:1024
	ds_read_b128 v[154:157], v158 offset:2048
	ds_read_b128 v[158:161], v158 offset:3072
	ds_read_b128 v[162:165], v174
	ds_read_b128 v[166:169], v174 offset:1024
	ds_read_b128 v[170:173], v174 offset:2048
	ds_read_b128 v[174:177], v174 offset:3072
	s_addc_u32 s41, s27, s29
	s_add_u32 s40, s40, 0x100
	s_addc_u32 s41, s41, 0
	s_add_u32 s84, s87, s28
	s_addc_u32 s85, s88, s29
	s_cmpk_eq_i32 s28, 0x1500
	s_cselect_b32 s45, s23, s41
	s_cselect_b32 s44, s22, s40
	s_cselect_b32 s41, s25, s85
	s_cselect_b32 s40, s24, s84
	s_mov_b32 m0, s66
	v_lshl_add_u64 v[186:187], v[140:141], 0, s[28:29]
	ds_read_b128 v[178:181], v145
	ds_read_b128 v[182:185], v145 offset:1024
	ds_read_b128 v[192:195], v145 offset:2048
	ds_read_b128 v[196:199], v145 offset:3072
	ds_read_b128 v[204:207], v145 offset:4096
	ds_read_b128 v[208:211], v145 offset:5120
	ds_read_b128 v[212:215], v145 offset:6144
	ds_read_b128 v[216:219], v145 offset:7168
	global_load_lds_dwordx4 v[186:187], off
	v_lshl_add_u64 v[186:187], v[142:143], 0, s[28:29]
	s_mov_b32 m0, s67
	s_nop 0
	global_load_lds_dwordx4 v[186:187], off
	s_waitcnt vmcnt(8)
	s_waitcnt lgkmcnt(0)
	s_barrier
	s_setprio 1
	s_waitcnt lgkmcnt(0)
	v_mfma_f32_16x16x32_bf16 v[124:127], v[146:149], v[178:181], v[124:127]
	v_mfma_f32_16x16x32_bf16 v[120:123], v[154:157], v[178:181], v[120:123]
	v_mfma_f32_16x16x32_bf16 v[108:111], v[146:149], v[192:195], v[108:111]
	v_mfma_f32_16x16x32_bf16 v[104:107], v[154:157], v[192:195], v[104:107]
	v_mfma_f32_16x16x32_bf16 v[92:95], v[146:149], v[204:207], v[92:95]
	v_mfma_f32_16x16x32_bf16 v[88:91], v[154:157], v[204:207], v[88:91]
	v_mfma_f32_16x16x32_bf16 v[76:79], v[146:149], v[212:215], v[76:79]
	v_mfma_f32_16x16x32_bf16 v[72:75], v[154:157], v[212:215], v[72:75]
	v_mfma_f32_16x16x32_bf16 v[124:127], v[150:153], v[182:185], v[124:127]
	v_mfma_f32_16x16x32_bf16 v[120:123], v[158:161], v[182:185], v[120:123]
	v_mfma_f32_16x16x32_bf16 v[108:111], v[150:153], v[196:199], v[108:111]
	v_mfma_f32_16x16x32_bf16 v[104:107], v[158:161], v[196:199], v[104:107]
	v_mfma_f32_16x16x32_bf16 v[92:95], v[150:153], v[208:211], v[92:95]
	v_mfma_f32_16x16x32_bf16 v[88:91], v[158:161], v[208:211], v[88:91]
	v_mfma_f32_16x16x32_bf16 v[76:79], v[150:153], v[216:219], v[76:79]
	v_mfma_f32_16x16x32_bf16 v[72:75], v[158:161], v[216:219], v[72:75]
	v_mfma_f32_16x16x32_bf16 v[116:119], v[162:165], v[178:181], v[116:119]
	v_mfma_f32_16x16x32_bf16 v[112:115], v[170:173], v[178:181], v[112:115]
	v_mfma_f32_16x16x32_bf16 v[100:103], v[162:165], v[192:195], v[100:103]
	v_mfma_f32_16x16x32_bf16 v[96:99], v[170:173], v[192:195], v[96:99]
	v_mfma_f32_16x16x32_bf16 v[84:87], v[162:165], v[204:207], v[84:87]
	v_mfma_f32_16x16x32_bf16 v[80:83], v[170:173], v[204:207], v[80:83]
	v_mfma_f32_16x16x32_bf16 v[68:71], v[162:165], v[212:215], v[68:71]
	v_mfma_f32_16x16x32_bf16 v[64:67], v[170:173], v[212:215], v[64:67]
	v_mfma_f32_16x16x32_bf16 v[116:119], v[166:169], v[182:185], v[116:119]
	v_mfma_f32_16x16x32_bf16 v[112:115], v[174:177], v[182:185], v[112:115]
	v_mfma_f32_16x16x32_bf16 v[100:103], v[166:169], v[196:199], v[100:103]
	v_mfma_f32_16x16x32_bf16 v[96:99], v[174:177], v[196:199], v[96:99]
	v_mfma_f32_16x16x32_bf16 v[84:87], v[166:169], v[208:211], v[84:87]
	v_mfma_f32_16x16x32_bf16 v[80:83], v[174:177], v[208:211], v[80:83]
	v_mfma_f32_16x16x32_bf16 v[68:71], v[166:169], v[216:219], v[68:71]
	v_mfma_f32_16x16x32_bf16 v[64:67], v[174:177], v[216:219], v[64:67]
	s_setprio 0
	s_barrier
	s_mov_b32 m0, s78
	v_lshl_add_u64 v[186:187], s[40:41], 0, v[130:131]
	ds_read_b128 v[178:181], v145 offset:16384
	ds_read_b128 v[182:185], v145 offset:17408
	ds_read_b128 v[192:195], v145 offset:18432
	ds_read_b128 v[196:199], v145 offset:19456
	ds_read_b128 v[204:207], v145 offset:20480
	ds_read_b128 v[208:211], v145 offset:21504
	ds_read_b128 v[212:215], v145 offset:22528
	ds_read_b128 v[216:219], v145 offset:23552
	global_load_lds_dwordx4 v[186:187], off
	s_add_i32 m0, s78, 0x2000
	s_add_u32 s84, s40, 0xb0000
	v_lshl_add_u64 v[200:201], s[40:41], 0, v[134:135]
	s_addc_u32 s85, s41, 0
	s_add_i32 s90, s65, s56
	global_load_lds_dwordx4 v[200:201], off
	v_lshl_add_u64 v[220:221], s[84:85], 0, v[130:131]
	s_mov_b32 m0, s90
	v_lshl_add_u64 v[222:223], s[44:45], 0, v[132:133]
	global_load_lds_dwordx4 v[220:221], off
	v_lshl_add_u64 v[220:221], s[84:85], 0, v[134:135]
	s_add_i32 m0, s90, 0x2000
	s_nop 0
	global_load_lds_dwordx4 v[220:221], off
	v_lshl_add_u64 v[220:221], s[44:45], 0, v[128:129]
	s_mov_b32 m0, s57
	s_nop 0
	global_load_lds_dwordx4 v[220:221], off
	s_mov_b32 m0, s58
	s_nop 0
	global_load_lds_dwordx4 v[222:223], off
	s_waitcnt vmcnt(8)
	s_waitcnt lgkmcnt(0)
	s_barrier
; #define PG8_STAGE(bufoff, gbase, voff) do { _Pragma("unroll") for (int _i = 0; _i < 2; ++_i) \
;         __builtin_amdgcn_global_load_lds((const unsigned*)((const char*)(gbase) + (voff)[_i]), (LAS unsigned*)(lds + (bufoff) + ldsw + _i * 8192), 16, 0, 0); } while (0)
; #define PG8_LDA(dst, b, h) do { _Pragma("unroll") for (int m = 0; m < 4; ++m) _Pragma("unroll") for (int k = 0; k < 2; ++k) dst[m][k] = *(const LAS bf16x8*)(lds + PG8_SA(b, h) + aoff + m * 2048 + k * 1024); } while (0)
; #define PG8_LDB(dst, b, h) do { _Pragma("unroll") for (int n = 0; n < 2; ++n) _Pragma("unroll") for (int k = 0; k < 2; ++k) dst[n][k] = *(const LAS bf16x8*)(lds + PG8_SB(b, h) + boff + n * 2048 + k * 1024); } while (0)
; #define PG8_MMA(ai, bj, At, Bt) do { __builtin_amdgcn_s_setprio(1); _Pragma("unroll") for (int m = 0; m < 4; ++m) _Pragma("unroll") for (int n = 0; n < 2; ++n) _Pragma("unroll") for (int k = 0; k < 2; ++k) \
;         acc[ai][bj][m][n] = __builtin_amdgcn_mfma_f32_16x16x32_bf16(Bt[n][k], At[m][k], acc[ai][bj][m][n], 0, 0, 0); __builtin_amdgcn_s_setprio(0); } while (0)
; #define PG8_WAIT_V(n) asm volatile("s_waitcnt vmcnt(" #n ")" ::: "memory")
; #define PG8_WAIT_L(n) asm volatile("s_waitcnt lgkmcnt(" #n ")" ::: "memory")
; #define PG8_BAR __builtin_amdgcn_s_barrier()
; #define PG8_SCHED __builtin_amdgcn_sched_barrier(0)
; template <class Epi>
; __device__ __forceinline__ void gemm_phase(LAS unsigned char* lds, const Gemm g, const Sched& S, const Epi& E) {
;     ...
;             PG8_WAIT_V(8); PG8_WAIT_L(0); PG8_BAR; PG8_MMA(1, 0, At, B0); PG8_MMA(1, 1, At, B1); PG8_BAR; PG8_SCHED;
;             PG8_LDB(B0, 1, 0); PG8_LDB(B1, 1, 1); PG8_SCHED; PG8_LDA(At, 1, 0); PG8_STAGE(PG8_SA(0, 1), a2 + hstepA, voffA);
;             PG8_WAIT_V(8); PG8_WAIT_L(0); PG8_BAR; PG8_MMA(0, 0, At, B0); PG8_MMA(0, 1, At, B1); PG8_BAR; PG8_SCHED;
	s_setprio 1
	s_waitcnt lgkmcnt(0)
	v_mfma_f32_16x16x32_bf16 v[60:63], v[146:149], v[178:181], v[60:63]
	v_mfma_f32_16x16x32_bf16 v[56:59], v[154:157], v[178:181], v[56:59]
	v_mfma_f32_16x16x32_bf16 v[44:47], v[146:149], v[192:195], v[44:47]
	v_mfma_f32_16x16x32_bf16 v[40:43], v[154:157], v[192:195], v[40:43]
	v_mfma_f32_16x16x32_bf16 v[28:31], v[146:149], v[204:207], v[28:31]
	v_mfma_f32_16x16x32_bf16 v[24:27], v[154:157], v[204:207], v[24:27]
	v_mfma_f32_16x16x32_bf16 v[12:15], v[146:149], v[212:215], v[12:15]
	v_mfma_f32_16x16x32_bf16 v[8:11], v[154:157], v[212:215], v[8:11]
	v_mfma_f32_16x16x32_bf16 v[60:63], v[150:153], v[182:185], v[60:63]
	v_mfma_f32_16x16x32_bf16 v[56:59], v[158:161], v[182:185], v[56:59]
	v_mfma_f32_16x16x32_bf16 v[44:47], v[150:153], v[196:199], v[44:47]
	v_mfma_f32_16x16x32_bf16 v[40:43], v[158:161], v[196:199], v[40:43]
	v_mfma_f32_16x16x32_bf16 v[28:31], v[150:153], v[208:211], v[28:31]
	v_mfma_f32_16x16x32_bf16 v[24:27], v[158:161], v[208:211], v[24:27]
	v_mfma_f32_16x16x32_bf16 v[12:15], v[150:153], v[216:219], v[12:15]
	v_mfma_f32_16x16x32_bf16 v[8:11], v[158:161], v[216:219], v[8:11]
	v_mfma_f32_16x16x32_bf16 v[52:55], v[162:165], v[178:181], v[52:55]
	v_mfma_f32_16x16x32_bf16 v[48:51], v[170:173], v[178:181], v[48:51]
	v_mfma_f32_16x16x32_bf16 v[36:39], v[162:165], v[192:195], v[36:39]
	v_mfma_f32_16x16x32_bf16 v[32:35], v[170:173], v[192:195], v[32:35]
	v_mfma_f32_16x16x32_bf16 v[20:23], v[162:165], v[204:207], v[20:23]
	v_mfma_f32_16x16x32_bf16 v[16:19], v[170:173], v[204:207], v[16:19]
	v_mfma_f32_16x16x32_bf16 v[4:7], v[162:165], v[212:215], v[4:7]
	v_mfma_f32_16x16x32_bf16 v[0:3], v[170:173], v[212:215], v[0:3]
	v_mfma_f32_16x16x32_bf16 v[52:55], v[166:169], v[182:185], v[52:55]
	v_mfma_f32_16x16x32_bf16 v[48:51], v[174:177], v[182:185], v[48:51]
	v_mfma_f32_16x16x32_bf16 v[36:39], v[166:169], v[196:199], v[36:39]
	v_mfma_f32_16x16x32_bf16 v[32:35], v[174:177], v[196:199], v[32:35]
	v_mfma_f32_16x16x32_bf16 v[20:23], v[166:169], v[208:211], v[20:23]
	v_mfma_f32_16x16x32_bf16 v[16:19], v[174:177], v[208:211], v[16:19]
	v_mfma_f32_16x16x32_bf16 v[4:7], v[166:169], v[216:219], v[4:7]
	v_mfma_f32_16x16x32_bf16 v[0:3], v[174:177], v[216:219], v[0:3]
	s_setprio 0
	s_barrier
	s_add_i32 s84, 0, 0x18000
	s_add_i32 s85, 0, 0x1c000
	v_add_u32_e32 v158, s84, v144
	v_add_u32_e32 v174, s85, v144
	ds_read_b128 v[146:149], v158
	ds_read_b128 v[150:153], v158 offset:1024
	ds_read_b128 v[154:157], v158 offset:2048
	ds_read_b128 v[158:161], v158 offset:3072
	ds_read_b128 v[162:165], v174
	ds_read_b128 v[166:169], v174 offset:1024
	ds_read_b128 v[170:173], v174 offset:2048
	ds_read_b128 v[174:177], v174 offset:3072
	s_add_u32 s44, s44, 0xb0000
	s_addc_u32 s45, s45, 0
	s_mov_b32 m0, s59
	v_lshl_add_u64 v[224:225], s[44:45], 0, v[128:129]
	ds_read_b128 v[178:181], v145 offset:32768
	ds_read_b128 v[182:185], v145 offset:33792
	ds_read_b128 v[192:195], v145 offset:34816
	ds_read_b128 v[196:199], v145 offset:35840
	ds_read_b128 v[204:207], v145 offset:36864
	ds_read_b128 v[208:211], v145 offset:37888
	ds_read_b128 v[212:215], v145 offset:38912
	ds_read_b128 v[216:219], v145 offset:39936
	global_load_lds_dwordx4 v[224:225], off
	v_lshl_add_u64 v[224:225], s[44:45], 0, v[132:133]
	s_mov_b32 m0, s60
	s_nop 0
	global_load_lds_dwordx4 v[224:225], off
	s_waitcnt vmcnt(8)
	s_waitcnt lgkmcnt(0)
	s_barrier
	s_setprio 1
	s_waitcnt lgkmcnt(0)
	v_mfma_f32_16x16x32_bf16 v[124:127], v[146:149], v[178:181], v[124:127]
	v_mfma_f32_16x16x32_bf16 v[120:123], v[154:157], v[178:181], v[120:123]
	v_mfma_f32_16x16x32_bf16 v[108:111], v[146:149], v[192:195], v[108:111]
	v_mfma_f32_16x16x32_bf16 v[104:107], v[154:157], v[192:195], v[104:107]
	v_mfma_f32_16x16x32_bf16 v[92:95], v[146:149], v[204:207], v[92:95]
	v_mfma_f32_16x16x32_bf16 v[88:91], v[154:157], v[204:207], v[88:91]
	v_mfma_f32_16x16x32_bf16 v[76:79], v[146:149], v[212:215], v[76:79]
	v_mfma_f32_16x16x32_bf16 v[72:75], v[154:157], v[212:215], v[72:75]
	v_mfma_f32_16x16x32_bf16 v[124:127], v[150:153], v[182:185], v[124:127]
	v_mfma_f32_16x16x32_bf16 v[120:123], v[158:161], v[182:185], v[120:123]
	v_mfma_f32_16x16x32_bf16 v[108:111], v[150:153], v[196:199], v[108:111]
	v_mfma_f32_16x16x32_bf16 v[104:107], v[158:161], v[196:199], v[104:107]
	v_mfma_f32_16x16x32_bf16 v[92:95], v[150:153], v[208:211], v[92:95]
	v_mfma_f32_16x16x32_bf16 v[88:91], v[158:161], v[208:211], v[88:91]
	v_mfma_f32_16x16x32_bf16 v[76:79], v[150:153], v[216:219], v[76:79]
	v_mfma_f32_16x16x32_bf16 v[72:75], v[158:161], v[216:219], v[72:75]
	v_mfma_f32_16x16x32_bf16 v[116:119], v[162:165], v[178:181], v[116:119]
	v_mfma_f32_16x16x32_bf16 v[112:115], v[170:173], v[178:181], v[112:115]
	v_mfma_f32_16x16x32_bf16 v[100:103], v[162:165], v[192:195], v[100:103]
	v_mfma_f32_16x16x32_bf16 v[96:99], v[170:173], v[192:195], v[96:99]
	v_mfma_f32_16x16x32_bf16 v[84:87], v[162:165], v[204:207], v[84:87]
	v_mfma_f32_16x16x32_bf16 v[80:83], v[170:173], v[204:207], v[80:83]
	v_mfma_f32_16x16x32_bf16 v[68:71], v[162:165], v[212:215], v[68:71]
	v_mfma_f32_16x16x32_bf16 v[64:67], v[170:173], v[212:215], v[64:67]
	v_mfma_f32_16x16x32_bf16 v[116:119], v[166:169], v[182:185], v[116:119]
	v_mfma_f32_16x16x32_bf16 v[112:115], v[174:177], v[182:185], v[112:115]
	v_mfma_f32_16x16x32_bf16 v[100:103], v[166:169], v[196:199], v[100:103]
	v_mfma_f32_16x16x32_bf16 v[96:99], v[174:177], v[196:199], v[96:99]
	v_mfma_f32_16x16x32_bf16 v[84:87], v[166:169], v[208:211], v[84:87]
	v_mfma_f32_16x16x32_bf16 v[80:83], v[174:177], v[208:211], v[80:83]
	v_mfma_f32_16x16x32_bf16 v[68:71], v[166:169], v[216:219], v[68:71]
	v_mfma_f32_16x16x32_bf16 v[64:67], v[174:177], v[216:219], v[64:67]
	s_setprio 0
	s_barrier
; #define PG8_STAGE(bufoff, gbase, voff) do { _Pragma("unroll") for (int _i = 0; _i < 2; ++_i) \
;         __builtin_amdgcn_global_load_lds((const unsigned*)((const char*)(gbase) + (voff)[_i]), (LAS unsigned*)(lds + (bufoff) + ldsw + _i * 8192), 16, 0, 0); } while (0)
; #define PG8_LDA(dst, b, h) do { _Pragma("unroll") for (int m = 0; m < 4; ++m) _Pragma("unroll") for (int k = 0; k < 2; ++k) dst[m][k] = *(const LAS bf16x8*)(lds + PG8_SA(b, h) + aoff + m * 2048 + k * 1024); } while (0)
; #define PG8_MMA(ai, bj, At, Bt) do { __builtin_amdgcn_s_setprio(1); _Pragma("unroll") for (int m = 0; m < 4; ++m) _Pragma("unroll") for (int n = 0; n < 2; ++n) _Pragma("unroll") for (int k = 0; k < 2; ++k) \
;         acc[ai][bj][m][n] = __builtin_amdgcn_mfma_f32_16x16x32_bf16(Bt[n][k], At[m][k], acc[ai][bj][m][n], 0, 0, 0); __builtin_amdgcn_s_setprio(0); } while (0)
; #define PG8_WAIT_V(n) asm volatile("s_waitcnt vmcnt(" #n ")" ::: "memory")
; #define PG8_WAIT_L(n) asm volatile("s_waitcnt lgkmcnt(" #n ")" ::: "memory")
; #define PG8_BAR __builtin_amdgcn_s_barrier()
; #define PG8_SCHED __builtin_amdgcn_sched_barrier(0)
; template <class Epi>
; __device__ __forceinline__ void gemm_phase(LAS unsigned char* lds, const Gemm g, const Sched& S, const Epi& E) {
;     ...
;             PG8_LDA(At, 1, 1); PG8_STAGE(PG8_SB(1, 0), b3, voffB); PG8_STAGE(PG8_SB(1, 1), b3 + hstepB, voffB); PG8_STAGE(PG8_SA(1, 0), a3, voffA);
;             PG8_WAIT_V(8); PG8_WAIT_L(0); PG8_BAR; PG8_MMA(1, 0, At, B0); PG8_MMA(1, 1, At, B1); PG8_BAR; PG8_SCHED;
;         }
	s_add_i32 s44, s84, s56
	v_lshl_add_u64 v[186:187], v[186:187], 0, s[8:9]
	s_mov_b32 m0, s44
	ds_read_b128 v[178:181], v145 offset:49152
	ds_read_b128 v[182:185], v145 offset:50176
	ds_read_b128 v[192:195], v145 offset:51200
	ds_read_b128 v[196:199], v145 offset:52224
	ds_read_b128 v[204:207], v145 offset:53248
	ds_read_b128 v[208:211], v145 offset:54272
	ds_read_b128 v[212:215], v145 offset:55296
	ds_read_b128 v[216:219], v145 offset:56320
	global_load_lds_dwordx4 v[186:187], off
	s_add_i32 m0, s44, 0x2000
	s_add_u32 s40, s40, 0xb0080
	v_lshl_add_u64 v[186:187], v[200:201], 0, s[8:9]
	s_addc_u32 s41, s41, 0
	s_add_i32 s44, s85, s56
	global_load_lds_dwordx4 v[186:187], off
	v_lshl_add_u64 v[186:187], s[40:41], 0, v[130:131]
	s_mov_b32 m0, s44
	s_nop 0
	global_load_lds_dwordx4 v[186:187], off
	v_lshl_add_u64 v[186:187], s[40:41], 0, v[134:135]
	s_add_i32 m0, s44, 0x2000
	s_nop 0
	global_load_lds_dwordx4 v[186:187], off
	v_lshl_add_u64 v[186:187], v[220:221], 0, s[8:9]
	s_mov_b32 m0, s62
	s_nop 0
	global_load_lds_dwordx4 v[186:187], off
	v_lshl_add_u64 v[186:187], v[222:223], 0, s[8:9]
	s_mov_b32 m0, s63
	s_nop 0
	global_load_lds_dwordx4 v[186:187], off
	s_waitcnt vmcnt(8)
	s_waitcnt lgkmcnt(0)
	s_barrier
	s_setprio 1
	s_waitcnt lgkmcnt(0)
	v_mfma_f32_16x16x32_bf16 v[60:63], v[146:149], v[178:181], v[60:63]
	v_mfma_f32_16x16x32_bf16 v[56:59], v[154:157], v[178:181], v[56:59]
	v_mfma_f32_16x16x32_bf16 v[44:47], v[146:149], v[192:195], v[44:47]
	v_mfma_f32_16x16x32_bf16 v[40:43], v[154:157], v[192:195], v[40:43]
	v_mfma_f32_16x16x32_bf16 v[28:31], v[146:149], v[204:207], v[28:31]
	v_mfma_f32_16x16x32_bf16 v[24:27], v[154:157], v[204:207], v[24:27]
	v_mfma_f32_16x16x32_bf16 v[12:15], v[146:149], v[212:215], v[12:15]
	v_mfma_f32_16x16x32_bf16 v[8:11], v[154:157], v[212:215], v[8:11]
	v_mfma_f32_16x16x32_bf16 v[60:63], v[150:153], v[182:185], v[60:63]
	v_mfma_f32_16x16x32_bf16 v[56:59], v[158:161], v[182:185], v[56:59]
	v_mfma_f32_16x16x32_bf16 v[44:47], v[150:153], v[196:199], v[44:47]
	v_mfma_f32_16x16x32_bf16 v[40:43], v[158:161], v[196:199], v[40:43]
	v_mfma_f32_16x16x32_bf16 v[28:31], v[150:153], v[208:211], v[28:31]
	v_mfma_f32_16x16x32_bf16 v[24:27], v[158:161], v[208:211], v[24:27]
	v_mfma_f32_16x16x32_bf16 v[12:15], v[150:153], v[216:219], v[12:15]
	v_mfma_f32_16x16x32_bf16 v[8:11], v[158:161], v[216:219], v[8:11]
	v_mfma_f32_16x16x32_bf16 v[52:55], v[162:165], v[178:181], v[52:55]
	v_mfma_f32_16x16x32_bf16 v[48:51], v[170:173], v[178:181], v[48:51]
	v_mfma_f32_16x16x32_bf16 v[36:39], v[162:165], v[192:195], v[36:39]
	v_mfma_f32_16x16x32_bf16 v[32:35], v[170:173], v[192:195], v[32:35]
	v_mfma_f32_16x16x32_bf16 v[20:23], v[162:165], v[204:207], v[20:23]
	v_mfma_f32_16x16x32_bf16 v[16:19], v[170:173], v[204:207], v[16:19]
	v_mfma_f32_16x16x32_bf16 v[4:7], v[162:165], v[212:215], v[4:7]
	v_mfma_f32_16x16x32_bf16 v[0:3], v[170:173], v[212:215], v[0:3]
	v_mfma_f32_16x16x32_bf16 v[52:55], v[166:169], v[182:185], v[52:55]
	v_mfma_f32_16x16x32_bf16 v[48:51], v[174:177], v[182:185], v[48:51]
	v_mfma_f32_16x16x32_bf16 v[36:39], v[166:169], v[196:199], v[36:39]
	v_mfma_f32_16x16x32_bf16 v[32:35], v[174:177], v[196:199], v[32:35]
	v_mfma_f32_16x16x32_bf16 v[20:23], v[166:169], v[208:211], v[20:23]
	v_mfma_f32_16x16x32_bf16 v[16:19], v[174:177], v[208:211], v[16:19]
	v_mfma_f32_16x16x32_bf16 v[4:7], v[166:169], v[216:219], v[4:7]
	v_mfma_f32_16x16x32_bf16 v[0:3], v[174:177], v[216:219], v[0:3]
	s_setprio 0
	s_barrier
	s_add_i32 s89, s89, 2
	s_add_u32 s28, s28, 0x100
	s_addc_u32 s29, s29, 0
	s_cmp_gt_u32 s89, 41
	s_cbranch_scc0 .LBB0_374
	s_and_b64 vcc, exec, s[14:15]
	s_cbranch_vccz .LBB0_377
	s_barrier

; #define PG8_STAGE(bufoff, gbase, voff) do { _Pragma("unroll") for (int _i = 0; _i < 2; ++_i) \
;         __builtin_amdgcn_global_load_lds((const unsigned*)((const char*)(gbase) + (voff)[_i]), (LAS unsigned*)(lds + (bufoff) + ldsw + _i * 8192), 16, 0, 0); } while (0)
; #define PG8_LDA(dst, b, h) do { _Pragma("unroll") for (int m = 0; m < 4; ++m) _Pragma("unroll") for (int k = 0; k < 2; ++k) dst[m][k] = *(const LAS bf16x8*)(lds + PG8_SA(b, h) + aoff + m * 2048 + k * 1024); } while (0)
; #define PG8_LDB(dst, b, h) do { _Pragma("unroll") for (int n = 0; n < 2; ++n) _Pragma("unroll") for (int k = 0; k < 2; ++k) dst[n][k] = *(const LAS bf16x8*)(lds + PG8_SB(b, h) + boff + n * 2048 + k * 1024); } while (0)
; #define PG8_MMA(ai, bj, At, Bt) do { __builtin_amdgcn_s_setprio(1); _Pragma("unroll") for (int m = 0; m < 4; ++m) _Pragma("unroll") for (int n = 0; n < 2; ++n) _Pragma("unroll") for (int k = 0; k < 2; ++k) \
;         acc[ai][bj][m][n] = __builtin_amdgcn_mfma_f32_16x16x32_bf16(Bt[n][k], At[m][k], acc[ai][bj][m][n], 0, 0, 0); __builtin_amdgcn_s_setprio(0); } while (0)
; #define PG8_WAIT_V(n) asm volatile("s_waitcnt vmcnt(" #n ")" ::: "memory")
; #define PG8_WAIT_L(n) asm volatile("s_waitcnt lgkmcnt(" #n ")" ::: "memory")
; #define PG8_BAR __builtin_amdgcn_s_barrier()
; #define PG8_SCHED __builtin_amdgcn_sched_barrier(0)
; template <class Epi>
; __device__ __forceinline__ void gemm_phase(LAS unsigned char* lds, const Gemm g, const Sched& S, const Epi& E) {
;     ...
;             const bool last = (t == nt - 2);
;             const char* a1 = cA + (size_t)(t + 1) * kstep;
;             const char* a2 = last ? nA : cA + (size_t)(t + 2) * kstep; const char* b2 = last ? nB : cB + (size_t)(t + 2) * kstep;
;             const char* a3 = a2 + kstep; const char* b3 = b2 + kstep;
;             PG8_LDB(B0, 0, 0); PG8_LDB(B1, 0, 1); PG8_SCHED; PG8_LDA(At, 0, 0); PG8_STAGE(PG8_SA(1, 1), a1 + hstepA, voffA);
;             PG8_WAIT_V(8); PG8_WAIT_L(0); PG8_BAR; PG8_MMA(0, 0, At, B0); PG8_MMA(0, 1, At, B1); PG8_BAR; PG8_SCHED;
;             PG8_LDA(At, 0, 1); PG8_STAGE(PG8_SB(0, 0), b2, voffB); PG8_STAGE(PG8_SB(0, 1), b2 + hstepB, voffB); PG8_STAGE(PG8_SA(0, 0), a2, voffA);
;             PG8_WAIT_V(8); PG8_WAIT_L(0); PG8_BAR; PG8_MMA(1, 0, At, B0); PG8_MMA(1, 1, At, B1); PG8_BAR; PG8_SCHED;
.LBB0_520:
	ds_read_b128 v[128:131], v160
	ds_read_b128 v[132:135], v160 offset:1024
	ds_read_b128 v[152:155], v160 offset:2048
	ds_read_b128 v[164:167], v160 offset:3072
	ds_read_b128 v[168:171], v161
	ds_read_b128 v[172:175], v161 offset:1024
	ds_read_b128 v[176:179], v161 offset:2048
	ds_read_b128 v[180:183], v161 offset:3072
	s_add_u32 s4, s2, 0xfffc0080
	s_addc_u32 s5, s3, -1
	s_cmp_eq_u32 s57, 12
	s_cselect_b32 s53, s0, s5
	s_cselect_b32 s52, s27, s4
	s_cselect_b32 s5, s25, s56
	s_cselect_b32 s4, s54, s55
	v_lshl_add_u64 v[200:201], s[2:3], 0, v[146:147]
	s_add_i32 m0, s10, 0xc000
	ds_read_b128 v[184:187], v162
	ds_read_b128 v[188:191], v162 offset:1024
	ds_read_b128 v[192:195], v162 offset:2048
	ds_read_b128 v[196:199], v162 offset:3072
	ds_read_b128 v[204:207], v162 offset:4096
	ds_read_b128 v[208:211], v162 offset:5120
	ds_read_b128 v[212:215], v162 offset:6144
	ds_read_b128 v[216:219], v162 offset:7168
	global_load_lds_dwordx4 v[200:201], off
	v_lshl_add_u64 v[200:201], s[2:3], 0, v[148:149]
	s_add_i32 m0, s10, 0xe000
	s_nop 0
	global_load_lds_dwordx4 v[200:201], off
	s_waitcnt vmcnt(8)
	s_waitcnt lgkmcnt(0)
	s_barrier
	s_setprio 1
	s_waitcnt lgkmcnt(0)
	v_mfma_f32_16x16x32_bf16 v[124:127], v[128:131], v[184:187], v[124:127]
	v_mfma_f32_16x16x32_bf16 v[116:119], v[152:155], v[184:187], v[116:119]
	v_mfma_f32_16x16x32_bf16 v[108:111], v[128:131], v[192:195], v[108:111]
	v_mfma_f32_16x16x32_bf16 v[100:103], v[152:155], v[192:195], v[100:103]
	v_mfma_f32_16x16x32_bf16 v[92:95], v[128:131], v[204:207], v[92:95]
	v_mfma_f32_16x16x32_bf16 v[84:87], v[152:155], v[204:207], v[84:87]
	v_mfma_f32_16x16x32_bf16 v[76:79], v[128:131], v[212:215], v[76:79]
	v_mfma_f32_16x16x32_bf16 v[68:71], v[152:155], v[212:215], v[68:71]
	v_mfma_f32_16x16x32_bf16 v[124:127], v[132:135], v[188:191], v[124:127]
	v_mfma_f32_16x16x32_bf16 v[116:119], v[164:167], v[188:191], v[116:119]
	v_mfma_f32_16x16x32_bf16 v[108:111], v[132:135], v[196:199], v[108:111]
	v_mfma_f32_16x16x32_bf16 v[100:103], v[164:167], v[196:199], v[100:103]
	v_mfma_f32_16x16x32_bf16 v[92:95], v[132:135], v[208:211], v[92:95]
	v_mfma_f32_16x16x32_bf16 v[84:87], v[164:167], v[208:211], v[84:87]
	v_mfma_f32_16x16x32_bf16 v[76:79], v[132:135], v[216:219], v[76:79]
	v_mfma_f32_16x16x32_bf16 v[68:71], v[164:167], v[216:219], v[68:71]
	v_mfma_f32_16x16x32_bf16 v[120:123], v[168:171], v[184:187], v[120:123]
	v_mfma_f32_16x16x32_bf16 v[112:115], v[176:179], v[184:187], v[112:115]
	v_mfma_f32_16x16x32_bf16 v[104:107], v[168:171], v[192:195], v[104:107]
	v_mfma_f32_16x16x32_bf16 v[96:99], v[176:179], v[192:195], v[96:99]
	v_mfma_f32_16x16x32_bf16 v[88:91], v[168:171], v[204:207], v[88:91]
	v_mfma_f32_16x16x32_bf16 v[80:83], v[176:179], v[204:207], v[80:83]
	v_mfma_f32_16x16x32_bf16 v[72:75], v[168:171], v[212:215], v[72:75]
	v_mfma_f32_16x16x32_bf16 v[64:67], v[176:179], v[212:215], v[64:67]
	v_mfma_f32_16x16x32_bf16 v[120:123], v[172:175], v[188:191], v[120:123]
	v_mfma_f32_16x16x32_bf16 v[112:115], v[180:183], v[188:191], v[112:115]
	v_mfma_f32_16x16x32_bf16 v[104:107], v[172:175], v[196:199], v[104:107]
	v_mfma_f32_16x16x32_bf16 v[96:99], v[180:183], v[196:199], v[96:99]
	v_mfma_f32_16x16x32_bf16 v[88:91], v[172:175], v[208:211], v[88:91]
	v_mfma_f32_16x16x32_bf16 v[80:83], v[180:183], v[208:211], v[80:83]
	v_mfma_f32_16x16x32_bf16 v[72:75], v[172:175], v[216:219], v[72:75]
	v_mfma_f32_16x16x32_bf16 v[64:67], v[180:183], v[216:219], v[64:67]
	s_setprio 0
	s_barrier
	s_add_i32 s58, s89, s86
	v_lshl_add_u64 v[200:201], s[4:5], 0, v[138:139]
	s_mov_b32 m0, s58
	ds_read_b128 v[184:187], v162 offset:16384
	ds_read_b128 v[188:191], v162 offset:17408
	ds_read_b128 v[192:195], v162 offset:18432
	ds_read_b128 v[196:199], v162 offset:19456
	ds_read_b128 v[204:207], v162 offset:20480
	ds_read_b128 v[208:211], v162 offset:21504
	ds_read_b128 v[212:215], v162 offset:22528
	ds_read_b128 v[216:219], v162 offset:23552
	global_load_lds_dwordx4 v[200:201], off
	s_add_i32 m0, s58, 0x2000
	s_add_u32 s58, s4, 0x40000
	v_lshl_add_u64 v[220:221], s[4:5], 0, v[142:143]
	s_addc_u32 s59, s5, 0
	s_add_i32 s60, s90, s86
	global_load_lds_dwordx4 v[220:221], off
	v_lshl_add_u64 v[222:223], s[58:59], 0, v[138:139]
	s_mov_b32 m0, s60
	v_lshl_add_u64 v[224:225], s[52:53], 0, v[140:141]
	global_load_lds_dwordx4 v[222:223], off
	v_lshl_add_u64 v[222:223], s[58:59], 0, v[142:143]
	s_add_i32 m0, s60, 0x2000
	s_nop 0
	global_load_lds_dwordx4 v[222:223], off
	v_lshl_add_u64 v[222:223], s[52:53], 0, v[136:137]
	s_mov_b32 m0, s10
	s_nop 0
	global_load_lds_dwordx4 v[222:223], off
	s_mov_b32 m0, s11
	s_nop 0
	global_load_lds_dwordx4 v[224:225], off
	s_waitcnt vmcnt(8)
	s_waitcnt lgkmcnt(0)
	s_barrier
; #define PG8_STAGE(bufoff, gbase, voff) do { _Pragma("unroll") for (int _i = 0; _i < 2; ++_i) \
;         __builtin_amdgcn_global_load_lds((const unsigned*)((const char*)(gbase) + (voff)[_i]), (LAS unsigned*)(lds + (bufoff) + ldsw + _i * 8192), 16, 0, 0); } while (0)
; #define PG8_LDA(dst, b, h) do { _Pragma("unroll") for (int m = 0; m < 4; ++m) _Pragma("unroll") for (int k = 0; k < 2; ++k) dst[m][k] = *(const LAS bf16x8*)(lds + PG8_SA(b, h) + aoff + m * 2048 + k * 1024); } while (0)
; #define PG8_LDB(dst, b, h) do { _Pragma("unroll") for (int n = 0; n < 2; ++n) _Pragma("unroll") for (int k = 0; k < 2; ++k) dst[n][k] = *(const LAS bf16x8*)(lds + PG8_SB(b, h) + boff + n * 2048 + k * 1024); } while (0)
; #define PG8_MMA(ai, bj, At, Bt) do { __builtin_amdgcn_s_setprio(1); _Pragma("unroll") for (int m = 0; m < 4; ++m) _Pragma("unroll") for (int n = 0; n < 2; ++n) _Pragma("unroll") for (int k = 0; k < 2; ++k) \
;         acc[ai][bj][m][n] = __builtin_amdgcn_mfma_f32_16x16x32_bf16(Bt[n][k], At[m][k], acc[ai][bj][m][n], 0, 0, 0); __builtin_amdgcn_s_setprio(0); } while (0)
; #define PG8_WAIT_V(n) asm volatile("s_waitcnt vmcnt(" #n ")" ::: "memory")
; #define PG8_WAIT_L(n) asm volatile("s_waitcnt lgkmcnt(" #n ")" ::: "memory")
; #define PG8_BAR __builtin_amdgcn_s_barrier()
; #define PG8_SCHED __builtin_amdgcn_sched_barrier(0)
; template <class Epi>
; __device__ __forceinline__ void gemm_phase(LAS unsigned char* lds, const Gemm g, const Sched& S, const Epi& E) {
;     ...
;             PG8_WAIT_V(8); PG8_WAIT_L(0); PG8_BAR; PG8_MMA(1, 0, At, B0); PG8_MMA(1, 1, At, B1); PG8_BAR; PG8_SCHED;
;             PG8_LDB(B0, 1, 0); PG8_LDB(B1, 1, 1); PG8_SCHED; PG8_LDA(At, 1, 0); PG8_STAGE(PG8_SA(0, 1), a2 + hstepA, voffA);
;             PG8_WAIT_V(8); PG8_WAIT_L(0); PG8_BAR; PG8_MMA(0, 0, At, B0); PG8_MMA(0, 1, At, B1); PG8_BAR; PG8_SCHED;
	s_setprio 1
	s_waitcnt lgkmcnt(0)
	v_mfma_f32_16x16x32_bf16 v[60:63], v[128:131], v[184:187], v[60:63]
	v_mfma_f32_16x16x32_bf16 v[52:55], v[152:155], v[184:187], v[52:55]
	v_mfma_f32_16x16x32_bf16 v[44:47], v[128:131], v[192:195], v[44:47]
	v_mfma_f32_16x16x32_bf16 v[36:39], v[152:155], v[192:195], v[36:39]
	v_mfma_f32_16x16x32_bf16 v[28:31], v[128:131], v[204:207], v[28:31]
	v_mfma_f32_16x16x32_bf16 v[20:23], v[152:155], v[204:207], v[20:23]
	v_mfma_f32_16x16x32_bf16 v[12:15], v[128:131], v[212:215], v[12:15]
	v_mfma_f32_16x16x32_bf16 v[4:7], v[152:155], v[212:215], v[4:7]
	v_mfma_f32_16x16x32_bf16 v[60:63], v[132:135], v[188:191], v[60:63]
	v_mfma_f32_16x16x32_bf16 v[52:55], v[164:167], v[188:191], v[52:55]
	v_mfma_f32_16x16x32_bf16 v[44:47], v[132:135], v[196:199], v[44:47]
	v_mfma_f32_16x16x32_bf16 v[36:39], v[164:167], v[196:199], v[36:39]
	v_mfma_f32_16x16x32_bf16 v[28:31], v[132:135], v[208:211], v[28:31]
	v_mfma_f32_16x16x32_bf16 v[20:23], v[164:167], v[208:211], v[20:23]
	v_mfma_f32_16x16x32_bf16 v[12:15], v[132:135], v[216:219], v[12:15]
	v_mfma_f32_16x16x32_bf16 v[4:7], v[164:167], v[216:219], v[4:7]
	v_mfma_f32_16x16x32_bf16 v[56:59], v[168:171], v[184:187], v[56:59]
	v_mfma_f32_16x16x32_bf16 v[48:51], v[176:179], v[184:187], v[48:51]
	v_mfma_f32_16x16x32_bf16 v[40:43], v[168:171], v[192:195], v[40:43]
	v_mfma_f32_16x16x32_bf16 v[32:35], v[176:179], v[192:195], v[32:35]
	v_mfma_f32_16x16x32_bf16 v[24:27], v[168:171], v[204:207], v[24:27]
	v_mfma_f32_16x16x32_bf16 v[16:19], v[176:179], v[204:207], v[16:19]
	v_mfma_f32_16x16x32_bf16 v[8:11], v[168:171], v[212:215], v[8:11]
	v_mfma_f32_16x16x32_bf16 v[0:3], v[176:179], v[212:215], v[0:3]
	v_mfma_f32_16x16x32_bf16 v[56:59], v[172:175], v[188:191], v[56:59]
	v_mfma_f32_16x16x32_bf16 v[48:51], v[180:183], v[188:191], v[48:51]
	v_mfma_f32_16x16x32_bf16 v[40:43], v[172:175], v[196:199], v[40:43]
	v_mfma_f32_16x16x32_bf16 v[32:35], v[180:183], v[196:199], v[32:35]
	v_mfma_f32_16x16x32_bf16 v[24:27], v[172:175], v[208:211], v[24:27]
	v_mfma_f32_16x16x32_bf16 v[16:19], v[180:183], v[208:211], v[16:19]
	v_mfma_f32_16x16x32_bf16 v[8:11], v[172:175], v[216:219], v[8:11]
	v_mfma_f32_16x16x32_bf16 v[0:3], v[180:183], v[216:219], v[0:3]
	s_setprio 0
	s_barrier
	s_add_i32 s58, 0, 0x18000
	v_add_u32_e32 v144, s58, v158
	s_add_i32 s59, 0, 0x1c000
	ds_read_b128 v[128:131], v144
	ds_read_b128 v[132:135], v144 offset:1024
	ds_read_b128 v[152:155], v144 offset:2048
	ds_read_b128 v[164:167], v144 offset:3072
	v_add_u32_e32 v144, s59, v158
	ds_read_b128 v[168:171], v144
	ds_read_b128 v[172:175], v144 offset:1024
	ds_read_b128 v[176:179], v144 offset:2048
	ds_read_b128 v[180:183], v144 offset:3072
	s_add_u32 s52, s52, 0x40000
	s_addc_u32 s53, s53, 0
	s_mov_b32 m0, s45
	v_lshl_add_u64 v[226:227], s[52:53], 0, v[136:137]
	ds_read_b128 v[184:187], v162 offset:32768
	ds_read_b128 v[188:191], v162 offset:33792
	ds_read_b128 v[192:195], v162 offset:34816
	ds_read_b128 v[196:199], v162 offset:35840
	ds_read_b128 v[204:207], v162 offset:36864
	ds_read_b128 v[208:211], v162 offset:37888
	ds_read_b128 v[212:215], v162 offset:38912
	ds_read_b128 v[216:219], v162 offset:39936
	global_load_lds_dwordx4 v[226:227], off
	v_lshl_add_u64 v[226:227], s[52:53], 0, v[140:141]
	s_mov_b32 m0, s47
	s_nop 0
	global_load_lds_dwordx4 v[226:227], off
	s_waitcnt vmcnt(8)
	s_waitcnt lgkmcnt(0)
	s_barrier
	s_setprio 1
	s_waitcnt lgkmcnt(0)
	v_mfma_f32_16x16x32_bf16 v[124:127], v[128:131], v[184:187], v[124:127]
	v_mfma_f32_16x16x32_bf16 v[116:119], v[152:155], v[184:187], v[116:119]
	v_mfma_f32_16x16x32_bf16 v[108:111], v[128:131], v[192:195], v[108:111]
	v_mfma_f32_16x16x32_bf16 v[100:103], v[152:155], v[192:195], v[100:103]
	v_mfma_f32_16x16x32_bf16 v[92:95], v[128:131], v[204:207], v[92:95]
	v_mfma_f32_16x16x32_bf16 v[84:87], v[152:155], v[204:207], v[84:87]
	v_mfma_f32_16x16x32_bf16 v[76:79], v[128:131], v[212:215], v[76:79]
	v_mfma_f32_16x16x32_bf16 v[68:71], v[152:155], v[212:215], v[68:71]
	v_mfma_f32_16x16x32_bf16 v[124:127], v[132:135], v[188:191], v[124:127]
	v_mfma_f32_16x16x32_bf16 v[116:119], v[164:167], v[188:191], v[116:119]
	v_mfma_f32_16x16x32_bf16 v[108:111], v[132:135], v[196:199], v[108:111]
	v_mfma_f32_16x16x32_bf16 v[100:103], v[164:167], v[196:199], v[100:103]
	v_mfma_f32_16x16x32_bf16 v[92:95], v[132:135], v[208:211], v[92:95]
	v_mfma_f32_16x16x32_bf16 v[84:87], v[164:167], v[208:211], v[84:87]
	v_mfma_f32_16x16x32_bf16 v[76:79], v[132:135], v[216:219], v[76:79]
	v_mfma_f32_16x16x32_bf16 v[68:71], v[164:167], v[216:219], v[68:71]
	v_mfma_f32_16x16x32_bf16 v[120:123], v[168:171], v[184:187], v[120:123]
	v_mfma_f32_16x16x32_bf16 v[112:115], v[176:179], v[184:187], v[112:115]
	v_mfma_f32_16x16x32_bf16 v[104:107], v[168:171], v[192:195], v[104:107]
	v_mfma_f32_16x16x32_bf16 v[96:99], v[176:179], v[192:195], v[96:99]
	v_mfma_f32_16x16x32_bf16 v[88:91], v[168:171], v[204:207], v[88:91]
	v_mfma_f32_16x16x32_bf16 v[80:83], v[176:179], v[204:207], v[80:83]
	v_mfma_f32_16x16x32_bf16 v[72:75], v[168:171], v[212:215], v[72:75]
	v_mfma_f32_16x16x32_bf16 v[64:67], v[176:179], v[212:215], v[64:67]
	v_mfma_f32_16x16x32_bf16 v[120:123], v[172:175], v[188:191], v[120:123]
	v_mfma_f32_16x16x32_bf16 v[112:115], v[180:183], v[188:191], v[112:115]
	v_mfma_f32_16x16x32_bf16 v[104:107], v[172:175], v[196:199], v[104:107]
	v_mfma_f32_16x16x32_bf16 v[96:99], v[180:183], v[196:199], v[96:99]
	v_mfma_f32_16x16x32_bf16 v[88:91], v[172:175], v[208:211], v[88:91]
	v_mfma_f32_16x16x32_bf16 v[80:83], v[180:183], v[208:211], v[80:83]
	v_mfma_f32_16x16x32_bf16 v[72:75], v[172:175], v[216:219], v[72:75]
	v_mfma_f32_16x16x32_bf16 v[64:67], v[180:183], v[216:219], v[64:67]
	s_setprio 0
	s_barrier
; #define PG8_STAGE(bufoff, gbase, voff) do { _Pragma("unroll") for (int _i = 0; _i < 2; ++_i) \
;         __builtin_amdgcn_global_load_lds((const unsigned*)((const char*)(gbase) + (voff)[_i]), (LAS unsigned*)(lds + (bufoff) + ldsw + _i * 8192), 16, 0, 0); } while (0)
; #define PG8_LDA(dst, b, h) do { _Pragma("unroll") for (int m = 0; m < 4; ++m) _Pragma("unroll") for (int k = 0; k < 2; ++k) dst[m][k] = *(const LAS bf16x8*)(lds + PG8_SA(b, h) + aoff + m * 2048 + k * 1024); } while (0)
; #define PG8_MMA(ai, bj, At, Bt) do { __builtin_amdgcn_s_setprio(1); _Pragma("unroll") for (int m = 0; m < 4; ++m) _Pragma("unroll") for (int n = 0; n < 2; ++n) _Pragma("unroll") for (int k = 0; k < 2; ++k) \
;         acc[ai][bj][m][n] = __builtin_amdgcn_mfma_f32_16x16x32_bf16(Bt[n][k], At[m][k], acc[ai][bj][m][n], 0, 0, 0); __builtin_amdgcn_s_setprio(0); } while (0)
; #define PG8_WAIT_V(n) asm volatile("s_waitcnt vmcnt(" #n ")" ::: "memory")
; #define PG8_WAIT_L(n) asm volatile("s_waitcnt lgkmcnt(" #n ")" ::: "memory")
; #define PG8_BAR __builtin_amdgcn_s_barrier()
; #define PG8_SCHED __builtin_amdgcn_sched_barrier(0)
; template <class Epi>
; __device__ __forceinline__ void gemm_phase(LAS unsigned char* lds, const Gemm g, const Sched& S, const Epi& E) {
;     ...
;             PG8_LDA(At, 1, 1); PG8_STAGE(PG8_SB(1, 0), b3, voffB); PG8_STAGE(PG8_SB(1, 1), b3 + hstepB, voffB); PG8_STAGE(PG8_SA(1, 0), a3, voffA);
;             PG8_WAIT_V(8); PG8_WAIT_L(0); PG8_BAR; PG8_MMA(1, 0, At, B0); PG8_MMA(1, 1, At, B1); PG8_BAR; PG8_SCHED;
;         }
;     __device__ __forceinline__ void operator()(AccRef acc, const Unit& u, int wr, int wc, int fr, int fq) const {
;     ...
;         if (pn >= 17 && pn < 25) {
	s_add_i32 s52, s58, s86
	v_lshl_add_u64 v[200:201], v[200:201], 0, s[14:15]
	s_mov_b32 m0, s52
	ds_read_b128 v[184:187], v162 offset:49152
	ds_read_b128 v[188:191], v162 offset:50176
	ds_read_b128 v[192:195], v162 offset:51200
	ds_read_b128 v[196:199], v162 offset:52224
	ds_read_b128 v[204:207], v162 offset:53248
	ds_read_b128 v[208:211], v162 offset:54272
	ds_read_b128 v[212:215], v162 offset:55296
	ds_read_b128 v[216:219], v162 offset:56320
	global_load_lds_dwordx4 v[200:201], off
	s_add_i32 m0, s52, 0x2000
	s_add_u32 s4, s4, 0x40080
	v_lshl_add_u64 v[200:201], v[220:221], 0, s[14:15]
	s_addc_u32 s5, s5, 0
	s_add_i32 s52, s59, s86
	global_load_lds_dwordx4 v[200:201], off
	v_lshl_add_u64 v[200:201], s[4:5], 0, v[138:139]
	s_mov_b32 m0, s52
	s_nop 0
	global_load_lds_dwordx4 v[200:201], off
	v_lshl_add_u64 v[200:201], s[4:5], 0, v[142:143]
	s_add_i32 m0, s52, 0x2000
	s_nop 0
	global_load_lds_dwordx4 v[200:201], off
	v_lshl_add_u64 v[200:201], v[222:223], 0, s[14:15]
	s_mov_b32 m0, s87
	s_nop 0
	global_load_lds_dwordx4 v[200:201], off
	v_lshl_add_u64 v[200:201], v[224:225], 0, s[14:15]
	s_mov_b32 m0, s88
	s_nop 0
	global_load_lds_dwordx4 v[200:201], off
	s_waitcnt vmcnt(8)
	s_waitcnt lgkmcnt(0)
	s_barrier
	s_setprio 1
	s_waitcnt lgkmcnt(0)
	v_mfma_f32_16x16x32_bf16 v[60:63], v[128:131], v[184:187], v[60:63]
	v_mfma_f32_16x16x32_bf16 v[52:55], v[152:155], v[184:187], v[52:55]
	v_mfma_f32_16x16x32_bf16 v[44:47], v[128:131], v[192:195], v[44:47]
	v_mfma_f32_16x16x32_bf16 v[36:39], v[152:155], v[192:195], v[36:39]
	v_mfma_f32_16x16x32_bf16 v[28:31], v[128:131], v[204:207], v[28:31]
	v_mfma_f32_16x16x32_bf16 v[20:23], v[152:155], v[204:207], v[20:23]
	v_mfma_f32_16x16x32_bf16 v[12:15], v[128:131], v[212:215], v[12:15]
	v_mfma_f32_16x16x32_bf16 v[4:7], v[152:155], v[212:215], v[4:7]
	v_mfma_f32_16x16x32_bf16 v[60:63], v[132:135], v[188:191], v[60:63]
	v_mfma_f32_16x16x32_bf16 v[52:55], v[164:167], v[188:191], v[52:55]
	v_mfma_f32_16x16x32_bf16 v[44:47], v[132:135], v[196:199], v[44:47]
	v_mfma_f32_16x16x32_bf16 v[36:39], v[164:167], v[196:199], v[36:39]
	v_mfma_f32_16x16x32_bf16 v[28:31], v[132:135], v[208:211], v[28:31]
	v_mfma_f32_16x16x32_bf16 v[20:23], v[164:167], v[208:211], v[20:23]
	v_mfma_f32_16x16x32_bf16 v[12:15], v[132:135], v[216:219], v[12:15]
	v_mfma_f32_16x16x32_bf16 v[4:7], v[164:167], v[216:219], v[4:7]
	v_mfma_f32_16x16x32_bf16 v[56:59], v[168:171], v[184:187], v[56:59]
	v_mfma_f32_16x16x32_bf16 v[48:51], v[176:179], v[184:187], v[48:51]
	v_mfma_f32_16x16x32_bf16 v[40:43], v[168:171], v[192:195], v[40:43]
	v_mfma_f32_16x16x32_bf16 v[32:35], v[176:179], v[192:195], v[32:35]
	v_mfma_f32_16x16x32_bf16 v[24:27], v[168:171], v[204:207], v[24:27]
	v_mfma_f32_16x16x32_bf16 v[16:19], v[176:179], v[204:207], v[16:19]
	v_mfma_f32_16x16x32_bf16 v[8:11], v[168:171], v[212:215], v[8:11]
	v_mfma_f32_16x16x32_bf16 v[0:3], v[176:179], v[212:215], v[0:3]
	v_mfma_f32_16x16x32_bf16 v[56:59], v[172:175], v[188:191], v[56:59]
	v_mfma_f32_16x16x32_bf16 v[48:51], v[180:183], v[188:191], v[48:51]
	v_mfma_f32_16x16x32_bf16 v[40:43], v[172:175], v[196:199], v[40:43]
	v_mfma_f32_16x16x32_bf16 v[32:35], v[180:183], v[196:199], v[32:35]
	v_mfma_f32_16x16x32_bf16 v[24:27], v[172:175], v[208:211], v[24:27]
	v_mfma_f32_16x16x32_bf16 v[16:19], v[180:183], v[208:211], v[16:19]
	v_mfma_f32_16x16x32_bf16 v[8:11], v[172:175], v[216:219], v[8:11]
	v_mfma_f32_16x16x32_bf16 v[0:3], v[180:183], v[216:219], v[0:3]
	s_setprio 0
	s_barrier
	s_add_i32 s57, s57, 2
	s_add_u32 s2, s2, 0x100
	s_addc_u32 s3, s3, 0
	s_add_u32 s55, s55, 0x100
	s_addc_u32 s56, s56, 0
	s_cmp_gt_u32 s57, 13
	s_cbranch_scc0 .LBB0_520
	s_and_b64 vcc, exec, s[20:21]
	s_cbranch_vccnz .LBB0_525
	s_sub_i32 s0, s44, 17
	s_cmp_gt_u32 s0, 7
	s_mov_b64 s[2:3], -1
	s_cbranch_scc1 .LBB0_526

; #define PG8_STAGE(bufoff, gbase, voff) do { _Pragma("unroll") for (int _i = 0; _i < 2; ++_i) \
;         __builtin_amdgcn_global_load_lds((const unsigned*)((const char*)(gbase) + (voff)[_i]), (LAS unsigned*)(lds + (bufoff) + ldsw + _i * 8192), 16, 0, 0); } while (0)
; #define PG8_LDA(dst, b, h) do { _Pragma("unroll") for (int m = 0; m < 4; ++m) _Pragma("unroll") for (int k = 0; k < 2; ++k) dst[m][k] = *(const LAS bf16x8*)(lds + PG8_SA(b, h) + aoff + m * 2048 + k * 1024); } while (0)
; #define PG8_LDB(dst, b, h) do { _Pragma("unroll") for (int n = 0; n < 2; ++n) _Pragma("unroll") for (int k = 0; k < 2; ++k) dst[n][k] = *(const LAS bf16x8*)(lds + PG8_SB(b, h) + boff + n * 2048 + k * 1024); } while (0)
; #define PG8_MMA(ai, bj, At, Bt) do { __builtin_amdgcn_s_setprio(1); _Pragma("unroll") for (int m = 0; m < 4; ++m) _Pragma("unroll") for (int n = 0; n < 2; ++n) _Pragma("unroll") for (int k = 0; k < 2; ++k) \
;         acc[ai][bj][m][n] = __builtin_amdgcn_mfma_f32_16x16x32_bf16(Bt[n][k], At[m][k], acc[ai][bj][m][n], 0, 0, 0); __builtin_amdgcn_s_setprio(0); } while (0)
; #define PG8_WAIT_V(n) asm volatile("s_waitcnt vmcnt(" #n ")" ::: "memory")
; template <class Epi>
; __device__ __forceinline__ void gemm_phase(LAS unsigned char* lds, const Gemm g, const Sched& S, const Epi& E) {
;     ...
;         const char* nA = has_next ? (const char*)g.A + (size_t)S.aoff(nxt) * 2 : cA; const char* nB = has_next ? (const char*)g.Bt + (size_t)S.boff(nxt) * 2 : cB;
;         _Pragma("nounroll")
;         for (int t = 0; t < nt; t += 2) {
;             const bool last = (t == nt - 2);
;             const char* a1 = cA + (size_t)(t + 1) * kstep;
;             const char* a2 = last ? nA : cA + (size_t)(t + 2) * kstep; const char* b2 = last ? nB : cB + (size_t)(t + 2) * kstep;
;             const char* a3 = a2 + kstep; const char* b3 = b2 + kstep;
;             PG8_LDB(B0, 0, 0); PG8_LDB(B1, 0, 1); PG8_SCHED; PG8_LDA(At, 0, 0); PG8_STAGE(PG8_SA(1, 1), a1 + hstepA, voffA);
;             PG8_WAIT_V(8); PG8_WAIT_L(0); PG8_BAR; PG8_MMA(0, 0, At, B0); PG8_MMA(0, 1, At, B1); PG8_BAR; PG8_SCHED;
;             PG8_LDA(At, 0, 1); PG8_STAGE(PG8_SB(0, 0), b2, voffB); PG8_STAGE(PG8_SB(0, 1), b2 + hstepB, voffB); PG8_STAGE(PG8_SA(0, 0), a2, voffA);
;             PG8_WAIT_V(8); PG8_WAIT_L(0); PG8_BAR; PG8_MMA(1, 0, At, B0); PG8_MMA(1, 1, At, B1); PG8_BAR; PG8_SCHED;
.LBB0_773:
	s_add_u32 s60, s46, s74
	s_addc_u32 s61, s47, s75
	s_add_u32 s62, s60, 0x100
	s_addc_u32 s63, s61, 0
	s_and_b64 s[58:59], s[56:57], exec
	s_cselect_b32 s77, s3, s63
	s_cselect_b32 s76, s5, s62
	s_add_u32 s58, s52, s74
	s_addc_u32 s59, s53, s75
	s_add_u32 s58, s58, 0x100
	s_addc_u32 s59, s59, 0
	s_and_b64 s[56:57], s[56:57], exec
	s_cselect_b32 s79, s25, s59
	s_cselect_b32 s78, s27, s58
	s_add_u32 s86, s60, 0x10080
	ds_read_b128 v[80:83], v162
	ds_read_b128 v[84:87], v162 offset:1024
	ds_read_b128 v[136:139], v162 offset:2048
	ds_read_b128 v[140:143], v162 offset:3072
	ds_read_b128 v[154:157], v163
	ds_read_b128 v[166:169], v163 offset:1024
	ds_read_b128 v[170:173], v163 offset:2048
	ds_read_b128 v[174:177], v163 offset:3072
	s_addc_u32 s87, s61, 0
	s_add_i32 s67, s96, s15
	s_add_i32 s64, s67, 0x2000
	s_add_u32 s82, s78, 0x10000
	s_addc_u32 s83, s79, 0
	s_add_i32 s66, s97, s15
	s_add_i32 s65, s66, 0x2000
	s_add_i32 s63, 0, 0x18000
	s_add_i32 s62, 0, 0x1c000
	s_add_u32 s74, s76, 0x10000
	s_addc_u32 s75, s77, 0
	s_add_i32 s61, s63, s15
	s_add_i32 s59, s61, 0x2000
	s_add_u32 s56, s78, 0x10080
	s_addc_u32 s57, s79, 0
	s_add_i32 s60, s62, s15
	s_add_i32 s58, s60, 0x2000
	s_mov_b32 m0, s88
	v_lshl_add_u64 v[212:213], s[86:87], 0, v[144:145]
	ds_read_b128 v[178:181], v164
	ds_read_b128 v[182:185], v164 offset:1024
	ds_read_b128 v[186:189], v164 offset:2048
	ds_read_b128 v[190:193], v164 offset:3072
	ds_read_b128 v[194:197], v164 offset:4096
	ds_read_b128 v[198:201], v164 offset:5120
	ds_read_b128 v[204:207], v164 offset:6144
	ds_read_b128 v[208:211], v164 offset:7168
	global_load_lds_dwordx4 v[212:213], off
	v_lshl_add_u64 v[212:213], s[86:87], 0, v[148:149]
	s_mov_b32 m0, s11
	s_nop 0
	global_load_lds_dwordx4 v[212:213], off
	s_waitcnt vmcnt(8)
	s_waitcnt lgkmcnt(0)
	s_barrier
	s_setprio 1
	s_waitcnt lgkmcnt(0)
	v_mfma_f32_16x16x32_bf16 v[132:135], v[80:83], v[178:181], v[132:135]
	v_mfma_f32_16x16x32_bf16 v[128:131], v[136:139], v[178:181], v[128:131]
	v_mfma_f32_16x16x32_bf16 v[124:127], v[80:83], v[186:189], v[124:127]
	v_mfma_f32_16x16x32_bf16 v[120:123], v[136:139], v[186:189], v[120:123]
	v_mfma_f32_16x16x32_bf16 v[116:119], v[80:83], v[194:197], v[116:119]
	v_mfma_f32_16x16x32_bf16 v[112:115], v[136:139], v[194:197], v[112:115]
	v_mfma_f32_16x16x32_bf16 v[108:111], v[80:83], v[204:207], v[108:111]
	v_mfma_f32_16x16x32_bf16 v[104:107], v[136:139], v[204:207], v[104:107]
	v_mfma_f32_16x16x32_bf16 v[132:135], v[84:87], v[182:185], v[132:135]
	v_mfma_f32_16x16x32_bf16 v[128:131], v[140:143], v[182:185], v[128:131]
	v_mfma_f32_16x16x32_bf16 v[124:127], v[84:87], v[190:193], v[124:127]
	v_mfma_f32_16x16x32_bf16 v[120:123], v[140:143], v[190:193], v[120:123]
	v_mfma_f32_16x16x32_bf16 v[116:119], v[84:87], v[198:201], v[116:119]
	v_mfma_f32_16x16x32_bf16 v[112:115], v[140:143], v[198:201], v[112:115]
	v_mfma_f32_16x16x32_bf16 v[108:111], v[84:87], v[208:211], v[108:111]
	v_mfma_f32_16x16x32_bf16 v[104:107], v[140:143], v[208:211], v[104:107]
	v_mfma_f32_16x16x32_bf16 v[60:63], v[154:157], v[178:181], v[60:63]
	v_mfma_f32_16x16x32_bf16 v[56:59], v[170:173], v[178:181], v[56:59]
	v_mfma_f32_16x16x32_bf16 v[52:55], v[154:157], v[186:189], v[52:55]
	v_mfma_f32_16x16x32_bf16 v[48:51], v[170:173], v[186:189], v[48:51]
	v_mfma_f32_16x16x32_bf16 v[44:47], v[154:157], v[194:197], v[44:47]
	v_mfma_f32_16x16x32_bf16 v[40:43], v[170:173], v[194:197], v[40:43]
	v_mfma_f32_16x16x32_bf16 v[36:39], v[154:157], v[204:207], v[36:39]
	v_mfma_f32_16x16x32_bf16 v[32:35], v[170:173], v[204:207], v[32:35]
	v_mfma_f32_16x16x32_bf16 v[60:63], v[166:169], v[182:185], v[60:63]
	v_mfma_f32_16x16x32_bf16 v[56:59], v[174:177], v[182:185], v[56:59]
	v_mfma_f32_16x16x32_bf16 v[52:55], v[166:169], v[190:193], v[52:55]
	v_mfma_f32_16x16x32_bf16 v[48:51], v[174:177], v[190:193], v[48:51]
	v_mfma_f32_16x16x32_bf16 v[44:47], v[166:169], v[198:201], v[44:47]
	v_mfma_f32_16x16x32_bf16 v[40:43], v[174:177], v[198:201], v[40:43]
	v_mfma_f32_16x16x32_bf16 v[36:39], v[166:169], v[208:211], v[36:39]
	v_mfma_f32_16x16x32_bf16 v[32:35], v[174:177], v[208:211], v[32:35]
	s_setprio 0
	s_barrier
	s_mov_b32 m0, s67
	v_lshl_add_u64 v[212:213], s[78:79], 0, v[146:147]
	ds_read_b128 v[178:181], v164 offset:16384
	ds_read_b128 v[182:185], v164 offset:17408
	ds_read_b128 v[186:189], v164 offset:18432
	ds_read_b128 v[190:193], v164 offset:19456
	ds_read_b128 v[194:197], v164 offset:20480
	ds_read_b128 v[198:201], v164 offset:21504
	ds_read_b128 v[204:207], v164 offset:22528
	ds_read_b128 v[208:211], v164 offset:23552
	global_load_lds_dwordx4 v[212:213], off
	v_lshl_add_u64 v[214:215], s[78:79], 0, v[150:151]
	s_mov_b32 m0, s64
	v_lshl_add_u64 v[216:217], s[82:83], 0, v[146:147]
	global_load_lds_dwordx4 v[214:215], off
	s_mov_b32 m0, s66
	v_lshl_add_u64 v[218:219], s[76:77], 0, v[148:149]
	global_load_lds_dwordx4 v[216:217], off
	v_lshl_add_u64 v[216:217], s[82:83], 0, v[150:151]
	s_mov_b32 m0, s65
	s_nop 0
	global_load_lds_dwordx4 v[216:217], off
	v_lshl_add_u64 v[216:217], s[76:77], 0, v[144:145]
	s_mov_b32 m0, s10
	s_nop 0
	global_load_lds_dwordx4 v[216:217], off
	s_mov_b32 m0, s89
	s_nop 0
	global_load_lds_dwordx4 v[218:219], off
	s_waitcnt vmcnt(8)
	s_waitcnt lgkmcnt(0)
	s_barrier
; #define PG8_STAGE(bufoff, gbase, voff) do { _Pragma("unroll") for (int _i = 0; _i < 2; ++_i) \
;         __builtin_amdgcn_global_load_lds((const unsigned*)((const char*)(gbase) + (voff)[_i]), (LAS unsigned*)(lds + (bufoff) + ldsw + _i * 8192), 16, 0, 0); } while (0)
; #define PG8_LDA(dst, b, h) do { _Pragma("unroll") for (int m = 0; m < 4; ++m) _Pragma("unroll") for (int k = 0; k < 2; ++k) dst[m][k] = *(const LAS bf16x8*)(lds + PG8_SA(b, h) + aoff + m * 2048 + k * 1024); } while (0)
; #define PG8_LDB(dst, b, h) do { _Pragma("unroll") for (int n = 0; n < 2; ++n) _Pragma("unroll") for (int k = 0; k < 2; ++k) dst[n][k] = *(const LAS bf16x8*)(lds + PG8_SB(b, h) + boff + n * 2048 + k * 1024); } while (0)
; #define PG8_MMA(ai, bj, At, Bt) do { __builtin_amdgcn_s_setprio(1); _Pragma("unroll") for (int m = 0; m < 4; ++m) _Pragma("unroll") for (int n = 0; n < 2; ++n) _Pragma("unroll") for (int k = 0; k < 2; ++k) \
;         acc[ai][bj][m][n] = __builtin_amdgcn_mfma_f32_16x16x32_bf16(Bt[n][k], At[m][k], acc[ai][bj][m][n], 0, 0, 0); __builtin_amdgcn_s_setprio(0); } while (0)
; #define PG8_WAIT_V(n) asm volatile("s_waitcnt vmcnt(" #n ")" ::: "memory")
; #define PG8_WAIT_L(n) asm volatile("s_waitcnt lgkmcnt(" #n ")" ::: "memory")
; #define PG8_BAR __builtin_amdgcn_s_barrier()
; #define PG8_SCHED __builtin_amdgcn_sched_barrier(0)
; template <class Epi>
; __device__ __forceinline__ void gemm_phase(LAS unsigned char* lds, const Gemm g, const Sched& S, const Epi& E) {
;     ...
;             PG8_WAIT_V(8); PG8_WAIT_L(0); PG8_BAR; PG8_MMA(1, 0, At, B0); PG8_MMA(1, 1, At, B1); PG8_BAR; PG8_SCHED;
;             PG8_LDB(B0, 1, 0); PG8_LDB(B1, 1, 1); PG8_SCHED; PG8_LDA(At, 1, 0); PG8_STAGE(PG8_SA(0, 1), a2 + hstepA, voffA);
;             PG8_WAIT_V(8); PG8_WAIT_L(0); PG8_BAR; PG8_MMA(0, 0, At, B0); PG8_MMA(0, 1, At, B1); PG8_BAR; PG8_SCHED;
	s_setprio 1
	s_waitcnt lgkmcnt(0)
	v_mfma_f32_16x16x32_bf16 v[100:103], v[80:83], v[178:181], v[100:103]
	v_mfma_f32_16x16x32_bf16 v[96:99], v[136:139], v[178:181], v[96:99]
	v_mfma_f32_16x16x32_bf16 v[92:95], v[80:83], v[186:189], v[92:95]
	v_mfma_f32_16x16x32_bf16 v[88:91], v[136:139], v[186:189], v[88:91]
	v_mfma_f32_16x16x32_bf16 v[76:79], v[80:83], v[194:197], v[76:79]
	v_mfma_f32_16x16x32_bf16 v[72:75], v[136:139], v[194:197], v[72:75]
	v_mfma_f32_16x16x32_bf16 v[68:71], v[80:83], v[204:207], v[68:71]
	v_mfma_f32_16x16x32_bf16 v[64:67], v[136:139], v[204:207], v[64:67]
	v_mfma_f32_16x16x32_bf16 v[100:103], v[84:87], v[182:185], v[100:103]
	v_mfma_f32_16x16x32_bf16 v[96:99], v[140:143], v[182:185], v[96:99]
	v_mfma_f32_16x16x32_bf16 v[92:95], v[84:87], v[190:193], v[92:95]
	v_mfma_f32_16x16x32_bf16 v[88:91], v[140:143], v[190:193], v[88:91]
	v_mfma_f32_16x16x32_bf16 v[76:79], v[84:87], v[198:201], v[76:79]
	v_mfma_f32_16x16x32_bf16 v[72:75], v[140:143], v[198:201], v[72:75]
	v_mfma_f32_16x16x32_bf16 v[68:71], v[84:87], v[208:211], v[68:71]
	v_mfma_f32_16x16x32_bf16 v[64:67], v[140:143], v[208:211], v[64:67]
	v_mfma_f32_16x16x32_bf16 v[28:31], v[154:157], v[178:181], v[28:31]
	v_mfma_f32_16x16x32_bf16 v[24:27], v[170:173], v[178:181], v[24:27]
	v_mfma_f32_16x16x32_bf16 v[20:23], v[154:157], v[186:189], v[20:23]
	v_mfma_f32_16x16x32_bf16 v[16:19], v[170:173], v[186:189], v[16:19]
	v_mfma_f32_16x16x32_bf16 v[12:15], v[154:157], v[194:197], v[12:15]
	v_mfma_f32_16x16x32_bf16 v[8:11], v[170:173], v[194:197], v[8:11]
	v_mfma_f32_16x16x32_bf16 v[4:7], v[154:157], v[204:207], v[4:7]
	v_mfma_f32_16x16x32_bf16 v[0:3], v[170:173], v[204:207], v[0:3]
	v_mfma_f32_16x16x32_bf16 v[28:31], v[166:169], v[182:185], v[28:31]
	v_mfma_f32_16x16x32_bf16 v[24:27], v[174:177], v[182:185], v[24:27]
	v_mfma_f32_16x16x32_bf16 v[20:23], v[166:169], v[190:193], v[20:23]
	v_mfma_f32_16x16x32_bf16 v[16:19], v[174:177], v[190:193], v[16:19]
	v_mfma_f32_16x16x32_bf16 v[12:15], v[166:169], v[198:201], v[12:15]
	v_mfma_f32_16x16x32_bf16 v[8:11], v[174:177], v[198:201], v[8:11]
	v_mfma_f32_16x16x32_bf16 v[4:7], v[166:169], v[208:211], v[4:7]
	v_mfma_f32_16x16x32_bf16 v[0:3], v[174:177], v[208:211], v[0:3]
	s_setprio 0
	s_barrier
	v_add_u32_e32 v140, s63, v160
	v_add_u32_e32 v152, s62, v160
	ds_read_b128 v[80:83], v140
	ds_read_b128 v[84:87], v140 offset:1024
	ds_read_b128 v[136:139], v140 offset:2048
	ds_read_b128 v[140:143], v140 offset:3072
	ds_read_b128 v[154:157], v152
	ds_read_b128 v[166:169], v152 offset:1024
	ds_read_b128 v[170:173], v152 offset:2048
	ds_read_b128 v[174:177], v152 offset:3072
	s_mov_b32 m0, s90
	v_lshl_add_u64 v[220:221], s[74:75], 0, v[144:145]
	ds_read_b128 v[178:181], v164 offset:32768
	ds_read_b128 v[182:185], v164 offset:33792
	ds_read_b128 v[186:189], v164 offset:34816
	ds_read_b128 v[190:193], v164 offset:35840
	ds_read_b128 v[194:197], v164 offset:36864
	ds_read_b128 v[198:201], v164 offset:37888
	ds_read_b128 v[204:207], v164 offset:38912
	ds_read_b128 v[208:211], v164 offset:39936
	global_load_lds_dwordx4 v[220:221], off
	v_lshl_add_u64 v[220:221], s[74:75], 0, v[148:149]
	s_mov_b32 m0, s91
	s_nop 0
	global_load_lds_dwordx4 v[220:221], off
	s_waitcnt vmcnt(8)
	s_waitcnt lgkmcnt(0)
	s_barrier
	s_setprio 1
	s_waitcnt lgkmcnt(0)
	v_mfma_f32_16x16x32_bf16 v[132:135], v[80:83], v[178:181], v[132:135]
	v_mfma_f32_16x16x32_bf16 v[128:131], v[136:139], v[178:181], v[128:131]
	v_mfma_f32_16x16x32_bf16 v[124:127], v[80:83], v[186:189], v[124:127]
	v_mfma_f32_16x16x32_bf16 v[120:123], v[136:139], v[186:189], v[120:123]
	v_mfma_f32_16x16x32_bf16 v[116:119], v[80:83], v[194:197], v[116:119]
	v_mfma_f32_16x16x32_bf16 v[112:115], v[136:139], v[194:197], v[112:115]
	v_mfma_f32_16x16x32_bf16 v[108:111], v[80:83], v[204:207], v[108:111]
	v_mfma_f32_16x16x32_bf16 v[104:107], v[136:139], v[204:207], v[104:107]
	v_mfma_f32_16x16x32_bf16 v[132:135], v[84:87], v[182:185], v[132:135]
	v_mfma_f32_16x16x32_bf16 v[128:131], v[140:143], v[182:185], v[128:131]
	v_mfma_f32_16x16x32_bf16 v[124:127], v[84:87], v[190:193], v[124:127]
	v_mfma_f32_16x16x32_bf16 v[120:123], v[140:143], v[190:193], v[120:123]
	v_mfma_f32_16x16x32_bf16 v[116:119], v[84:87], v[198:201], v[116:119]
	v_mfma_f32_16x16x32_bf16 v[112:115], v[140:143], v[198:201], v[112:115]
	v_mfma_f32_16x16x32_bf16 v[108:111], v[84:87], v[208:211], v[108:111]
	v_mfma_f32_16x16x32_bf16 v[104:107], v[140:143], v[208:211], v[104:107]
	v_mfma_f32_16x16x32_bf16 v[60:63], v[154:157], v[178:181], v[60:63]
	v_mfma_f32_16x16x32_bf16 v[56:59], v[170:173], v[178:181], v[56:59]
	v_mfma_f32_16x16x32_bf16 v[52:55], v[154:157], v[186:189], v[52:55]
	v_mfma_f32_16x16x32_bf16 v[48:51], v[170:173], v[186:189], v[48:51]
	v_mfma_f32_16x16x32_bf16 v[44:47], v[154:157], v[194:197], v[44:47]
	v_mfma_f32_16x16x32_bf16 v[40:43], v[170:173], v[194:197], v[40:43]
	v_mfma_f32_16x16x32_bf16 v[36:39], v[154:157], v[204:207], v[36:39]
	v_mfma_f32_16x16x32_bf16 v[32:35], v[170:173], v[204:207], v[32:35]
	v_mfma_f32_16x16x32_bf16 v[60:63], v[166:169], v[182:185], v[60:63]
	v_mfma_f32_16x16x32_bf16 v[56:59], v[174:177], v[182:185], v[56:59]
	v_mfma_f32_16x16x32_bf16 v[52:55], v[166:169], v[190:193], v[52:55]
	v_mfma_f32_16x16x32_bf16 v[48:51], v[174:177], v[190:193], v[48:51]
	v_mfma_f32_16x16x32_bf16 v[44:47], v[166:169], v[198:201], v[44:47]
	v_mfma_f32_16x16x32_bf16 v[40:43], v[174:177], v[198:201], v[40:43]
	v_mfma_f32_16x16x32_bf16 v[36:39], v[166:169], v[208:211], v[36:39]
	v_mfma_f32_16x16x32_bf16 v[32:35], v[174:177], v[208:211], v[32:35]
	s_setprio 0
	s_barrier
; #define PG8_STAGE(bufoff, gbase, voff) do { _Pragma("unroll") for (int _i = 0; _i < 2; ++_i) \
;         __builtin_amdgcn_global_load_lds((const unsigned*)((const char*)(gbase) + (voff)[_i]), (LAS unsigned*)(lds + (bufoff) + ldsw + _i * 8192), 16, 0, 0); } while (0)
; #define PG8_LDA(dst, b, h) do { _Pragma("unroll") for (int m = 0; m < 4; ++m) _Pragma("unroll") for (int k = 0; k < 2; ++k) dst[m][k] = *(const LAS bf16x8*)(lds + PG8_SA(b, h) + aoff + m * 2048 + k * 1024); } while (0)
; #define PG8_MMA(ai, bj, At, Bt) do { __builtin_amdgcn_s_setprio(1); _Pragma("unroll") for (int m = 0; m < 4; ++m) _Pragma("unroll") for (int n = 0; n < 2; ++n) _Pragma("unroll") for (int k = 0; k < 2; ++k) \
;         acc[ai][bj][m][n] = __builtin_amdgcn_mfma_f32_16x16x32_bf16(Bt[n][k], At[m][k], acc[ai][bj][m][n], 0, 0, 0); __builtin_amdgcn_s_setprio(0); } while (0)
; #define PG8_WAIT_V(n) asm volatile("s_waitcnt vmcnt(" #n ")" ::: "memory")
; #define PG8_WAIT_L(n) asm volatile("s_waitcnt lgkmcnt(" #n ")" ::: "memory")
; #define PG8_BAR __builtin_amdgcn_s_barrier()
; #define PG8_SCHED __builtin_amdgcn_sched_barrier(0)
; template <class Epi>
; __device__ __forceinline__ void gemm_phase(LAS unsigned char* lds, const Gemm g, const Sched& S, const Epi& E) {
;     ...
;             PG8_LDA(At, 1, 1); PG8_STAGE(PG8_SB(1, 0), b3, voffB); PG8_STAGE(PG8_SB(1, 1), b3 + hstepB, voffB); PG8_STAGE(PG8_SA(1, 0), a3, voffA);
;             PG8_WAIT_V(8); PG8_WAIT_L(0); PG8_BAR; PG8_MMA(1, 0, At, B0); PG8_MMA(1, 1, At, B1); PG8_BAR; PG8_SCHED;
;         }
	s_mov_b32 m0, s61
	v_lshl_add_u64 v[212:213], v[212:213], 0, s[6:7]
	ds_read_b128 v[178:181], v164 offset:49152
	ds_read_b128 v[182:185], v164 offset:50176
	ds_read_b128 v[186:189], v164 offset:51200
	ds_read_b128 v[190:193], v164 offset:52224
	ds_read_b128 v[194:197], v164 offset:53248
	ds_read_b128 v[198:201], v164 offset:54272
	ds_read_b128 v[204:207], v164 offset:55296
	ds_read_b128 v[208:211], v164 offset:56320
	global_load_lds_dwordx4 v[212:213], off
	v_lshl_add_u64 v[212:213], v[214:215], 0, s[6:7]
	s_mov_b32 m0, s59
	s_nop 0
	global_load_lds_dwordx4 v[212:213], off
	v_lshl_add_u64 v[212:213], s[56:57], 0, v[146:147]
	s_mov_b32 m0, s60
	s_nop 0
	global_load_lds_dwordx4 v[212:213], off
	v_lshl_add_u64 v[212:213], s[56:57], 0, v[150:151]
	s_mov_b32 m0, s58
	s_nop 0
	global_load_lds_dwordx4 v[212:213], off
	v_lshl_add_u64 v[212:213], v[216:217], 0, s[6:7]
	s_mov_b32 m0, s94
	s_nop 0
	global_load_lds_dwordx4 v[212:213], off
	v_lshl_add_u64 v[212:213], v[218:219], 0, s[6:7]
	s_mov_b32 m0, s95
	s_nop 0
	global_load_lds_dwordx4 v[212:213], off
	s_waitcnt vmcnt(8)
	s_waitcnt lgkmcnt(0)
	s_barrier
	s_setprio 1
	s_waitcnt lgkmcnt(0)
	v_mfma_f32_16x16x32_bf16 v[100:103], v[80:83], v[178:181], v[100:103]
	v_mfma_f32_16x16x32_bf16 v[96:99], v[136:139], v[178:181], v[96:99]
	v_mfma_f32_16x16x32_bf16 v[92:95], v[80:83], v[186:189], v[92:95]
	v_mfma_f32_16x16x32_bf16 v[88:91], v[136:139], v[186:189], v[88:91]
	v_mfma_f32_16x16x32_bf16 v[76:79], v[80:83], v[194:197], v[76:79]
	v_mfma_f32_16x16x32_bf16 v[72:75], v[136:139], v[194:197], v[72:75]
	v_mfma_f32_16x16x32_bf16 v[68:71], v[80:83], v[204:207], v[68:71]
	v_mfma_f32_16x16x32_bf16 v[64:67], v[136:139], v[204:207], v[64:67]
	v_mfma_f32_16x16x32_bf16 v[100:103], v[84:87], v[182:185], v[100:103]
	v_mfma_f32_16x16x32_bf16 v[96:99], v[140:143], v[182:185], v[96:99]
	v_mfma_f32_16x16x32_bf16 v[92:95], v[84:87], v[190:193], v[92:95]
	v_mfma_f32_16x16x32_bf16 v[88:91], v[140:143], v[190:193], v[88:91]
	v_mfma_f32_16x16x32_bf16 v[76:79], v[84:87], v[198:201], v[76:79]
	v_mfma_f32_16x16x32_bf16 v[72:75], v[140:143], v[198:201], v[72:75]
	v_mfma_f32_16x16x32_bf16 v[68:71], v[84:87], v[208:211], v[68:71]
	v_mfma_f32_16x16x32_bf16 v[64:67], v[140:143], v[208:211], v[64:67]
	v_mfma_f32_16x16x32_bf16 v[28:31], v[154:157], v[178:181], v[28:31]
	v_mfma_f32_16x16x32_bf16 v[24:27], v[170:173], v[178:181], v[24:27]
	v_mfma_f32_16x16x32_bf16 v[20:23], v[154:157], v[186:189], v[20:23]
	v_mfma_f32_16x16x32_bf16 v[16:19], v[170:173], v[186:189], v[16:19]
	v_mfma_f32_16x16x32_bf16 v[12:15], v[154:157], v[194:197], v[12:15]
	v_mfma_f32_16x16x32_bf16 v[8:11], v[170:173], v[194:197], v[8:11]
	v_mfma_f32_16x16x32_bf16 v[4:7], v[154:157], v[204:207], v[4:7]
	v_mfma_f32_16x16x32_bf16 v[0:3], v[170:173], v[204:207], v[0:3]
	v_mfma_f32_16x16x32_bf16 v[28:31], v[166:169], v[182:185], v[28:31]
	v_mfma_f32_16x16x32_bf16 v[24:27], v[174:177], v[182:185], v[24:27]
	v_mfma_f32_16x16x32_bf16 v[20:23], v[166:169], v[190:193], v[20:23]
	v_mfma_f32_16x16x32_bf16 v[16:19], v[174:177], v[190:193], v[16:19]
	v_mfma_f32_16x16x32_bf16 v[12:15], v[166:169], v[198:201], v[12:15]
	v_mfma_f32_16x16x32_bf16 v[8:11], v[174:177], v[198:201], v[8:11]
	v_mfma_f32_16x16x32_bf16 v[4:7], v[166:169], v[208:211], v[4:7]
	v_mfma_f32_16x16x32_bf16 v[0:3], v[174:177], v[208:211], v[0:3]
	s_setprio 0
	s_barrier
	s_andn2_b64 vcc, exec, s[54:55]
	s_mov_b64 s[56:57], -1
	s_mov_b64 s[54:55], 0
	s_mov_b64 s[74:75], 0x100
	s_cbranch_vccz .LBB0_773
	s_and_b64 vcc, exec, s[8:9]
	s_cbranch_vccz .LBB0_776
	s_barrier

; #define PG8_STAGE(bufoff, gbase, voff) do { _Pragma("unroll") for (int _i = 0; _i < 2; ++_i) \
;         __builtin_amdgcn_global_load_lds((const unsigned*)((const char*)(gbase) + (voff)[_i]), (LAS unsigned*)(lds + (bufoff) + ldsw + _i * 8192), 16, 0, 0); } while (0)
; #define PG8_LDA(dst, b, h) do { _Pragma("unroll") for (int m = 0; m < 4; ++m) _Pragma("unroll") for (int k = 0; k < 2; ++k) dst[m][k] = *(const LAS bf16x8*)(lds + PG8_SA(b, h) + aoff + m * 2048 + k * 1024); } while (0)
; #define PG8_LDB(dst, b, h) do { _Pragma("unroll") for (int n = 0; n < 2; ++n) _Pragma("unroll") for (int k = 0; k < 2; ++k) dst[n][k] = *(const LAS bf16x8*)(lds + PG8_SB(b, h) + boff + n * 2048 + k * 1024); } while (0)
; #define PG8_MMA(ai, bj, At, Bt) do { __builtin_amdgcn_s_setprio(1); _Pragma("unroll") for (int m = 0; m < 4; ++m) _Pragma("unroll") for (int n = 0; n < 2; ++n) _Pragma("unroll") for (int k = 0; k < 2; ++k) \
;         acc[ai][bj][m][n] = __builtin_amdgcn_mfma_f32_16x16x32_bf16(Bt[n][k], At[m][k], acc[ai][bj][m][n], 0, 0, 0); __builtin_amdgcn_s_setprio(0); } while (0)
; #define PG8_WAIT_V(n) asm volatile("s_waitcnt vmcnt(" #n ")" ::: "memory")
; template <class Epi>
; __device__ __forceinline__ void gemm_phase(LAS unsigned char* lds, const Gemm g, const Sched& S, const Epi& E) {
;     ...
;         const char* nA = has_next ? (const char*)g.A + (size_t)S.aoff(nxt) * 2 : cA; const char* nB = has_next ? (const char*)g.Bt + (size_t)S.boff(nxt) * 2 : cB;
;         _Pragma("nounroll")
;         for (int t = 0; t < nt; t += 2) {
;             const bool last = (t == nt - 2);
;             const char* a1 = cA + (size_t)(t + 1) * kstep;
;             const char* a2 = last ? nA : cA + (size_t)(t + 2) * kstep; const char* b2 = last ? nB : cB + (size_t)(t + 2) * kstep;
;             const char* a3 = a2 + kstep; const char* b3 = b2 + kstep;
;             PG8_LDB(B0, 0, 0); PG8_LDB(B1, 0, 1); PG8_SCHED; PG8_LDA(At, 0, 0); PG8_STAGE(PG8_SA(1, 1), a1 + hstepA, voffA);
;             PG8_WAIT_V(8); PG8_WAIT_L(0); PG8_BAR; PG8_MMA(0, 0, At, B0); PG8_MMA(0, 1, At, B1); PG8_BAR; PG8_SCHED;
;             PG8_LDA(At, 0, 1); PG8_STAGE(PG8_SB(0, 0), b2, voffB); PG8_STAGE(PG8_SB(0, 1), b2 + hstepB, voffB); PG8_STAGE(PG8_SA(0, 0), a2, voffA);
;             PG8_WAIT_V(8); PG8_WAIT_L(0); PG8_BAR; PG8_MMA(1, 0, At, B0); PG8_MMA(1, 1, At, B1); PG8_BAR; PG8_SCHED;
.LBB0_900:
	s_add_u32 s57, s4, s78
	s_addc_u32 s64, s5, s79
	s_add_u32 s65, s57, 0x100
	s_addc_u32 s66, s64, 0
	s_and_b64 s[62:63], s[14:15], exec
	s_cselect_b32 s83, s75, s66
	s_cselect_b32 s82, s74, s65
	s_add_u32 s62, s6, s78
	s_addc_u32 s63, s7, s79
	s_add_u32 s62, s62, 0x100
	s_addc_u32 s63, s63, 0
	s_and_b64 s[14:15], s[14:15], exec
	s_cselect_b32 s87, s1, s63
	s_cselect_b32 s86, s55, s62
	s_add_u32 s90, s57, 0x40080
	ds_read_b128 v[96:99], v155
	ds_read_b128 v[100:103], v155 offset:1024
	ds_read_b128 v[144:147], v155 offset:2048
	ds_read_b128 v[148:151], v155 offset:3072
	ds_read_b128 v[160:163], v156
	ds_read_b128 v[164:167], v156 offset:1024
	ds_read_b128 v[168:171], v156 offset:2048
	ds_read_b128 v[172:175], v156 offset:3072
	s_addc_u32 s91, s64, 0
	s_add_i32 s67, s59, s10
	s_add_i32 m0, s11, 0xc000
	s_add_i32 s85, s11, 0xe000
	s_add_i32 s84, s67, 0x2000
	s_add_u32 s88, s86, 0x10000
	s_addc_u32 s89, s87, 0
	s_add_i32 vcc_hi, s60, s10
	s_add_i32 vcc_lo, vcc_hi, 0x2000
	s_add_i32 s66, 0, 0x18000
	s_add_i32 s65, 0, 0x1c000
	s_add_u32 s78, s82, 0x40000
	s_addc_u32 s79, s83, 0
	s_add_i32 s64, s66, s10
	s_add_i32 s62, s64, 0x2000
	s_add_u32 s14, s86, 0x10080
	s_addc_u32 s15, s87, 0
	s_add_i32 s63, s65, s10
	s_add_i32 s57, s63, 0x2000
	v_lshl_add_u64 v[200:201], s[90:91], 0, v[136:137]
	ds_read_b128 v[176:179], v157
	ds_read_b128 v[180:183], v157 offset:1024
	ds_read_b128 v[184:187], v157 offset:2048
	ds_read_b128 v[188:191], v157 offset:3072
	ds_read_b128 v[192:195], v157 offset:4096
	ds_read_b128 v[196:199], v157 offset:5120
	ds_read_b128 v[204:207], v157 offset:6144
	ds_read_b128 v[208:211], v157 offset:7168
	global_load_lds_dwordx4 v[200:201], off
	v_lshl_add_u64 v[200:201], s[90:91], 0, v[140:141]
	s_mov_b32 m0, s85
	s_nop 0
	global_load_lds_dwordx4 v[200:201], off
	s_waitcnt vmcnt(8)
	s_waitcnt lgkmcnt(0)
	s_barrier
	s_setprio 1
	s_waitcnt lgkmcnt(0)
	v_mfma_f32_16x16x32_bf16 v[132:135], v[96:99], v[176:179], v[132:135]
	v_mfma_f32_16x16x32_bf16 v[128:131], v[144:147], v[176:179], v[128:131]
	v_mfma_f32_16x16x32_bf16 v[124:127], v[96:99], v[184:187], v[124:127]
	v_mfma_f32_16x16x32_bf16 v[120:123], v[144:147], v[184:187], v[120:123]
	v_mfma_f32_16x16x32_bf16 v[116:119], v[96:99], v[192:195], v[116:119]
	v_mfma_f32_16x16x32_bf16 v[112:115], v[144:147], v[192:195], v[112:115]
	v_mfma_f32_16x16x32_bf16 v[108:111], v[96:99], v[204:207], v[108:111]
	v_mfma_f32_16x16x32_bf16 v[104:107], v[144:147], v[204:207], v[104:107]
	v_mfma_f32_16x16x32_bf16 v[132:135], v[100:103], v[180:183], v[132:135]
	v_mfma_f32_16x16x32_bf16 v[128:131], v[148:151], v[180:183], v[128:131]
	v_mfma_f32_16x16x32_bf16 v[124:127], v[100:103], v[188:191], v[124:127]
	v_mfma_f32_16x16x32_bf16 v[120:123], v[148:151], v[188:191], v[120:123]
	v_mfma_f32_16x16x32_bf16 v[116:119], v[100:103], v[196:199], v[116:119]
	v_mfma_f32_16x16x32_bf16 v[112:115], v[148:151], v[196:199], v[112:115]
	v_mfma_f32_16x16x32_bf16 v[108:111], v[100:103], v[208:211], v[108:111]
	v_mfma_f32_16x16x32_bf16 v[104:107], v[148:151], v[208:211], v[104:107]
	v_mfma_f32_16x16x32_bf16 v[60:63], v[160:163], v[176:179], v[60:63]
	v_mfma_f32_16x16x32_bf16 v[56:59], v[168:171], v[176:179], v[56:59]
	v_mfma_f32_16x16x32_bf16 v[52:55], v[160:163], v[184:187], v[52:55]
	v_mfma_f32_16x16x32_bf16 v[48:51], v[168:171], v[184:187], v[48:51]
	v_mfma_f32_16x16x32_bf16 v[44:47], v[160:163], v[192:195], v[44:47]
	v_mfma_f32_16x16x32_bf16 v[40:43], v[168:171], v[192:195], v[40:43]
	v_mfma_f32_16x16x32_bf16 v[36:39], v[160:163], v[204:207], v[36:39]
	v_mfma_f32_16x16x32_bf16 v[32:35], v[168:171], v[204:207], v[32:35]
	v_mfma_f32_16x16x32_bf16 v[60:63], v[164:167], v[180:183], v[60:63]
	v_mfma_f32_16x16x32_bf16 v[56:59], v[172:175], v[180:183], v[56:59]
	v_mfma_f32_16x16x32_bf16 v[52:55], v[164:167], v[188:191], v[52:55]
	v_mfma_f32_16x16x32_bf16 v[48:51], v[172:175], v[188:191], v[48:51]
	v_mfma_f32_16x16x32_bf16 v[44:47], v[164:167], v[196:199], v[44:47]
	v_mfma_f32_16x16x32_bf16 v[40:43], v[172:175], v[196:199], v[40:43]
	v_mfma_f32_16x16x32_bf16 v[36:39], v[164:167], v[208:211], v[36:39]
	v_mfma_f32_16x16x32_bf16 v[32:35], v[172:175], v[208:211], v[32:35]
	s_setprio 0
	s_barrier
	s_mov_b32 m0, s67
	v_lshl_add_u64 v[200:201], s[86:87], 0, v[138:139]
	ds_read_b128 v[176:179], v157 offset:16384
	ds_read_b128 v[180:183], v157 offset:17408
	ds_read_b128 v[184:187], v157 offset:18432
	ds_read_b128 v[188:191], v157 offset:19456
	ds_read_b128 v[192:195], v157 offset:20480
	ds_read_b128 v[196:199], v157 offset:21504
	ds_read_b128 v[204:207], v157 offset:22528
	ds_read_b128 v[208:211], v157 offset:23552
	global_load_lds_dwordx4 v[200:201], off
	v_lshl_add_u64 v[212:213], s[86:87], 0, v[142:143]
	s_mov_b32 m0, s84
	v_lshl_add_u64 v[214:215], s[88:89], 0, v[138:139]
	global_load_lds_dwordx4 v[212:213], off
	s_mov_b32 m0, vcc_hi
	v_lshl_add_u64 v[216:217], s[82:83], 0, v[140:141]
	global_load_lds_dwordx4 v[214:215], off
	v_lshl_add_u64 v[214:215], s[88:89], 0, v[142:143]
	s_mov_b32 m0, vcc_lo
	s_nop 0
	global_load_lds_dwordx4 v[214:215], off
	v_lshl_add_u64 v[214:215], s[82:83], 0, v[136:137]
	s_mov_b32 m0, s11
	s_nop 0
	global_load_lds_dwordx4 v[214:215], off
	s_mov_b32 m0, s93
	s_nop 0
	global_load_lds_dwordx4 v[216:217], off
	s_waitcnt vmcnt(8)
	s_waitcnt lgkmcnt(0)
	s_barrier
; #define PG8_STAGE(bufoff, gbase, voff) do { _Pragma("unroll") for (int _i = 0; _i < 2; ++_i) \
;         __builtin_amdgcn_global_load_lds((const unsigned*)((const char*)(gbase) + (voff)[_i]), (LAS unsigned*)(lds + (bufoff) + ldsw + _i * 8192), 16, 0, 0); } while (0)
; #define PG8_LDA(dst, b, h) do { _Pragma("unroll") for (int m = 0; m < 4; ++m) _Pragma("unroll") for (int k = 0; k < 2; ++k) dst[m][k] = *(const LAS bf16x8*)(lds + PG8_SA(b, h) + aoff + m * 2048 + k * 1024); } while (0)
; #define PG8_LDB(dst, b, h) do { _Pragma("unroll") for (int n = 0; n < 2; ++n) _Pragma("unroll") for (int k = 0; k < 2; ++k) dst[n][k] = *(const LAS bf16x8*)(lds + PG8_SB(b, h) + boff + n * 2048 + k * 1024); } while (0)
; #define PG8_MMA(ai, bj, At, Bt) do { __builtin_amdgcn_s_setprio(1); _Pragma("unroll") for (int m = 0; m < 4; ++m) _Pragma("unroll") for (int n = 0; n < 2; ++n) _Pragma("unroll") for (int k = 0; k < 2; ++k) \
;         acc[ai][bj][m][n] = __builtin_amdgcn_mfma_f32_16x16x32_bf16(Bt[n][k], At[m][k], acc[ai][bj][m][n], 0, 0, 0); __builtin_amdgcn_s_setprio(0); } while (0)
; #define PG8_WAIT_V(n) asm volatile("s_waitcnt vmcnt(" #n ")" ::: "memory")
; #define PG8_WAIT_L(n) asm volatile("s_waitcnt lgkmcnt(" #n ")" ::: "memory")
; #define PG8_BAR __builtin_amdgcn_s_barrier()
; #define PG8_SCHED __builtin_amdgcn_sched_barrier(0)
; template <class Epi>
; __device__ __forceinline__ void gemm_phase(LAS unsigned char* lds, const Gemm g, const Sched& S, const Epi& E) {
;     ...
;             PG8_WAIT_V(8); PG8_WAIT_L(0); PG8_BAR; PG8_MMA(1, 0, At, B0); PG8_MMA(1, 1, At, B1); PG8_BAR; PG8_SCHED;
;             PG8_LDB(B0, 1, 0); PG8_LDB(B1, 1, 1); PG8_SCHED; PG8_LDA(At, 1, 0); PG8_STAGE(PG8_SA(0, 1), a2 + hstepA, voffA);
;             PG8_WAIT_V(8); PG8_WAIT_L(0); PG8_BAR; PG8_MMA(0, 0, At, B0); PG8_MMA(0, 1, At, B1); PG8_BAR; PG8_SCHED;
	s_setprio 1
	s_waitcnt lgkmcnt(0)
	v_mfma_f32_16x16x32_bf16 v[92:95], v[96:99], v[176:179], v[92:95]
	v_mfma_f32_16x16x32_bf16 v[88:91], v[144:147], v[176:179], v[88:91]
	v_mfma_f32_16x16x32_bf16 v[84:87], v[96:99], v[184:187], v[84:87]
	v_mfma_f32_16x16x32_bf16 v[80:83], v[144:147], v[184:187], v[80:83]
	v_mfma_f32_16x16x32_bf16 v[76:79], v[96:99], v[192:195], v[76:79]
	v_mfma_f32_16x16x32_bf16 v[72:75], v[144:147], v[192:195], v[72:75]
	v_mfma_f32_16x16x32_bf16 v[68:71], v[96:99], v[204:207], v[68:71]
	v_mfma_f32_16x16x32_bf16 v[64:67], v[144:147], v[204:207], v[64:67]
	v_mfma_f32_16x16x32_bf16 v[92:95], v[100:103], v[180:183], v[92:95]
	v_mfma_f32_16x16x32_bf16 v[88:91], v[148:151], v[180:183], v[88:91]
	v_mfma_f32_16x16x32_bf16 v[84:87], v[100:103], v[188:191], v[84:87]
	v_mfma_f32_16x16x32_bf16 v[80:83], v[148:151], v[188:191], v[80:83]
	v_mfma_f32_16x16x32_bf16 v[76:79], v[100:103], v[196:199], v[76:79]
	v_mfma_f32_16x16x32_bf16 v[72:75], v[148:151], v[196:199], v[72:75]
	v_mfma_f32_16x16x32_bf16 v[68:71], v[100:103], v[208:211], v[68:71]
	v_mfma_f32_16x16x32_bf16 v[64:67], v[148:151], v[208:211], v[64:67]
	v_mfma_f32_16x16x32_bf16 v[28:31], v[160:163], v[176:179], v[28:31]
	v_mfma_f32_16x16x32_bf16 v[24:27], v[168:171], v[176:179], v[24:27]
	v_mfma_f32_16x16x32_bf16 v[20:23], v[160:163], v[184:187], v[20:23]
	v_mfma_f32_16x16x32_bf16 v[16:19], v[168:171], v[184:187], v[16:19]
	v_mfma_f32_16x16x32_bf16 v[12:15], v[160:163], v[192:195], v[12:15]
	v_mfma_f32_16x16x32_bf16 v[8:11], v[168:171], v[192:195], v[8:11]
	v_mfma_f32_16x16x32_bf16 v[4:7], v[160:163], v[204:207], v[4:7]
	v_mfma_f32_16x16x32_bf16 v[0:3], v[168:171], v[204:207], v[0:3]
	v_mfma_f32_16x16x32_bf16 v[28:31], v[164:167], v[180:183], v[28:31]
	v_mfma_f32_16x16x32_bf16 v[24:27], v[172:175], v[180:183], v[24:27]
	v_mfma_f32_16x16x32_bf16 v[20:23], v[164:167], v[188:191], v[20:23]
	v_mfma_f32_16x16x32_bf16 v[16:19], v[172:175], v[188:191], v[16:19]
	v_mfma_f32_16x16x32_bf16 v[12:15], v[164:167], v[196:199], v[12:15]
	v_mfma_f32_16x16x32_bf16 v[8:11], v[172:175], v[196:199], v[8:11]
	v_mfma_f32_16x16x32_bf16 v[4:7], v[164:167], v[208:211], v[4:7]
	v_mfma_f32_16x16x32_bf16 v[0:3], v[172:175], v[208:211], v[0:3]
	s_setprio 0
	s_barrier
	v_add_u32_e32 v148, s66, v153
	v_add_u32_e32 v159, s65, v153
	ds_read_b128 v[96:99], v148
	ds_read_b128 v[100:103], v148 offset:1024
	ds_read_b128 v[144:147], v148 offset:2048
	ds_read_b128 v[148:151], v148 offset:3072
	ds_read_b128 v[160:163], v159
	ds_read_b128 v[164:167], v159 offset:1024
	ds_read_b128 v[168:171], v159 offset:2048
	ds_read_b128 v[172:175], v159 offset:3072
	s_mov_b32 m0, s94
	v_lshl_add_u64 v[218:219], s[78:79], 0, v[136:137]
	ds_read_b128 v[176:179], v157 offset:32768
	ds_read_b128 v[180:183], v157 offset:33792
	ds_read_b128 v[184:187], v157 offset:34816
	ds_read_b128 v[188:191], v157 offset:35840
	ds_read_b128 v[192:195], v157 offset:36864
	ds_read_b128 v[196:199], v157 offset:37888
	ds_read_b128 v[204:207], v157 offset:38912
	ds_read_b128 v[208:211], v157 offset:39936
	global_load_lds_dwordx4 v[218:219], off
	v_lshl_add_u64 v[218:219], s[78:79], 0, v[140:141]
	s_mov_b32 m0, s95
	s_nop 0
	global_load_lds_dwordx4 v[218:219], off
	s_waitcnt vmcnt(8)
	s_waitcnt lgkmcnt(0)
	s_barrier
	s_setprio 1
	s_waitcnt lgkmcnt(0)
	v_mfma_f32_16x16x32_bf16 v[132:135], v[96:99], v[176:179], v[132:135]
	v_mfma_f32_16x16x32_bf16 v[128:131], v[144:147], v[176:179], v[128:131]
	v_mfma_f32_16x16x32_bf16 v[124:127], v[96:99], v[184:187], v[124:127]
	v_mfma_f32_16x16x32_bf16 v[120:123], v[144:147], v[184:187], v[120:123]
	v_mfma_f32_16x16x32_bf16 v[116:119], v[96:99], v[192:195], v[116:119]
	v_mfma_f32_16x16x32_bf16 v[112:115], v[144:147], v[192:195], v[112:115]
	v_mfma_f32_16x16x32_bf16 v[108:111], v[96:99], v[204:207], v[108:111]
	v_mfma_f32_16x16x32_bf16 v[104:107], v[144:147], v[204:207], v[104:107]
	v_mfma_f32_16x16x32_bf16 v[132:135], v[100:103], v[180:183], v[132:135]
	v_mfma_f32_16x16x32_bf16 v[128:131], v[148:151], v[180:183], v[128:131]
	v_mfma_f32_16x16x32_bf16 v[124:127], v[100:103], v[188:191], v[124:127]
	v_mfma_f32_16x16x32_bf16 v[120:123], v[148:151], v[188:191], v[120:123]
	v_mfma_f32_16x16x32_bf16 v[116:119], v[100:103], v[196:199], v[116:119]
	v_mfma_f32_16x16x32_bf16 v[112:115], v[148:151], v[196:199], v[112:115]
	v_mfma_f32_16x16x32_bf16 v[108:111], v[100:103], v[208:211], v[108:111]
	v_mfma_f32_16x16x32_bf16 v[104:107], v[148:151], v[208:211], v[104:107]
	v_mfma_f32_16x16x32_bf16 v[60:63], v[160:163], v[176:179], v[60:63]
	v_mfma_f32_16x16x32_bf16 v[56:59], v[168:171], v[176:179], v[56:59]
	v_mfma_f32_16x16x32_bf16 v[52:55], v[160:163], v[184:187], v[52:55]
	v_mfma_f32_16x16x32_bf16 v[48:51], v[168:171], v[184:187], v[48:51]
	v_mfma_f32_16x16x32_bf16 v[44:47], v[160:163], v[192:195], v[44:47]
	v_mfma_f32_16x16x32_bf16 v[40:43], v[168:171], v[192:195], v[40:43]
	v_mfma_f32_16x16x32_bf16 v[36:39], v[160:163], v[204:207], v[36:39]
	v_mfma_f32_16x16x32_bf16 v[32:35], v[168:171], v[204:207], v[32:35]
	v_mfma_f32_16x16x32_bf16 v[60:63], v[164:167], v[180:183], v[60:63]
	v_mfma_f32_16x16x32_bf16 v[56:59], v[172:175], v[180:183], v[56:59]
	v_mfma_f32_16x16x32_bf16 v[52:55], v[164:167], v[188:191], v[52:55]
	v_mfma_f32_16x16x32_bf16 v[48:51], v[172:175], v[188:191], v[48:51]
	v_mfma_f32_16x16x32_bf16 v[44:47], v[164:167], v[196:199], v[44:47]
	v_mfma_f32_16x16x32_bf16 v[40:43], v[172:175], v[196:199], v[40:43]
	v_mfma_f32_16x16x32_bf16 v[36:39], v[164:167], v[208:211], v[36:39]
	v_mfma_f32_16x16x32_bf16 v[32:35], v[172:175], v[208:211], v[32:35]
	s_setprio 0
	s_barrier
; #define PG8_STAGE(bufoff, gbase, voff) do { _Pragma("unroll") for (int _i = 0; _i < 2; ++_i) \
;         __builtin_amdgcn_global_load_lds((const unsigned*)((const char*)(gbase) + (voff)[_i]), (LAS unsigned*)(lds + (bufoff) + ldsw + _i * 8192), 16, 0, 0); } while (0)
; #define PG8_LDA(dst, b, h) do { _Pragma("unroll") for (int m = 0; m < 4; ++m) _Pragma("unroll") for (int k = 0; k < 2; ++k) dst[m][k] = *(const LAS bf16x8*)(lds + PG8_SA(b, h) + aoff + m * 2048 + k * 1024); } while (0)
; #define PG8_MMA(ai, bj, At, Bt) do { __builtin_amdgcn_s_setprio(1); _Pragma("unroll") for (int m = 0; m < 4; ++m) _Pragma("unroll") for (int n = 0; n < 2; ++n) _Pragma("unroll") for (int k = 0; k < 2; ++k) \
;         acc[ai][bj][m][n] = __builtin_amdgcn_mfma_f32_16x16x32_bf16(Bt[n][k], At[m][k], acc[ai][bj][m][n], 0, 0, 0); __builtin_amdgcn_s_setprio(0); } while (0)
; #define PG8_WAIT_V(n) asm volatile("s_waitcnt vmcnt(" #n ")" ::: "memory")
; #define PG8_WAIT_L(n) asm volatile("s_waitcnt lgkmcnt(" #n ")" ::: "memory")
; #define PG8_BAR __builtin_amdgcn_s_barrier()
; #define PG8_SCHED __builtin_amdgcn_sched_barrier(0)
; template <class Epi>
; __device__ __forceinline__ void gemm_phase(LAS unsigned char* lds, const Gemm g, const Sched& S, const Epi& E) {
;     ...
;             PG8_LDA(At, 1, 1); PG8_STAGE(PG8_SB(1, 0), b3, voffB); PG8_STAGE(PG8_SB(1, 1), b3 + hstepB, voffB); PG8_STAGE(PG8_SA(1, 0), a3, voffA);
;             PG8_WAIT_V(8); PG8_WAIT_L(0); PG8_BAR; PG8_MMA(1, 0, At, B0); PG8_MMA(1, 1, At, B1); PG8_BAR; PG8_SCHED;
;         }
;         if (wr == 0) PG8_BAR;
	s_mov_b32 m0, s64
	v_lshl_add_u64 v[200:201], v[200:201], 0, s[46:47]
	ds_read_b128 v[176:179], v157 offset:49152
	ds_read_b128 v[180:183], v157 offset:50176
	ds_read_b128 v[184:187], v157 offset:51200
	ds_read_b128 v[188:191], v157 offset:52224
	ds_read_b128 v[192:195], v157 offset:53248
	ds_read_b128 v[196:199], v157 offset:54272
	ds_read_b128 v[204:207], v157 offset:55296
	ds_read_b128 v[208:211], v157 offset:56320
	global_load_lds_dwordx4 v[200:201], off
	v_lshl_add_u64 v[200:201], v[212:213], 0, s[46:47]
	s_mov_b32 m0, s62
	s_nop 0
	global_load_lds_dwordx4 v[200:201], off
	v_lshl_add_u64 v[200:201], s[14:15], 0, v[138:139]
	s_mov_b32 m0, s63
	s_nop 0
	global_load_lds_dwordx4 v[200:201], off
	v_lshl_add_u64 v[200:201], s[14:15], 0, v[142:143]
	s_mov_b32 m0, s57
	s_nop 0
	global_load_lds_dwordx4 v[200:201], off
	v_lshl_add_u64 v[200:201], v[214:215], 0, s[46:47]
	s_mov_b32 m0, s97
	s_nop 0
	global_load_lds_dwordx4 v[200:201], off
	v_lshl_add_u64 v[200:201], v[216:217], 0, s[46:47]
	s_mov_b32 m0, s58
	s_nop 0
	global_load_lds_dwordx4 v[200:201], off
	s_waitcnt vmcnt(8)
	s_waitcnt lgkmcnt(0)
	s_barrier
	s_setprio 1
	s_waitcnt lgkmcnt(0)
	v_mfma_f32_16x16x32_bf16 v[92:95], v[96:99], v[176:179], v[92:95]
	v_mfma_f32_16x16x32_bf16 v[88:91], v[144:147], v[176:179], v[88:91]
	v_mfma_f32_16x16x32_bf16 v[84:87], v[96:99], v[184:187], v[84:87]
	v_mfma_f32_16x16x32_bf16 v[80:83], v[144:147], v[184:187], v[80:83]
	v_mfma_f32_16x16x32_bf16 v[76:79], v[96:99], v[192:195], v[76:79]
	v_mfma_f32_16x16x32_bf16 v[72:75], v[144:147], v[192:195], v[72:75]
	v_mfma_f32_16x16x32_bf16 v[68:71], v[96:99], v[204:207], v[68:71]
	v_mfma_f32_16x16x32_bf16 v[64:67], v[144:147], v[204:207], v[64:67]
	v_mfma_f32_16x16x32_bf16 v[92:95], v[100:103], v[180:183], v[92:95]
	v_mfma_f32_16x16x32_bf16 v[88:91], v[148:151], v[180:183], v[88:91]
	v_mfma_f32_16x16x32_bf16 v[84:87], v[100:103], v[188:191], v[84:87]
	v_mfma_f32_16x16x32_bf16 v[80:83], v[148:151], v[188:191], v[80:83]
	v_mfma_f32_16x16x32_bf16 v[76:79], v[100:103], v[196:199], v[76:79]
	v_mfma_f32_16x16x32_bf16 v[72:75], v[148:151], v[196:199], v[72:75]
	v_mfma_f32_16x16x32_bf16 v[68:71], v[100:103], v[208:211], v[68:71]
	v_mfma_f32_16x16x32_bf16 v[64:67], v[148:151], v[208:211], v[64:67]
	v_mfma_f32_16x16x32_bf16 v[28:31], v[160:163], v[176:179], v[28:31]
	v_mfma_f32_16x16x32_bf16 v[24:27], v[168:171], v[176:179], v[24:27]
	v_mfma_f32_16x16x32_bf16 v[20:23], v[160:163], v[184:187], v[20:23]
	v_mfma_f32_16x16x32_bf16 v[16:19], v[168:171], v[184:187], v[16:19]
	v_mfma_f32_16x16x32_bf16 v[12:15], v[160:163], v[192:195], v[12:15]
	v_mfma_f32_16x16x32_bf16 v[8:11], v[168:171], v[192:195], v[8:11]
	v_mfma_f32_16x16x32_bf16 v[4:7], v[160:163], v[204:207], v[4:7]
	v_mfma_f32_16x16x32_bf16 v[0:3], v[168:171], v[204:207], v[0:3]
	v_mfma_f32_16x16x32_bf16 v[28:31], v[164:167], v[180:183], v[28:31]
	v_mfma_f32_16x16x32_bf16 v[24:27], v[172:175], v[180:183], v[24:27]
	v_mfma_f32_16x16x32_bf16 v[20:23], v[164:167], v[188:191], v[20:23]
	v_mfma_f32_16x16x32_bf16 v[16:19], v[172:175], v[188:191], v[16:19]
	v_mfma_f32_16x16x32_bf16 v[12:15], v[164:167], v[196:199], v[12:15]
	v_mfma_f32_16x16x32_bf16 v[8:11], v[172:175], v[196:199], v[8:11]
	v_mfma_f32_16x16x32_bf16 v[4:7], v[164:167], v[208:211], v[4:7]
	v_mfma_f32_16x16x32_bf16 v[0:3], v[172:175], v[208:211], v[0:3]
	s_setprio 0
	s_barrier
	s_andn2_b64 vcc, exec, s[8:9]
	s_mov_b64 s[14:15], -1
	s_mov_b64 s[8:9], 0
	s_mov_b64 s[78:79], 0x100
	s_cbranch_vccz .LBB0_900
	s_and_b64 vcc, exec, s[52:53]
	s_cbranch_vccz .LBB0_903
	s_barrier

; #define PG8_STAGE(bufoff, gbase, voff) do { _Pragma("unroll") for (int _i = 0; _i < 2; ++_i) \
;         __builtin_amdgcn_global_load_lds((const unsigned*)((const char*)(gbase) + (voff)[_i]), (LAS unsigned*)(lds + (bufoff) + ldsw + _i * 8192), 16, 0, 0); } while (0)
; #define PG8_LDA(dst, b, h) do { _Pragma("unroll") for (int m = 0; m < 4; ++m) _Pragma("unroll") for (int k = 0; k < 2; ++k) dst[m][k] = *(const LAS bf16x8*)(lds + PG8_SA(b, h) + aoff + m * 2048 + k * 1024); } while (0)
; #define PG8_LDB(dst, b, h) do { _Pragma("unroll") for (int n = 0; n < 2; ++n) _Pragma("unroll") for (int k = 0; k < 2; ++k) dst[n][k] = *(const LAS bf16x8*)(lds + PG8_SB(b, h) + boff + n * 2048 + k * 1024); } while (0)
; #define PG8_MMA(ai, bj, At, Bt) do { __builtin_amdgcn_s_setprio(1); _Pragma("unroll") for (int m = 0; m < 4; ++m) _Pragma("unroll") for (int n = 0; n < 2; ++n) _Pragma("unroll") for (int k = 0; k < 2; ++k) \
;         acc[ai][bj][m][n] = __builtin_amdgcn_mfma_f32_16x16x32_bf16(Bt[n][k], At[m][k], acc[ai][bj][m][n], 0, 0, 0); __builtin_amdgcn_s_setprio(0); } while (0)
; #define PG8_WAIT_V(n) asm volatile("s_waitcnt vmcnt(" #n ")" ::: "memory")
; #define PG8_WAIT_L(n) asm volatile("s_waitcnt lgkmcnt(" #n ")" ::: "memory")
; #define PG8_BAR __builtin_amdgcn_s_barrier()
; #define PG8_SCHED __builtin_amdgcn_sched_barrier(0)
; template <class Epi>
; __device__ __forceinline__ void gemm_phase(LAS unsigned char* lds, const Gemm g, const Sched& S, const Epi& E) {
;     ...
;             const bool last = (t == nt - 2);
;             const char* a1 = cA + (size_t)(t + 1) * kstep;
;             const char* a2 = last ? nA : cA + (size_t)(t + 2) * kstep; const char* b2 = last ? nB : cB + (size_t)(t + 2) * kstep;
;             const char* a3 = a2 + kstep; const char* b3 = b2 + kstep;
;             PG8_LDB(B0, 0, 0); PG8_LDB(B1, 0, 1); PG8_SCHED; PG8_LDA(At, 0, 0); PG8_STAGE(PG8_SA(1, 1), a1 + hstepA, voffA);
;             PG8_WAIT_V(8); PG8_WAIT_L(0); PG8_BAR; PG8_MMA(0, 0, At, B0); PG8_MMA(0, 1, At, B1); PG8_BAR; PG8_SCHED;
;             PG8_LDA(At, 0, 1); PG8_STAGE(PG8_SB(0, 0), b2, voffB); PG8_STAGE(PG8_SB(0, 1), b2 + hstepB, voffB); PG8_STAGE(PG8_SA(0, 0), a2, voffA);
;             PG8_WAIT_V(8); PG8_WAIT_L(0); PG8_BAR; PG8_MMA(1, 0, At, B0); PG8_MMA(1, 1, At, B1); PG8_BAR; PG8_SCHED;
.LBB0_1214:
	v_add_u32_e32 v158, s58, v144
	v_add_u32_e32 v174, s59, v144
	s_add_u32 s46, s40, s44
	ds_read_b128 v[146:149], v158
	ds_read_b128 v[150:153], v158 offset:1024
	ds_read_b128 v[154:157], v158 offset:2048
	ds_read_b128 v[158:161], v158 offset:3072
	ds_read_b128 v[162:165], v174
	ds_read_b128 v[166:169], v174 offset:1024
	ds_read_b128 v[170:173], v174 offset:2048
	ds_read_b128 v[174:177], v174 offset:3072
	s_addc_u32 s47, s41, s45
	s_add_u32 s46, s46, 0x100
	s_addc_u32 s47, s47, 0
	s_add_u32 s67, s62, s44
	s_addc_u32 s68, s63, s45
	s_cmpk_eq_i32 s44, 0x700
	s_cselect_b32 s49, s25, s47
	s_cselect_b32 s48, s64, s46
	s_cselect_b32 s47, s27, s68
	s_cselect_b32 s46, s65, s67
	v_lshl_add_u64 v[186:187], v[140:141], 0, s[44:45]
	s_add_i32 m0, s51, 0xc000
	ds_read_b128 v[178:181], v145
	ds_read_b128 v[182:185], v145 offset:1024
	ds_read_b128 v[192:195], v145 offset:2048
	ds_read_b128 v[196:199], v145 offset:3072
	ds_read_b128 v[204:207], v145 offset:4096
	ds_read_b128 v[208:211], v145 offset:5120
	ds_read_b128 v[212:215], v145 offset:6144
	ds_read_b128 v[216:219], v145 offset:7168
	global_load_lds_dwordx4 v[186:187], off
	v_lshl_add_u64 v[186:187], v[142:143], 0, s[44:45]
	s_add_i32 m0, s51, 0xe000
	s_nop 0
	global_load_lds_dwordx4 v[186:187], off
	s_waitcnt vmcnt(8)
	s_waitcnt lgkmcnt(0)
	s_barrier
	s_setprio 1
	s_waitcnt lgkmcnt(0)
	v_mfma_f32_16x16x32_bf16 v[124:127], v[146:149], v[178:181], v[124:127]
	v_mfma_f32_16x16x32_bf16 v[120:123], v[154:157], v[178:181], v[120:123]
	v_mfma_f32_16x16x32_bf16 v[108:111], v[146:149], v[192:195], v[108:111]
	v_mfma_f32_16x16x32_bf16 v[104:107], v[154:157], v[192:195], v[104:107]
	v_mfma_f32_16x16x32_bf16 v[92:95], v[146:149], v[204:207], v[92:95]
	v_mfma_f32_16x16x32_bf16 v[88:91], v[154:157], v[204:207], v[88:91]
	v_mfma_f32_16x16x32_bf16 v[76:79], v[146:149], v[212:215], v[76:79]
	v_mfma_f32_16x16x32_bf16 v[72:75], v[154:157], v[212:215], v[72:75]
	v_mfma_f32_16x16x32_bf16 v[124:127], v[150:153], v[182:185], v[124:127]
	v_mfma_f32_16x16x32_bf16 v[120:123], v[158:161], v[182:185], v[120:123]
	v_mfma_f32_16x16x32_bf16 v[108:111], v[150:153], v[196:199], v[108:111]
	v_mfma_f32_16x16x32_bf16 v[104:107], v[158:161], v[196:199], v[104:107]
	v_mfma_f32_16x16x32_bf16 v[92:95], v[150:153], v[208:211], v[92:95]
	v_mfma_f32_16x16x32_bf16 v[88:91], v[158:161], v[208:211], v[88:91]
	v_mfma_f32_16x16x32_bf16 v[76:79], v[150:153], v[216:219], v[76:79]
	v_mfma_f32_16x16x32_bf16 v[72:75], v[158:161], v[216:219], v[72:75]
	v_mfma_f32_16x16x32_bf16 v[116:119], v[162:165], v[178:181], v[116:119]
	v_mfma_f32_16x16x32_bf16 v[112:115], v[170:173], v[178:181], v[112:115]
	v_mfma_f32_16x16x32_bf16 v[100:103], v[162:165], v[192:195], v[100:103]
	v_mfma_f32_16x16x32_bf16 v[96:99], v[170:173], v[192:195], v[96:99]
	v_mfma_f32_16x16x32_bf16 v[84:87], v[162:165], v[204:207], v[84:87]
	v_mfma_f32_16x16x32_bf16 v[80:83], v[170:173], v[204:207], v[80:83]
	v_mfma_f32_16x16x32_bf16 v[68:71], v[162:165], v[212:215], v[68:71]
	v_mfma_f32_16x16x32_bf16 v[64:67], v[170:173], v[212:215], v[64:67]
	v_mfma_f32_16x16x32_bf16 v[116:119], v[166:169], v[182:185], v[116:119]
	v_mfma_f32_16x16x32_bf16 v[112:115], v[174:177], v[182:185], v[112:115]
	v_mfma_f32_16x16x32_bf16 v[100:103], v[166:169], v[196:199], v[100:103]
	v_mfma_f32_16x16x32_bf16 v[96:99], v[174:177], v[196:199], v[96:99]
	v_mfma_f32_16x16x32_bf16 v[84:87], v[166:169], v[208:211], v[84:87]
	v_mfma_f32_16x16x32_bf16 v[80:83], v[174:177], v[208:211], v[80:83]
	v_mfma_f32_16x16x32_bf16 v[68:71], v[166:169], v[216:219], v[68:71]
	v_mfma_f32_16x16x32_bf16 v[64:67], v[174:177], v[216:219], v[64:67]
	s_setprio 0
	s_barrier
	s_add_i32 s67, s58, s50
	v_lshl_add_u64 v[186:187], s[46:47], 0, v[130:131]
	s_mov_b32 m0, s67
	ds_read_b128 v[178:181], v145 offset:16384
	ds_read_b128 v[182:185], v145 offset:17408
	ds_read_b128 v[192:195], v145 offset:18432
	ds_read_b128 v[196:199], v145 offset:19456
	ds_read_b128 v[204:207], v145 offset:20480
	ds_read_b128 v[208:211], v145 offset:21504
	ds_read_b128 v[212:215], v145 offset:22528
	ds_read_b128 v[216:219], v145 offset:23552
	global_load_lds_dwordx4 v[186:187], off
	s_add_i32 m0, s67, 0x2000
	s_add_u32 s68, s46, 0x40000
	v_lshl_add_u64 v[200:201], s[46:47], 0, v[134:135]
	s_addc_u32 s69, s47, 0
	s_add_i32 s67, s59, s50
	global_load_lds_dwordx4 v[200:201], off
	v_lshl_add_u64 v[220:221], s[68:69], 0, v[130:131]
	s_mov_b32 m0, s67
	v_lshl_add_u64 v[222:223], s[48:49], 0, v[132:133]
	global_load_lds_dwordx4 v[220:221], off
	v_lshl_add_u64 v[220:221], s[68:69], 0, v[134:135]
	s_add_i32 m0, s67, 0x2000
	s_nop 0
	global_load_lds_dwordx4 v[220:221], off
	v_lshl_add_u64 v[220:221], s[48:49], 0, v[128:129]
	s_mov_b32 m0, s51
	s_nop 0
	global_load_lds_dwordx4 v[220:221], off
	s_mov_b32 m0, s52
	s_nop 0
	global_load_lds_dwordx4 v[222:223], off
	s_waitcnt vmcnt(8)
	s_waitcnt lgkmcnt(0)
	s_barrier
; #define PG8_STAGE(bufoff, gbase, voff) do { _Pragma("unroll") for (int _i = 0; _i < 2; ++_i) \
;         __builtin_amdgcn_global_load_lds((const unsigned*)((const char*)(gbase) + (voff)[_i]), (LAS unsigned*)(lds + (bufoff) + ldsw + _i * 8192), 16, 0, 0); } while (0)
; #define PG8_LDA(dst, b, h) do { _Pragma("unroll") for (int m = 0; m < 4; ++m) _Pragma("unroll") for (int k = 0; k < 2; ++k) dst[m][k] = *(const LAS bf16x8*)(lds + PG8_SA(b, h) + aoff + m * 2048 + k * 1024); } while (0)
; #define PG8_LDB(dst, b, h) do { _Pragma("unroll") for (int n = 0; n < 2; ++n) _Pragma("unroll") for (int k = 0; k < 2; ++k) dst[n][k] = *(const LAS bf16x8*)(lds + PG8_SB(b, h) + boff + n * 2048 + k * 1024); } while (0)
; #define PG8_MMA(ai, bj, At, Bt) do { __builtin_amdgcn_s_setprio(1); _Pragma("unroll") for (int m = 0; m < 4; ++m) _Pragma("unroll") for (int n = 0; n < 2; ++n) _Pragma("unroll") for (int k = 0; k < 2; ++k) \
;         acc[ai][bj][m][n] = __builtin_amdgcn_mfma_f32_16x16x32_bf16(Bt[n][k], At[m][k], acc[ai][bj][m][n], 0, 0, 0); __builtin_amdgcn_s_setprio(0); } while (0)
; #define PG8_WAIT_V(n) asm volatile("s_waitcnt vmcnt(" #n ")" ::: "memory")
; #define PG8_WAIT_L(n) asm volatile("s_waitcnt lgkmcnt(" #n ")" ::: "memory")
; #define PG8_BAR __builtin_amdgcn_s_barrier()
; #define PG8_SCHED __builtin_amdgcn_sched_barrier(0)
; template <class Epi>
; __device__ __forceinline__ void gemm_phase(LAS unsigned char* lds, const Gemm g, const Sched& S, const Epi& E) {
;     ...
;             PG8_WAIT_V(8); PG8_WAIT_L(0); PG8_BAR; PG8_MMA(1, 0, At, B0); PG8_MMA(1, 1, At, B1); PG8_BAR; PG8_SCHED;
;             PG8_LDB(B0, 1, 0); PG8_LDB(B1, 1, 1); PG8_SCHED; PG8_LDA(At, 1, 0); PG8_STAGE(PG8_SA(0, 1), a2 + hstepA, voffA);
;             PG8_WAIT_V(8); PG8_WAIT_L(0); PG8_BAR; PG8_MMA(0, 0, At, B0); PG8_MMA(0, 1, At, B1); PG8_BAR; PG8_SCHED;
	s_setprio 1
	s_waitcnt lgkmcnt(0)
	v_mfma_f32_16x16x32_bf16 v[60:63], v[146:149], v[178:181], v[60:63]
	v_mfma_f32_16x16x32_bf16 v[56:59], v[154:157], v[178:181], v[56:59]
	v_mfma_f32_16x16x32_bf16 v[44:47], v[146:149], v[192:195], v[44:47]
	v_mfma_f32_16x16x32_bf16 v[40:43], v[154:157], v[192:195], v[40:43]
	v_mfma_f32_16x16x32_bf16 v[28:31], v[146:149], v[204:207], v[28:31]
	v_mfma_f32_16x16x32_bf16 v[24:27], v[154:157], v[204:207], v[24:27]
	v_mfma_f32_16x16x32_bf16 v[12:15], v[146:149], v[212:215], v[12:15]
	v_mfma_f32_16x16x32_bf16 v[8:11], v[154:157], v[212:215], v[8:11]
	v_mfma_f32_16x16x32_bf16 v[60:63], v[150:153], v[182:185], v[60:63]
	v_mfma_f32_16x16x32_bf16 v[56:59], v[158:161], v[182:185], v[56:59]
	v_mfma_f32_16x16x32_bf16 v[44:47], v[150:153], v[196:199], v[44:47]
	v_mfma_f32_16x16x32_bf16 v[40:43], v[158:161], v[196:199], v[40:43]
	v_mfma_f32_16x16x32_bf16 v[28:31], v[150:153], v[208:211], v[28:31]
	v_mfma_f32_16x16x32_bf16 v[24:27], v[158:161], v[208:211], v[24:27]
	v_mfma_f32_16x16x32_bf16 v[12:15], v[150:153], v[216:219], v[12:15]
	v_mfma_f32_16x16x32_bf16 v[8:11], v[158:161], v[216:219], v[8:11]
	v_mfma_f32_16x16x32_bf16 v[52:55], v[162:165], v[178:181], v[52:55]
	v_mfma_f32_16x16x32_bf16 v[48:51], v[170:173], v[178:181], v[48:51]
	v_mfma_f32_16x16x32_bf16 v[36:39], v[162:165], v[192:195], v[36:39]
	v_mfma_f32_16x16x32_bf16 v[32:35], v[170:173], v[192:195], v[32:35]
	v_mfma_f32_16x16x32_bf16 v[20:23], v[162:165], v[204:207], v[20:23]
	v_mfma_f32_16x16x32_bf16 v[16:19], v[170:173], v[204:207], v[16:19]
	v_mfma_f32_16x16x32_bf16 v[4:7], v[162:165], v[212:215], v[4:7]
	v_mfma_f32_16x16x32_bf16 v[0:3], v[170:173], v[212:215], v[0:3]
	v_mfma_f32_16x16x32_bf16 v[52:55], v[166:169], v[182:185], v[52:55]
	v_mfma_f32_16x16x32_bf16 v[48:51], v[174:177], v[182:185], v[48:51]
	v_mfma_f32_16x16x32_bf16 v[36:39], v[166:169], v[196:199], v[36:39]
	v_mfma_f32_16x16x32_bf16 v[32:35], v[174:177], v[196:199], v[32:35]
	v_mfma_f32_16x16x32_bf16 v[20:23], v[166:169], v[208:211], v[20:23]
	v_mfma_f32_16x16x32_bf16 v[16:19], v[174:177], v[208:211], v[16:19]
	v_mfma_f32_16x16x32_bf16 v[4:7], v[166:169], v[216:219], v[4:7]
	v_mfma_f32_16x16x32_bf16 v[0:3], v[174:177], v[216:219], v[0:3]
	s_setprio 0
	s_barrier
	s_add_i32 s67, 0, 0x18000
	s_add_i32 s68, 0, 0x1c000
	v_add_u32_e32 v158, s67, v144
	v_add_u32_e32 v174, s68, v144
	ds_read_b128 v[146:149], v158
	ds_read_b128 v[150:153], v158 offset:1024
	ds_read_b128 v[154:157], v158 offset:2048
	ds_read_b128 v[158:161], v158 offset:3072
	ds_read_b128 v[162:165], v174
	ds_read_b128 v[166:169], v174 offset:1024
	ds_read_b128 v[170:173], v174 offset:2048
	ds_read_b128 v[174:177], v174 offset:3072
	s_add_u32 s48, s48, 0x40000
	s_addc_u32 s49, s49, 0
	s_mov_b32 m0, s53
	v_lshl_add_u64 v[224:225], s[48:49], 0, v[128:129]
	ds_read_b128 v[178:181], v145 offset:32768
	ds_read_b128 v[182:185], v145 offset:33792
	ds_read_b128 v[192:195], v145 offset:34816
	ds_read_b128 v[196:199], v145 offset:35840
	ds_read_b128 v[204:207], v145 offset:36864
	ds_read_b128 v[208:211], v145 offset:37888
	ds_read_b128 v[212:215], v145 offset:38912
	ds_read_b128 v[216:219], v145 offset:39936
	global_load_lds_dwordx4 v[224:225], off
	v_lshl_add_u64 v[224:225], s[48:49], 0, v[132:133]
	s_mov_b32 m0, s54
	s_nop 0
	global_load_lds_dwordx4 v[224:225], off
	s_waitcnt vmcnt(8)
	s_waitcnt lgkmcnt(0)
	s_barrier
	s_setprio 1
	s_waitcnt lgkmcnt(0)
	v_mfma_f32_16x16x32_bf16 v[124:127], v[146:149], v[178:181], v[124:127]
	v_mfma_f32_16x16x32_bf16 v[120:123], v[154:157], v[178:181], v[120:123]
	v_mfma_f32_16x16x32_bf16 v[108:111], v[146:149], v[192:195], v[108:111]
	v_mfma_f32_16x16x32_bf16 v[104:107], v[154:157], v[192:195], v[104:107]
	v_mfma_f32_16x16x32_bf16 v[92:95], v[146:149], v[204:207], v[92:95]
	v_mfma_f32_16x16x32_bf16 v[88:91], v[154:157], v[204:207], v[88:91]
	v_mfma_f32_16x16x32_bf16 v[76:79], v[146:149], v[212:215], v[76:79]
	v_mfma_f32_16x16x32_bf16 v[72:75], v[154:157], v[212:215], v[72:75]
	v_mfma_f32_16x16x32_bf16 v[124:127], v[150:153], v[182:185], v[124:127]
	v_mfma_f32_16x16x32_bf16 v[120:123], v[158:161], v[182:185], v[120:123]
	v_mfma_f32_16x16x32_bf16 v[108:111], v[150:153], v[196:199], v[108:111]
	v_mfma_f32_16x16x32_bf16 v[104:107], v[158:161], v[196:199], v[104:107]
	v_mfma_f32_16x16x32_bf16 v[92:95], v[150:153], v[208:211], v[92:95]
	v_mfma_f32_16x16x32_bf16 v[88:91], v[158:161], v[208:211], v[88:91]
	v_mfma_f32_16x16x32_bf16 v[76:79], v[150:153], v[216:219], v[76:79]
	v_mfma_f32_16x16x32_bf16 v[72:75], v[158:161], v[216:219], v[72:75]
	v_mfma_f32_16x16x32_bf16 v[116:119], v[162:165], v[178:181], v[116:119]
	v_mfma_f32_16x16x32_bf16 v[112:115], v[170:173], v[178:181], v[112:115]
	v_mfma_f32_16x16x32_bf16 v[100:103], v[162:165], v[192:195], v[100:103]
	v_mfma_f32_16x16x32_bf16 v[96:99], v[170:173], v[192:195], v[96:99]
	v_mfma_f32_16x16x32_bf16 v[84:87], v[162:165], v[204:207], v[84:87]
	v_mfma_f32_16x16x32_bf16 v[80:83], v[170:173], v[204:207], v[80:83]
	v_mfma_f32_16x16x32_bf16 v[68:71], v[162:165], v[212:215], v[68:71]
	v_mfma_f32_16x16x32_bf16 v[64:67], v[170:173], v[212:215], v[64:67]
	v_mfma_f32_16x16x32_bf16 v[116:119], v[166:169], v[182:185], v[116:119]
	v_mfma_f32_16x16x32_bf16 v[112:115], v[174:177], v[182:185], v[112:115]
	v_mfma_f32_16x16x32_bf16 v[100:103], v[166:169], v[196:199], v[100:103]
	v_mfma_f32_16x16x32_bf16 v[96:99], v[174:177], v[196:199], v[96:99]
	v_mfma_f32_16x16x32_bf16 v[84:87], v[166:169], v[208:211], v[84:87]
	v_mfma_f32_16x16x32_bf16 v[80:83], v[174:177], v[208:211], v[80:83]
	v_mfma_f32_16x16x32_bf16 v[68:71], v[166:169], v[216:219], v[68:71]
	v_mfma_f32_16x16x32_bf16 v[64:67], v[174:177], v[216:219], v[64:67]
	s_setprio 0
	s_barrier
; #define PG8_STAGE(bufoff, gbase, voff) do { _Pragma("unroll") for (int _i = 0; _i < 2; ++_i) \
;         __builtin_amdgcn_global_load_lds((const unsigned*)((const char*)(gbase) + (voff)[_i]), (LAS unsigned*)(lds + (bufoff) + ldsw + _i * 8192), 16, 0, 0); } while (0)
; #define PG8_LDA(dst, b, h) do { _Pragma("unroll") for (int m = 0; m < 4; ++m) _Pragma("unroll") for (int k = 0; k < 2; ++k) dst[m][k] = *(const LAS bf16x8*)(lds + PG8_SA(b, h) + aoff + m * 2048 + k * 1024); } while (0)
; #define PG8_MMA(ai, bj, At, Bt) do { __builtin_amdgcn_s_setprio(1); _Pragma("unroll") for (int m = 0; m < 4; ++m) _Pragma("unroll") for (int n = 0; n < 2; ++n) _Pragma("unroll") for (int k = 0; k < 2; ++k) \
;         acc[ai][bj][m][n] = __builtin_amdgcn_mfma_f32_16x16x32_bf16(Bt[n][k], At[m][k], acc[ai][bj][m][n], 0, 0, 0); __builtin_amdgcn_s_setprio(0); } while (0)
; #define PG8_WAIT_V(n) asm volatile("s_waitcnt vmcnt(" #n ")" ::: "memory")
; #define PG8_WAIT_L(n) asm volatile("s_waitcnt lgkmcnt(" #n ")" ::: "memory")
; #define PG8_BAR __builtin_amdgcn_s_barrier()
; #define PG8_SCHED __builtin_amdgcn_sched_barrier(0)
; template <class Epi>
; __device__ __forceinline__ void gemm_phase(LAS unsigned char* lds, const Gemm g, const Sched& S, const Epi& E) {
;     ...
;             PG8_LDA(At, 1, 1); PG8_STAGE(PG8_SB(1, 0), b3, voffB); PG8_STAGE(PG8_SB(1, 1), b3 + hstepB, voffB); PG8_STAGE(PG8_SA(1, 0), a3, voffA);
;             PG8_WAIT_V(8); PG8_WAIT_L(0); PG8_BAR; PG8_MMA(1, 0, At, B0); PG8_MMA(1, 1, At, B1); PG8_BAR; PG8_SCHED;
;         }
;         if (wr == 0) PG8_BAR;
	s_add_i32 s48, s67, s50
	v_lshl_add_u64 v[186:187], v[186:187], 0, s[4:5]
	s_mov_b32 m0, s48
	ds_read_b128 v[178:181], v145 offset:49152
	ds_read_b128 v[182:185], v145 offset:50176
	ds_read_b128 v[192:195], v145 offset:51200
	ds_read_b128 v[196:199], v145 offset:52224
	ds_read_b128 v[204:207], v145 offset:53248
	ds_read_b128 v[208:211], v145 offset:54272
	ds_read_b128 v[212:215], v145 offset:55296
	ds_read_b128 v[216:219], v145 offset:56320
	global_load_lds_dwordx4 v[186:187], off
	s_add_i32 m0, s48, 0x2000
	s_add_u32 s46, s46, 0x40080
	v_lshl_add_u64 v[186:187], v[200:201], 0, s[4:5]
	s_addc_u32 s47, s47, 0
	s_add_i32 s48, s68, s50
	global_load_lds_dwordx4 v[186:187], off
	v_lshl_add_u64 v[186:187], s[46:47], 0, v[130:131]
	s_mov_b32 m0, s48
	s_nop 0
	global_load_lds_dwordx4 v[186:187], off
	v_lshl_add_u64 v[186:187], s[46:47], 0, v[134:135]
	s_add_i32 m0, s48, 0x2000
	s_nop 0
	global_load_lds_dwordx4 v[186:187], off
	v_lshl_add_u64 v[186:187], v[220:221], 0, s[4:5]
	s_mov_b32 m0, s56
	s_nop 0
	global_load_lds_dwordx4 v[186:187], off
	v_lshl_add_u64 v[186:187], v[222:223], 0, s[4:5]
	s_mov_b32 m0, s57
	s_nop 0
	global_load_lds_dwordx4 v[186:187], off
	s_waitcnt vmcnt(8)
	s_waitcnt lgkmcnt(0)
	s_barrier
	s_setprio 1
	s_waitcnt lgkmcnt(0)
	v_mfma_f32_16x16x32_bf16 v[60:63], v[146:149], v[178:181], v[60:63]
	v_mfma_f32_16x16x32_bf16 v[56:59], v[154:157], v[178:181], v[56:59]
	v_mfma_f32_16x16x32_bf16 v[44:47], v[146:149], v[192:195], v[44:47]
	v_mfma_f32_16x16x32_bf16 v[40:43], v[154:157], v[192:195], v[40:43]
	v_mfma_f32_16x16x32_bf16 v[28:31], v[146:149], v[204:207], v[28:31]
	v_mfma_f32_16x16x32_bf16 v[24:27], v[154:157], v[204:207], v[24:27]
	v_mfma_f32_16x16x32_bf16 v[12:15], v[146:149], v[212:215], v[12:15]
	v_mfma_f32_16x16x32_bf16 v[8:11], v[154:157], v[212:215], v[8:11]
	v_mfma_f32_16x16x32_bf16 v[60:63], v[150:153], v[182:185], v[60:63]
	v_mfma_f32_16x16x32_bf16 v[56:59], v[158:161], v[182:185], v[56:59]
	v_mfma_f32_16x16x32_bf16 v[44:47], v[150:153], v[196:199], v[44:47]
	v_mfma_f32_16x16x32_bf16 v[40:43], v[158:161], v[196:199], v[40:43]
	v_mfma_f32_16x16x32_bf16 v[28:31], v[150:153], v[208:211], v[28:31]
	v_mfma_f32_16x16x32_bf16 v[24:27], v[158:161], v[208:211], v[24:27]
	v_mfma_f32_16x16x32_bf16 v[12:15], v[150:153], v[216:219], v[12:15]
	v_mfma_f32_16x16x32_bf16 v[8:11], v[158:161], v[216:219], v[8:11]
	v_mfma_f32_16x16x32_bf16 v[52:55], v[162:165], v[178:181], v[52:55]
	v_mfma_f32_16x16x32_bf16 v[48:51], v[170:173], v[178:181], v[48:51]
	v_mfma_f32_16x16x32_bf16 v[36:39], v[162:165], v[192:195], v[36:39]
	v_mfma_f32_16x16x32_bf16 v[32:35], v[170:173], v[192:195], v[32:35]
	v_mfma_f32_16x16x32_bf16 v[20:23], v[162:165], v[204:207], v[20:23]
	v_mfma_f32_16x16x32_bf16 v[16:19], v[170:173], v[204:207], v[16:19]
	v_mfma_f32_16x16x32_bf16 v[4:7], v[162:165], v[212:215], v[4:7]
	v_mfma_f32_16x16x32_bf16 v[0:3], v[170:173], v[212:215], v[0:3]
	v_mfma_f32_16x16x32_bf16 v[52:55], v[166:169], v[182:185], v[52:55]
	v_mfma_f32_16x16x32_bf16 v[48:51], v[174:177], v[182:185], v[48:51]
	v_mfma_f32_16x16x32_bf16 v[36:39], v[166:169], v[196:199], v[36:39]
	v_mfma_f32_16x16x32_bf16 v[32:35], v[174:177], v[196:199], v[32:35]
	v_mfma_f32_16x16x32_bf16 v[20:23], v[166:169], v[208:211], v[20:23]
	v_mfma_f32_16x16x32_bf16 v[16:19], v[174:177], v[208:211], v[16:19]
	v_mfma_f32_16x16x32_bf16 v[4:7], v[166:169], v[216:219], v[4:7]
	v_mfma_f32_16x16x32_bf16 v[0:3], v[174:177], v[216:219], v[0:3]
	s_setprio 0
	s_barrier
	s_add_i32 s66, s66, 2
	s_add_u32 s44, s44, 0x100
	s_addc_u32 s45, s45, 0
	s_cmp_gt_u32 s66, 13
	s_cbranch_scc0 .LBB0_1214
	s_and_b64 vcc, exec, s[22:23]
	s_cbranch_vccz .LBB0_1217
	s_barrier

; #define PG8_STAGE(bufoff, gbase, voff) do { _Pragma("unroll") for (int _i = 0; _i < 2; ++_i) \
;         __builtin_amdgcn_global_load_lds((const unsigned*)((const char*)(gbase) + (voff)[_i]), (LAS unsigned*)(lds + (bufoff) + ldsw + _i * 8192), 16, 0, 0); } while (0)
; #define PG8_LDA(dst, b, h) do { _Pragma("unroll") for (int m = 0; m < 4; ++m) _Pragma("unroll") for (int k = 0; k < 2; ++k) dst[m][k] = *(const LAS bf16x8*)(lds + PG8_SA(b, h) + aoff + m * 2048 + k * 1024); } while (0)
; #define PG8_LDB(dst, b, h) do { _Pragma("unroll") for (int n = 0; n < 2; ++n) _Pragma("unroll") for (int k = 0; k < 2; ++k) dst[n][k] = *(const LAS bf16x8*)(lds + PG8_SB(b, h) + boff + n * 2048 + k * 1024); } while (0)
; #define PG8_MMA(ai, bj, At, Bt) do { __builtin_amdgcn_s_setprio(1); _Pragma("unroll") for (int m = 0; m < 4; ++m) _Pragma("unroll") for (int n = 0; n < 2; ++n) _Pragma("unroll") for (int k = 0; k < 2; ++k) \
;         acc[ai][bj][m][n] = __builtin_amdgcn_mfma_f32_16x16x32_bf16(Bt[n][k], At[m][k], acc[ai][bj][m][n], 0, 0, 0); __builtin_amdgcn_s_setprio(0); } while (0)
; #define PG8_WAIT_V(n) asm volatile("s_waitcnt vmcnt(" #n ")" ::: "memory")
; #define PG8_WAIT_L(n) asm volatile("s_waitcnt lgkmcnt(" #n ")" ::: "memory")
; #define PG8_BAR __builtin_amdgcn_s_barrier()
; #define PG8_SCHED __builtin_amdgcn_sched_barrier(0)
; template <class Epi>
; __device__ __forceinline__ void gemm_phase(LAS unsigned char* lds, const Gemm g, const Sched& S, const Epi& E) {
;     ...
;             const bool last = (t == nt - 2);
;             const char* a1 = cA + (size_t)(t + 1) * kstep;
;             const char* a2 = last ? nA : cA + (size_t)(t + 2) * kstep; const char* b2 = last ? nB : cB + (size_t)(t + 2) * kstep;
;             const char* a3 = a2 + kstep; const char* b3 = b2 + kstep;
;             PG8_LDB(B0, 0, 0); PG8_LDB(B1, 0, 1); PG8_SCHED; PG8_LDA(At, 0, 0); PG8_STAGE(PG8_SA(1, 1), a1 + hstepA, voffA);
;             PG8_WAIT_V(8); PG8_WAIT_L(0); PG8_BAR; PG8_MMA(0, 0, At, B0); PG8_MMA(0, 1, At, B1); PG8_BAR; PG8_SCHED;
;             PG8_LDA(At, 0, 1); PG8_STAGE(PG8_SB(0, 0), b2, voffB); PG8_STAGE(PG8_SB(0, 1), b2 + hstepB, voffB); PG8_STAGE(PG8_SA(0, 0), a2, voffA);
;             PG8_WAIT_V(8); PG8_WAIT_L(0); PG8_BAR; PG8_MMA(1, 0, At, B0); PG8_MMA(1, 1, At, B1); PG8_BAR; PG8_SCHED;
.LBB0_1355:
	ds_read_b128 v[140:143], v148
	ds_read_b128 v[152:155], v148 offset:1024
	ds_read_b128 v[156:159], v148 offset:2048
	ds_read_b128 v[160:163], v148 offset:3072
	ds_read_b128 v[164:167], v149
	ds_read_b128 v[168:171], v149 offset:1024
	ds_read_b128 v[172:175], v149 offset:2048
	ds_read_b128 v[176:179], v149 offset:3072
	s_add_u32 s40, s38, 0xfffc0080
	s_addc_u32 s41, s39, -1
	s_cmp_eq_u32 s54, 12
	s_cselect_b32 s43, s23, s41
	s_cselect_b32 s42, s50, s40
	s_cselect_b32 s41, s25, s53
	s_cselect_b32 s40, s51, s52
	v_lshl_add_u64 v[200:201], s[38:39], 0, v[136:137]
	s_add_i32 m0, s11, 0xc000
	ds_read_b128 v[180:183], v150
	ds_read_b128 v[184:187], v150 offset:1024
	ds_read_b128 v[188:191], v150 offset:2048
	ds_read_b128 v[192:195], v150 offset:3072
	ds_read_b128 v[196:199], v150 offset:4096
	ds_read_b128 v[204:207], v150 offset:5120
	ds_read_b128 v[208:211], v150 offset:6144
	ds_read_b128 v[212:215], v150 offset:7168
	global_load_lds_dwordx4 v[200:201], off
	v_lshl_add_u64 v[200:201], s[38:39], 0, v[138:139]
	s_add_i32 m0, s11, 0xe000
	s_nop 0
	global_load_lds_dwordx4 v[200:201], off
	s_waitcnt vmcnt(8)
	s_waitcnt lgkmcnt(0)
	s_barrier
	s_setprio 1
	s_waitcnt lgkmcnt(0)
	v_mfma_f32_16x16x32_bf16 v[124:127], v[140:143], v[180:183], v[124:127]
	v_mfma_f32_16x16x32_bf16 v[120:123], v[156:159], v[180:183], v[120:123]
	v_mfma_f32_16x16x32_bf16 v[116:119], v[140:143], v[188:191], v[116:119]
	v_mfma_f32_16x16x32_bf16 v[108:111], v[156:159], v[188:191], v[108:111]
	v_mfma_f32_16x16x32_bf16 v[100:103], v[140:143], v[196:199], v[100:103]
	v_mfma_f32_16x16x32_bf16 v[92:95], v[156:159], v[196:199], v[92:95]
	v_mfma_f32_16x16x32_bf16 v[84:87], v[140:143], v[208:211], v[84:87]
	v_mfma_f32_16x16x32_bf16 v[76:79], v[156:159], v[208:211], v[76:79]
	v_mfma_f32_16x16x32_bf16 v[124:127], v[152:155], v[184:187], v[124:127]
	v_mfma_f32_16x16x32_bf16 v[120:123], v[160:163], v[184:187], v[120:123]
	v_mfma_f32_16x16x32_bf16 v[116:119], v[152:155], v[192:195], v[116:119]
	v_mfma_f32_16x16x32_bf16 v[108:111], v[160:163], v[192:195], v[108:111]
	v_mfma_f32_16x16x32_bf16 v[100:103], v[152:155], v[204:207], v[100:103]
	v_mfma_f32_16x16x32_bf16 v[92:95], v[160:163], v[204:207], v[92:95]
	v_mfma_f32_16x16x32_bf16 v[84:87], v[152:155], v[212:215], v[84:87]
	v_mfma_f32_16x16x32_bf16 v[76:79], v[160:163], v[212:215], v[76:79]
	v_mfma_f32_16x16x32_bf16 v[112:115], v[164:167], v[180:183], v[112:115]
	v_mfma_f32_16x16x32_bf16 v[104:107], v[172:175], v[180:183], v[104:107]
	v_mfma_f32_16x16x32_bf16 v[96:99], v[164:167], v[188:191], v[96:99]
	v_mfma_f32_16x16x32_bf16 v[88:91], v[172:175], v[188:191], v[88:91]
	v_mfma_f32_16x16x32_bf16 v[80:83], v[164:167], v[196:199], v[80:83]
	v_mfma_f32_16x16x32_bf16 v[72:75], v[172:175], v[196:199], v[72:75]
	v_mfma_f32_16x16x32_bf16 v[68:71], v[164:167], v[208:211], v[68:71]
	v_mfma_f32_16x16x32_bf16 v[64:67], v[172:175], v[208:211], v[64:67]
	v_mfma_f32_16x16x32_bf16 v[112:115], v[168:171], v[184:187], v[112:115]
	v_mfma_f32_16x16x32_bf16 v[104:107], v[176:179], v[184:187], v[104:107]
	v_mfma_f32_16x16x32_bf16 v[96:99], v[168:171], v[192:195], v[96:99]
	v_mfma_f32_16x16x32_bf16 v[88:91], v[176:179], v[192:195], v[88:91]
	v_mfma_f32_16x16x32_bf16 v[80:83], v[168:171], v[204:207], v[80:83]
	v_mfma_f32_16x16x32_bf16 v[72:75], v[176:179], v[204:207], v[72:75]
	v_mfma_f32_16x16x32_bf16 v[68:71], v[168:171], v[212:215], v[68:71]
	v_mfma_f32_16x16x32_bf16 v[64:67], v[176:179], v[212:215], v[64:67]
	s_setprio 0
	s_barrier
	s_add_i32 s55, s47, s10
	v_lshl_add_u64 v[200:201], s[40:41], 0, v[130:131]
	s_mov_b32 m0, s55
	ds_read_b128 v[180:183], v150 offset:16384
	ds_read_b128 v[184:187], v150 offset:17408
	ds_read_b128 v[188:191], v150 offset:18432
	ds_read_b128 v[192:195], v150 offset:19456
	ds_read_b128 v[196:199], v150 offset:20480
	ds_read_b128 v[204:207], v150 offset:21504
	ds_read_b128 v[208:211], v150 offset:22528
	ds_read_b128 v[212:215], v150 offset:23552
	global_load_lds_dwordx4 v[200:201], off
	s_add_i32 m0, s55, 0x2000
	s_add_u32 s56, s40, 0x40000
	v_lshl_add_u64 v[216:217], s[40:41], 0, v[134:135]
	s_addc_u32 s57, s41, 0
	s_add_i32 s55, s48, s10
	global_load_lds_dwordx4 v[216:217], off
	v_lshl_add_u64 v[218:219], s[56:57], 0, v[130:131]
	s_mov_b32 m0, s55
	v_lshl_add_u64 v[220:221], s[42:43], 0, v[132:133]
	global_load_lds_dwordx4 v[218:219], off
	v_lshl_add_u64 v[218:219], s[56:57], 0, v[134:135]
	s_add_i32 m0, s55, 0x2000
	s_nop 0
	global_load_lds_dwordx4 v[218:219], off
	v_lshl_add_u64 v[218:219], s[42:43], 0, v[128:129]
	s_mov_b32 m0, s11
	s_nop 0
	global_load_lds_dwordx4 v[218:219], off
	s_mov_b32 m0, s13
	s_nop 0
	global_load_lds_dwordx4 v[220:221], off
	s_waitcnt vmcnt(8)
	s_waitcnt lgkmcnt(0)
	s_barrier
; #define PG8_STAGE(bufoff, gbase, voff) do { _Pragma("unroll") for (int _i = 0; _i < 2; ++_i) \
;         __builtin_amdgcn_global_load_lds((const unsigned*)((const char*)(gbase) + (voff)[_i]), (LAS unsigned*)(lds + (bufoff) + ldsw + _i * 8192), 16, 0, 0); } while (0)
; #define PG8_LDA(dst, b, h) do { _Pragma("unroll") for (int m = 0; m < 4; ++m) _Pragma("unroll") for (int k = 0; k < 2; ++k) dst[m][k] = *(const LAS bf16x8*)(lds + PG8_SA(b, h) + aoff + m * 2048 + k * 1024); } while (0)
; #define PG8_LDB(dst, b, h) do { _Pragma("unroll") for (int n = 0; n < 2; ++n) _Pragma("unroll") for (int k = 0; k < 2; ++k) dst[n][k] = *(const LAS bf16x8*)(lds + PG8_SB(b, h) + boff + n * 2048 + k * 1024); } while (0)
; #define PG8_MMA(ai, bj, At, Bt) do { __builtin_amdgcn_s_setprio(1); _Pragma("unroll") for (int m = 0; m < 4; ++m) _Pragma("unroll") for (int n = 0; n < 2; ++n) _Pragma("unroll") for (int k = 0; k < 2; ++k) \
;         acc[ai][bj][m][n] = __builtin_amdgcn_mfma_f32_16x16x32_bf16(Bt[n][k], At[m][k], acc[ai][bj][m][n], 0, 0, 0); __builtin_amdgcn_s_setprio(0); } while (0)
; #define PG8_WAIT_V(n) asm volatile("s_waitcnt vmcnt(" #n ")" ::: "memory")
; #define PG8_WAIT_L(n) asm volatile("s_waitcnt lgkmcnt(" #n ")" ::: "memory")
; #define PG8_BAR __builtin_amdgcn_s_barrier()
; #define PG8_SCHED __builtin_amdgcn_sched_barrier(0)
; template <class Epi>
; __device__ __forceinline__ void gemm_phase(LAS unsigned char* lds, const Gemm g, const Sched& S, const Epi& E) {
;     ...
;             PG8_WAIT_V(8); PG8_WAIT_L(0); PG8_BAR; PG8_MMA(1, 0, At, B0); PG8_MMA(1, 1, At, B1); PG8_BAR; PG8_SCHED;
;             PG8_LDB(B0, 1, 0); PG8_LDB(B1, 1, 1); PG8_SCHED; PG8_LDA(At, 1, 0); PG8_STAGE(PG8_SA(0, 1), a2 + hstepA, voffA);
;             PG8_WAIT_V(8); PG8_WAIT_L(0); PG8_BAR; PG8_MMA(0, 0, At, B0); PG8_MMA(0, 1, At, B1); PG8_BAR; PG8_SCHED;
	s_setprio 1
	s_waitcnt lgkmcnt(0)
	v_mfma_f32_16x16x32_bf16 v[60:63], v[140:143], v[180:183], v[60:63]
	v_mfma_f32_16x16x32_bf16 v[56:59], v[156:159], v[180:183], v[56:59]
	v_mfma_f32_16x16x32_bf16 v[52:55], v[140:143], v[188:191], v[52:55]
	v_mfma_f32_16x16x32_bf16 v[44:47], v[156:159], v[188:191], v[44:47]
	v_mfma_f32_16x16x32_bf16 v[36:39], v[140:143], v[196:199], v[36:39]
	v_mfma_f32_16x16x32_bf16 v[28:31], v[156:159], v[196:199], v[28:31]
	v_mfma_f32_16x16x32_bf16 v[20:23], v[140:143], v[208:211], v[20:23]
	v_mfma_f32_16x16x32_bf16 v[12:15], v[156:159], v[208:211], v[12:15]
	v_mfma_f32_16x16x32_bf16 v[60:63], v[152:155], v[184:187], v[60:63]
	v_mfma_f32_16x16x32_bf16 v[56:59], v[160:163], v[184:187], v[56:59]
	v_mfma_f32_16x16x32_bf16 v[52:55], v[152:155], v[192:195], v[52:55]
	v_mfma_f32_16x16x32_bf16 v[44:47], v[160:163], v[192:195], v[44:47]
	v_mfma_f32_16x16x32_bf16 v[36:39], v[152:155], v[204:207], v[36:39]
	v_mfma_f32_16x16x32_bf16 v[28:31], v[160:163], v[204:207], v[28:31]
	v_mfma_f32_16x16x32_bf16 v[20:23], v[152:155], v[212:215], v[20:23]
	v_mfma_f32_16x16x32_bf16 v[12:15], v[160:163], v[212:215], v[12:15]
	v_mfma_f32_16x16x32_bf16 v[48:51], v[164:167], v[180:183], v[48:51]
	v_mfma_f32_16x16x32_bf16 v[40:43], v[172:175], v[180:183], v[40:43]
	v_mfma_f32_16x16x32_bf16 v[32:35], v[164:167], v[188:191], v[32:35]
	v_mfma_f32_16x16x32_bf16 v[24:27], v[172:175], v[188:191], v[24:27]
	v_mfma_f32_16x16x32_bf16 v[16:19], v[164:167], v[196:199], v[16:19]
	v_mfma_f32_16x16x32_bf16 v[8:11], v[172:175], v[196:199], v[8:11]
	v_mfma_f32_16x16x32_bf16 v[4:7], v[164:167], v[208:211], v[4:7]
	v_mfma_f32_16x16x32_bf16 v[0:3], v[172:175], v[208:211], v[0:3]
	v_mfma_f32_16x16x32_bf16 v[48:51], v[168:171], v[184:187], v[48:51]
	v_mfma_f32_16x16x32_bf16 v[40:43], v[176:179], v[184:187], v[40:43]
	v_mfma_f32_16x16x32_bf16 v[32:35], v[168:171], v[192:195], v[32:35]
	v_mfma_f32_16x16x32_bf16 v[24:27], v[176:179], v[192:195], v[24:27]
	v_mfma_f32_16x16x32_bf16 v[16:19], v[168:171], v[204:207], v[16:19]
	v_mfma_f32_16x16x32_bf16 v[8:11], v[176:179], v[204:207], v[8:11]
	v_mfma_f32_16x16x32_bf16 v[4:7], v[168:171], v[212:215], v[4:7]
	v_mfma_f32_16x16x32_bf16 v[0:3], v[176:179], v[212:215], v[0:3]
	s_setprio 0
	s_barrier
	s_add_i32 s55, 0, 0x18000
	v_add_u32_e32 v151, s55, v146
	s_add_i32 s56, 0, 0x1c000
	ds_read_b128 v[140:143], v151
	ds_read_b128 v[152:155], v151 offset:1024
	ds_read_b128 v[156:159], v151 offset:2048
	ds_read_b128 v[160:163], v151 offset:3072
	v_add_u32_e32 v151, s56, v146
	ds_read_b128 v[164:167], v151
	ds_read_b128 v[168:171], v151 offset:1024
	ds_read_b128 v[172:175], v151 offset:2048
	ds_read_b128 v[176:179], v151 offset:3072
	s_add_u32 s42, s42, 0x40000
	s_addc_u32 s43, s43, 0
	s_mov_b32 m0, s19
	v_lshl_add_u64 v[222:223], s[42:43], 0, v[128:129]
	ds_read_b128 v[180:183], v150 offset:32768
	ds_read_b128 v[184:187], v150 offset:33792
	ds_read_b128 v[188:191], v150 offset:34816
	ds_read_b128 v[192:195], v150 offset:35840
	ds_read_b128 v[196:199], v150 offset:36864
	ds_read_b128 v[204:207], v150 offset:37888
	ds_read_b128 v[208:211], v150 offset:38912
	ds_read_b128 v[212:215], v150 offset:39936
	global_load_lds_dwordx4 v[222:223], off
	v_lshl_add_u64 v[222:223], s[42:43], 0, v[132:133]
	s_mov_b32 m0, s37
	s_nop 0
	global_load_lds_dwordx4 v[222:223], off
	s_waitcnt vmcnt(8)
	s_waitcnt lgkmcnt(0)
	s_barrier
	s_setprio 1
	s_waitcnt lgkmcnt(0)
	v_mfma_f32_16x16x32_bf16 v[124:127], v[140:143], v[180:183], v[124:127]
	v_mfma_f32_16x16x32_bf16 v[120:123], v[156:159], v[180:183], v[120:123]
	v_mfma_f32_16x16x32_bf16 v[116:119], v[140:143], v[188:191], v[116:119]
	v_mfma_f32_16x16x32_bf16 v[108:111], v[156:159], v[188:191], v[108:111]
	v_mfma_f32_16x16x32_bf16 v[100:103], v[140:143], v[196:199], v[100:103]
	v_mfma_f32_16x16x32_bf16 v[92:95], v[156:159], v[196:199], v[92:95]
	v_mfma_f32_16x16x32_bf16 v[84:87], v[140:143], v[208:211], v[84:87]
	v_mfma_f32_16x16x32_bf16 v[76:79], v[156:159], v[208:211], v[76:79]
	v_mfma_f32_16x16x32_bf16 v[124:127], v[152:155], v[184:187], v[124:127]
	v_mfma_f32_16x16x32_bf16 v[120:123], v[160:163], v[184:187], v[120:123]
	v_mfma_f32_16x16x32_bf16 v[116:119], v[152:155], v[192:195], v[116:119]
	v_mfma_f32_16x16x32_bf16 v[108:111], v[160:163], v[192:195], v[108:111]
	v_mfma_f32_16x16x32_bf16 v[100:103], v[152:155], v[204:207], v[100:103]
	v_mfma_f32_16x16x32_bf16 v[92:95], v[160:163], v[204:207], v[92:95]
	v_mfma_f32_16x16x32_bf16 v[84:87], v[152:155], v[212:215], v[84:87]
	v_mfma_f32_16x16x32_bf16 v[76:79], v[160:163], v[212:215], v[76:79]
	v_mfma_f32_16x16x32_bf16 v[112:115], v[164:167], v[180:183], v[112:115]
	v_mfma_f32_16x16x32_bf16 v[104:107], v[172:175], v[180:183], v[104:107]
	v_mfma_f32_16x16x32_bf16 v[96:99], v[164:167], v[188:191], v[96:99]
	v_mfma_f32_16x16x32_bf16 v[88:91], v[172:175], v[188:191], v[88:91]
	v_mfma_f32_16x16x32_bf16 v[80:83], v[164:167], v[196:199], v[80:83]
	v_mfma_f32_16x16x32_bf16 v[72:75], v[172:175], v[196:199], v[72:75]
	v_mfma_f32_16x16x32_bf16 v[68:71], v[164:167], v[208:211], v[68:71]
	v_mfma_f32_16x16x32_bf16 v[64:67], v[172:175], v[208:211], v[64:67]
	v_mfma_f32_16x16x32_bf16 v[112:115], v[168:171], v[184:187], v[112:115]
	v_mfma_f32_16x16x32_bf16 v[104:107], v[176:179], v[184:187], v[104:107]
	v_mfma_f32_16x16x32_bf16 v[96:99], v[168:171], v[192:195], v[96:99]
	v_mfma_f32_16x16x32_bf16 v[88:91], v[176:179], v[192:195], v[88:91]
	v_mfma_f32_16x16x32_bf16 v[80:83], v[168:171], v[204:207], v[80:83]
	v_mfma_f32_16x16x32_bf16 v[72:75], v[176:179], v[204:207], v[72:75]
	v_mfma_f32_16x16x32_bf16 v[68:71], v[168:171], v[212:215], v[68:71]
	v_mfma_f32_16x16x32_bf16 v[64:67], v[176:179], v[212:215], v[64:67]
	s_setprio 0
	s_barrier
; #define PG8_STAGE(bufoff, gbase, voff) do { _Pragma("unroll") for (int _i = 0; _i < 2; ++_i) \
;         __builtin_amdgcn_global_load_lds((const unsigned*)((const char*)(gbase) + (voff)[_i]), (LAS unsigned*)(lds + (bufoff) + ldsw + _i * 8192), 16, 0, 0); } while (0)
; #define PG8_LDA(dst, b, h) do { _Pragma("unroll") for (int m = 0; m < 4; ++m) _Pragma("unroll") for (int k = 0; k < 2; ++k) dst[m][k] = *(const LAS bf16x8*)(lds + PG8_SA(b, h) + aoff + m * 2048 + k * 1024); } while (0)
; #define PG8_MMA(ai, bj, At, Bt) do { __builtin_amdgcn_s_setprio(1); _Pragma("unroll") for (int m = 0; m < 4; ++m) _Pragma("unroll") for (int n = 0; n < 2; ++n) _Pragma("unroll") for (int k = 0; k < 2; ++k) \
;         acc[ai][bj][m][n] = __builtin_amdgcn_mfma_f32_16x16x32_bf16(Bt[n][k], At[m][k], acc[ai][bj][m][n], 0, 0, 0); __builtin_amdgcn_s_setprio(0); } while (0)
; #define PG8_WAIT_V(n) asm volatile("s_waitcnt vmcnt(" #n ")" ::: "memory")
; #define PG8_WAIT_L(n) asm volatile("s_waitcnt lgkmcnt(" #n ")" ::: "memory")
; #define PG8_BAR __builtin_amdgcn_s_barrier()
; #define PG8_SCHED __builtin_amdgcn_sched_barrier(0)
; template <class Epi>
; __device__ __forceinline__ void gemm_phase(LAS unsigned char* lds, const Gemm g, const Sched& S, const Epi& E) {
;     ...
;             PG8_LDA(At, 1, 1); PG8_STAGE(PG8_SB(1, 0), b3, voffB); PG8_STAGE(PG8_SB(1, 1), b3 + hstepB, voffB); PG8_STAGE(PG8_SA(1, 0), a3, voffA);
;             PG8_WAIT_V(8); PG8_WAIT_L(0); PG8_BAR; PG8_MMA(1, 0, At, B0); PG8_MMA(1, 1, At, B1); PG8_BAR; PG8_SCHED;
;         }
;         if (wr == 0) PG8_BAR;
	s_add_i32 s42, s55, s10
	v_lshl_add_u64 v[200:201], v[200:201], 0, s[14:15]
	s_mov_b32 m0, s42
	ds_read_b128 v[180:183], v150 offset:49152
	ds_read_b128 v[184:187], v150 offset:50176
	ds_read_b128 v[188:191], v150 offset:51200
	ds_read_b128 v[192:195], v150 offset:52224
	ds_read_b128 v[196:199], v150 offset:53248
	ds_read_b128 v[204:207], v150 offset:54272
	ds_read_b128 v[208:211], v150 offset:55296
	ds_read_b128 v[212:215], v150 offset:56320
	global_load_lds_dwordx4 v[200:201], off
	s_add_i32 m0, s42, 0x2000
	s_add_u32 s40, s40, 0x40080
	v_lshl_add_u64 v[200:201], v[216:217], 0, s[14:15]
	s_addc_u32 s41, s41, 0
	s_add_i32 s42, s56, s10
	global_load_lds_dwordx4 v[200:201], off
	v_lshl_add_u64 v[200:201], s[40:41], 0, v[130:131]
	s_mov_b32 m0, s42
	s_nop 0
	global_load_lds_dwordx4 v[200:201], off
	v_lshl_add_u64 v[200:201], s[40:41], 0, v[134:135]
	s_add_i32 m0, s42, 0x2000
	s_nop 0
	global_load_lds_dwordx4 v[200:201], off
	v_lshl_add_u64 v[200:201], v[218:219], 0, s[14:15]
	s_mov_b32 m0, s45
	s_nop 0
	global_load_lds_dwordx4 v[200:201], off
	v_lshl_add_u64 v[200:201], v[220:221], 0, s[14:15]
	s_mov_b32 m0, s46
	s_nop 0
	global_load_lds_dwordx4 v[200:201], off
	s_waitcnt vmcnt(8)
	s_waitcnt lgkmcnt(0)
	s_barrier
	s_setprio 1
	s_waitcnt lgkmcnt(0)
	v_mfma_f32_16x16x32_bf16 v[60:63], v[140:143], v[180:183], v[60:63]
	v_mfma_f32_16x16x32_bf16 v[56:59], v[156:159], v[180:183], v[56:59]
	v_mfma_f32_16x16x32_bf16 v[52:55], v[140:143], v[188:191], v[52:55]
	v_mfma_f32_16x16x32_bf16 v[44:47], v[156:159], v[188:191], v[44:47]
	v_mfma_f32_16x16x32_bf16 v[36:39], v[140:143], v[196:199], v[36:39]
	v_mfma_f32_16x16x32_bf16 v[28:31], v[156:159], v[196:199], v[28:31]
	v_mfma_f32_16x16x32_bf16 v[20:23], v[140:143], v[208:211], v[20:23]
	v_mfma_f32_16x16x32_bf16 v[12:15], v[156:159], v[208:211], v[12:15]
	v_mfma_f32_16x16x32_bf16 v[60:63], v[152:155], v[184:187], v[60:63]
	v_mfma_f32_16x16x32_bf16 v[56:59], v[160:163], v[184:187], v[56:59]
	v_mfma_f32_16x16x32_bf16 v[52:55], v[152:155], v[192:195], v[52:55]
	v_mfma_f32_16x16x32_bf16 v[44:47], v[160:163], v[192:195], v[44:47]
	v_mfma_f32_16x16x32_bf16 v[36:39], v[152:155], v[204:207], v[36:39]
	v_mfma_f32_16x16x32_bf16 v[28:31], v[160:163], v[204:207], v[28:31]
	v_mfma_f32_16x16x32_bf16 v[20:23], v[152:155], v[212:215], v[20:23]
	v_mfma_f32_16x16x32_bf16 v[12:15], v[160:163], v[212:215], v[12:15]
	v_mfma_f32_16x16x32_bf16 v[48:51], v[164:167], v[180:183], v[48:51]
	v_mfma_f32_16x16x32_bf16 v[40:43], v[172:175], v[180:183], v[40:43]
	v_mfma_f32_16x16x32_bf16 v[32:35], v[164:167], v[188:191], v[32:35]
	v_mfma_f32_16x16x32_bf16 v[24:27], v[172:175], v[188:191], v[24:27]
	v_mfma_f32_16x16x32_bf16 v[16:19], v[164:167], v[196:199], v[16:19]
	v_mfma_f32_16x16x32_bf16 v[8:11], v[172:175], v[196:199], v[8:11]
	v_mfma_f32_16x16x32_bf16 v[4:7], v[164:167], v[208:211], v[4:7]
	v_mfma_f32_16x16x32_bf16 v[0:3], v[172:175], v[208:211], v[0:3]
	v_mfma_f32_16x16x32_bf16 v[48:51], v[168:171], v[184:187], v[48:51]
	v_mfma_f32_16x16x32_bf16 v[40:43], v[176:179], v[184:187], v[40:43]
	v_mfma_f32_16x16x32_bf16 v[32:35], v[168:171], v[192:195], v[32:35]
	v_mfma_f32_16x16x32_bf16 v[24:27], v[176:179], v[192:195], v[24:27]
	v_mfma_f32_16x16x32_bf16 v[16:19], v[168:171], v[204:207], v[16:19]
	v_mfma_f32_16x16x32_bf16 v[8:11], v[176:179], v[204:207], v[8:11]
	v_mfma_f32_16x16x32_bf16 v[4:7], v[168:171], v[212:215], v[4:7]
	v_mfma_f32_16x16x32_bf16 v[0:3], v[176:179], v[212:215], v[0:3]
	s_setprio 0
	s_barrier
	s_add_i32 s54, s54, 2
	s_add_u32 s38, s38, 0x100
	s_addc_u32 s39, s39, 0
	s_add_u32 s52, s52, 0x100
	s_addc_u32 s53, s53, 0
	s_cmp_gt_u32 s54, 13
	s_cbranch_scc0 .LBB0_1355
	s_and_b64 vcc, exec, s[16:17]
	s_cbranch_vccz .LBB0_1358
	s_barrier

; #define PG8_STAGE(bufoff, gbase, voff) do { _Pragma("unroll") for (int _i = 0; _i < 2; ++_i) \
;         __builtin_amdgcn_global_load_lds((const unsigned*)((const char*)(gbase) + (voff)[_i]), (LAS unsigned*)(lds + (bufoff) + ldsw + _i * 8192), 16, 0, 0); } while (0)
; #define PG8_LDA(dst, b, h) do { _Pragma("unroll") for (int m = 0; m < 4; ++m) _Pragma("unroll") for (int k = 0; k < 2; ++k) dst[m][k] = *(const LAS bf16x8*)(lds + PG8_SA(b, h) + aoff + m * 2048 + k * 1024); } while (0)
; #define PG8_LDB(dst, b, h) do { _Pragma("unroll") for (int n = 0; n < 2; ++n) _Pragma("unroll") for (int k = 0; k < 2; ++k) dst[n][k] = *(const LAS bf16x8*)(lds + PG8_SB(b, h) + boff + n * 2048 + k * 1024); } while (0)
; #define PG8_MMA(ai, bj, At, Bt) do { __builtin_amdgcn_s_setprio(1); _Pragma("unroll") for (int m = 0; m < 4; ++m) _Pragma("unroll") for (int n = 0; n < 2; ++n) _Pragma("unroll") for (int k = 0; k < 2; ++k) \
;         acc[ai][bj][m][n] = __builtin_amdgcn_mfma_f32_16x16x32_bf16(Bt[n][k], At[m][k], acc[ai][bj][m][n], 0, 0, 0); __builtin_amdgcn_s_setprio(0); } while (0)
; #define PG8_WAIT_V(n) asm volatile("s_waitcnt vmcnt(" #n ")" ::: "memory")
; #define PG8_WAIT_L(n) asm volatile("s_waitcnt lgkmcnt(" #n ")" ::: "memory")
; #define PG8_BAR __builtin_amdgcn_s_barrier()
; #define PG8_SCHED __builtin_amdgcn_sched_barrier(0)
; template <class Epi>
; __device__ __forceinline__ void gemm_phase(LAS unsigned char* lds, const Gemm g, const Sched& S, const Epi& E) {
;     ...
;             const bool last = (t == nt - 2);
;             const char* a1 = cA + (size_t)(t + 1) * kstep;
;             const char* a2 = last ? nA : cA + (size_t)(t + 2) * kstep; const char* b2 = last ? nB : cB + (size_t)(t + 2) * kstep;
;             const char* a3 = a2 + kstep; const char* b3 = b2 + kstep;
;             PG8_LDB(B0, 0, 0); PG8_LDB(B1, 0, 1); PG8_SCHED; PG8_LDA(At, 0, 0); PG8_STAGE(PG8_SA(1, 1), a1 + hstepA, voffA);
;             PG8_WAIT_V(8); PG8_WAIT_L(0); PG8_BAR; PG8_MMA(0, 0, At, B0); PG8_MMA(0, 1, At, B1); PG8_BAR; PG8_SCHED;
;             PG8_LDA(At, 0, 1); PG8_STAGE(PG8_SB(0, 0), b2, voffB); PG8_STAGE(PG8_SB(0, 1), b2 + hstepB, voffB); PG8_STAGE(PG8_SA(0, 0), a2, voffA);
;             PG8_WAIT_V(8); PG8_WAIT_L(0); PG8_BAR; PG8_MMA(1, 0, At, B0); PG8_MMA(1, 1, At, B1); PG8_BAR; PG8_SCHED;
.LBB0_1381:
	s_add_u32 s52, s18, s46
	s_addc_u32 s53, s19, s47
	s_add_u32 s50, s52, 0x100
	s_addc_u32 s51, s53, 0
	s_and_b64 s[48:49], s[44:45], exec
	s_cselect_b32 s49, s29, s51
	s_cselect_b32 s48, s70, s50
	s_add_u32 s46, s20, s46
	s_addc_u32 s47, s21, s47
	s_add_u32 s46, s46, 0x100
	s_addc_u32 s47, s47, 0
	s_and_b64 s[44:45], s[44:45], exec
	s_cselect_b32 s51, s39, s47
	s_cselect_b32 s50, s38, s46
	s_add_u32 s54, s52, 0x40080
	s_addc_u32 s55, s53, 0
	s_add_i32 s78, s66, s57
	s_add_i32 m0, s17, 0xc000
	s_add_i32 s81, s17, 0xe000
	s_add_i32 s75, s78, 0x2000
	v_add_u32_e32 v142, s66, v140
	s_add_u32 s52, s50, 0x40000
	ds_read_b128 v[146:149], v142
	ds_read_b128 v[150:153], v142 offset:1024
	ds_read_b128 v[154:157], v142 offset:2048
	ds_read_b128 v[158:161], v142 offset:3072
	v_add_u32_e32 v142, s67, v140
	s_addc_u32 s53, s51, 0
	s_add_i32 s77, s67, s57
	ds_read_b128 v[162:165], v142
	ds_read_b128 v[166:169], v142 offset:1024
	ds_read_b128 v[170:173], v142 offset:2048
	ds_read_b128 v[174:177], v142 offset:3072
	s_add_i32 s76, s77, 0x2000
	s_add_i32 s74, 0, 0x18000
	s_add_i32 s73, 0, 0x1c000
	s_add_u32 s46, s48, 0x40000
	s_addc_u32 s47, s49, 0
	s_add_i32 s72, s74, s57
	s_add_i32 s71, s72, 0x2000
	s_add_u32 s44, s50, 0x40080
	s_addc_u32 s45, s51, 0
	s_add_i32 s80, s73, s57
	s_add_i32 s79, s80, 0x2000
	v_lshl_add_u64 v[142:143], s[54:55], 0, v[128:129]
	ds_read_b128 v[178:181], v141
	ds_read_b128 v[182:185], v141 offset:1024
	ds_read_b128 v[186:189], v141 offset:2048
	ds_read_b128 v[190:193], v141 offset:3072
	ds_read_b128 v[194:197], v141 offset:4096
	ds_read_b128 v[198:201], v141 offset:5120
	ds_read_b128 v[204:207], v141 offset:6144
	ds_read_b128 v[208:211], v141 offset:7168
	global_load_lds_dwordx4 v[142:143], off
	v_lshl_add_u64 v[142:143], s[54:55], 0, v[132:133]
	s_mov_b32 m0, s81
	s_nop 0
	global_load_lds_dwordx4 v[142:143], off
	s_waitcnt vmcnt(8)
	s_waitcnt lgkmcnt(0)
	s_barrier
	s_setprio 1
	s_waitcnt lgkmcnt(0)
	v_mfma_f32_16x16x32_bf16 v[124:127], v[146:149], v[178:181], v[124:127]
	v_mfma_f32_16x16x32_bf16 v[120:123], v[154:157], v[178:181], v[120:123]
	v_mfma_f32_16x16x32_bf16 v[112:115], v[146:149], v[186:189], v[112:115]
	v_mfma_f32_16x16x32_bf16 v[108:111], v[154:157], v[186:189], v[108:111]
	v_mfma_f32_16x16x32_bf16 v[100:103], v[146:149], v[194:197], v[100:103]
	v_mfma_f32_16x16x32_bf16 v[92:95], v[154:157], v[194:197], v[92:95]
	v_mfma_f32_16x16x32_bf16 v[84:87], v[146:149], v[204:207], v[84:87]
	v_mfma_f32_16x16x32_bf16 v[76:79], v[154:157], v[204:207], v[76:79]
	v_mfma_f32_16x16x32_bf16 v[124:127], v[150:153], v[182:185], v[124:127]
	v_mfma_f32_16x16x32_bf16 v[120:123], v[158:161], v[182:185], v[120:123]
	v_mfma_f32_16x16x32_bf16 v[112:115], v[150:153], v[190:193], v[112:115]
	v_mfma_f32_16x16x32_bf16 v[108:111], v[158:161], v[190:193], v[108:111]
	v_mfma_f32_16x16x32_bf16 v[100:103], v[150:153], v[198:201], v[100:103]
	v_mfma_f32_16x16x32_bf16 v[92:95], v[158:161], v[198:201], v[92:95]
	v_mfma_f32_16x16x32_bf16 v[84:87], v[150:153], v[208:211], v[84:87]
	v_mfma_f32_16x16x32_bf16 v[76:79], v[158:161], v[208:211], v[76:79]
	v_mfma_f32_16x16x32_bf16 v[116:119], v[162:165], v[178:181], v[116:119]
	v_mfma_f32_16x16x32_bf16 v[104:107], v[170:173], v[178:181], v[104:107]
	v_mfma_f32_16x16x32_bf16 v[96:99], v[162:165], v[186:189], v[96:99]
	v_mfma_f32_16x16x32_bf16 v[88:91], v[170:173], v[186:189], v[88:91]
	v_mfma_f32_16x16x32_bf16 v[80:83], v[162:165], v[194:197], v[80:83]
	v_mfma_f32_16x16x32_bf16 v[72:75], v[170:173], v[194:197], v[72:75]
	v_mfma_f32_16x16x32_bf16 v[68:71], v[162:165], v[204:207], v[68:71]
	v_mfma_f32_16x16x32_bf16 v[64:67], v[170:173], v[204:207], v[64:67]
	v_mfma_f32_16x16x32_bf16 v[116:119], v[166:169], v[182:185], v[116:119]
	v_mfma_f32_16x16x32_bf16 v[104:107], v[174:177], v[182:185], v[104:107]
	v_mfma_f32_16x16x32_bf16 v[96:99], v[166:169], v[190:193], v[96:99]
	v_mfma_f32_16x16x32_bf16 v[88:91], v[174:177], v[190:193], v[88:91]
	v_mfma_f32_16x16x32_bf16 v[80:83], v[166:169], v[198:201], v[80:83]
	v_mfma_f32_16x16x32_bf16 v[72:75], v[174:177], v[198:201], v[72:75]
	v_mfma_f32_16x16x32_bf16 v[68:71], v[166:169], v[208:211], v[68:71]
	v_mfma_f32_16x16x32_bf16 v[64:67], v[174:177], v[208:211], v[64:67]
	s_setprio 0
	s_barrier
	s_mov_b32 m0, s78
	v_lshl_add_u64 v[142:143], s[50:51], 0, v[130:131]
	ds_read_b128 v[178:181], v141 offset:16384
	ds_read_b128 v[182:185], v141 offset:17408
	ds_read_b128 v[186:189], v141 offset:18432
	ds_read_b128 v[190:193], v141 offset:19456
	ds_read_b128 v[194:197], v141 offset:20480
	ds_read_b128 v[198:201], v141 offset:21504
	ds_read_b128 v[204:207], v141 offset:22528
	ds_read_b128 v[208:211], v141 offset:23552
	global_load_lds_dwordx4 v[142:143], off
	v_lshl_add_u64 v[212:213], s[50:51], 0, v[134:135]
	s_mov_b32 m0, s75
	v_lshl_add_u64 v[214:215], s[52:53], 0, v[130:131]
	global_load_lds_dwordx4 v[212:213], off
	s_mov_b32 m0, s77
	v_lshl_add_u64 v[216:217], s[48:49], 0, v[132:133]
	global_load_lds_dwordx4 v[214:215], off
	v_lshl_add_u64 v[214:215], s[52:53], 0, v[134:135]
	s_mov_b32 m0, s76
	s_nop 0
	global_load_lds_dwordx4 v[214:215], off
	v_lshl_add_u64 v[214:215], s[48:49], 0, v[128:129]
	s_mov_b32 m0, s17
	s_nop 0
	global_load_lds_dwordx4 v[214:215], off
	s_mov_b32 m0, s60
	s_nop 0
	global_load_lds_dwordx4 v[216:217], off
	s_waitcnt vmcnt(8)
	s_waitcnt lgkmcnt(0)
	s_barrier
; #define PG8_STAGE(bufoff, gbase, voff) do { _Pragma("unroll") for (int _i = 0; _i < 2; ++_i) \
;         __builtin_amdgcn_global_load_lds((const unsigned*)((const char*)(gbase) + (voff)[_i]), (LAS unsigned*)(lds + (bufoff) + ldsw + _i * 8192), 16, 0, 0); } while (0)
; #define PG8_LDA(dst, b, h) do { _Pragma("unroll") for (int m = 0; m < 4; ++m) _Pragma("unroll") for (int k = 0; k < 2; ++k) dst[m][k] = *(const LAS bf16x8*)(lds + PG8_SA(b, h) + aoff + m * 2048 + k * 1024); } while (0)
; #define PG8_LDB(dst, b, h) do { _Pragma("unroll") for (int n = 0; n < 2; ++n) _Pragma("unroll") for (int k = 0; k < 2; ++k) dst[n][k] = *(const LAS bf16x8*)(lds + PG8_SB(b, h) + boff + n * 2048 + k * 1024); } while (0)
; #define PG8_MMA(ai, bj, At, Bt) do { __builtin_amdgcn_s_setprio(1); _Pragma("unroll") for (int m = 0; m < 4; ++m) _Pragma("unroll") for (int n = 0; n < 2; ++n) _Pragma("unroll") for (int k = 0; k < 2; ++k) \
;         acc[ai][bj][m][n] = __builtin_amdgcn_mfma_f32_16x16x32_bf16(Bt[n][k], At[m][k], acc[ai][bj][m][n], 0, 0, 0); __builtin_amdgcn_s_setprio(0); } while (0)
; #define PG8_WAIT_V(n) asm volatile("s_waitcnt vmcnt(" #n ")" ::: "memory")
; #define PG8_WAIT_L(n) asm volatile("s_waitcnt lgkmcnt(" #n ")" ::: "memory")
; #define PG8_BAR __builtin_amdgcn_s_barrier()
; #define PG8_SCHED __builtin_amdgcn_sched_barrier(0)
; template <class Epi>
; __device__ __forceinline__ void gemm_phase(LAS unsigned char* lds, const Gemm g, const Sched& S, const Epi& E) {
;     ...
;             PG8_WAIT_V(8); PG8_WAIT_L(0); PG8_BAR; PG8_MMA(1, 0, At, B0); PG8_MMA(1, 1, At, B1); PG8_BAR; PG8_SCHED;
;             PG8_LDB(B0, 1, 0); PG8_LDB(B1, 1, 1); PG8_SCHED; PG8_LDA(At, 1, 0); PG8_STAGE(PG8_SA(0, 1), a2 + hstepA, voffA);
;             PG8_WAIT_V(8); PG8_WAIT_L(0); PG8_BAR; PG8_MMA(0, 0, At, B0); PG8_MMA(0, 1, At, B1); PG8_BAR; PG8_SCHED;
	s_setprio 1
	s_waitcnt lgkmcnt(0)
	v_mfma_f32_16x16x32_bf16 v[60:63], v[146:149], v[178:181], v[60:63]
	v_mfma_f32_16x16x32_bf16 v[56:59], v[154:157], v[178:181], v[56:59]
	v_mfma_f32_16x16x32_bf16 v[52:55], v[146:149], v[186:189], v[52:55]
	v_mfma_f32_16x16x32_bf16 v[44:47], v[154:157], v[186:189], v[44:47]
	v_mfma_f32_16x16x32_bf16 v[36:39], v[146:149], v[194:197], v[36:39]
	v_mfma_f32_16x16x32_bf16 v[28:31], v[154:157], v[194:197], v[28:31]
	v_mfma_f32_16x16x32_bf16 v[20:23], v[146:149], v[204:207], v[20:23]
	v_mfma_f32_16x16x32_bf16 v[12:15], v[154:157], v[204:207], v[12:15]
	v_mfma_f32_16x16x32_bf16 v[60:63], v[150:153], v[182:185], v[60:63]
	v_mfma_f32_16x16x32_bf16 v[56:59], v[158:161], v[182:185], v[56:59]
	v_mfma_f32_16x16x32_bf16 v[52:55], v[150:153], v[190:193], v[52:55]
	v_mfma_f32_16x16x32_bf16 v[44:47], v[158:161], v[190:193], v[44:47]
	v_mfma_f32_16x16x32_bf16 v[36:39], v[150:153], v[198:201], v[36:39]
	v_mfma_f32_16x16x32_bf16 v[28:31], v[158:161], v[198:201], v[28:31]
	v_mfma_f32_16x16x32_bf16 v[20:23], v[150:153], v[208:211], v[20:23]
	v_mfma_f32_16x16x32_bf16 v[12:15], v[158:161], v[208:211], v[12:15]
	v_mfma_f32_16x16x32_bf16 v[48:51], v[162:165], v[178:181], v[48:51]
	v_mfma_f32_16x16x32_bf16 v[40:43], v[170:173], v[178:181], v[40:43]
	v_mfma_f32_16x16x32_bf16 v[32:35], v[162:165], v[186:189], v[32:35]
	v_mfma_f32_16x16x32_bf16 v[24:27], v[170:173], v[186:189], v[24:27]
	v_mfma_f32_16x16x32_bf16 v[16:19], v[162:165], v[194:197], v[16:19]
	v_mfma_f32_16x16x32_bf16 v[8:11], v[170:173], v[194:197], v[8:11]
	v_mfma_f32_16x16x32_bf16 v[4:7], v[162:165], v[204:207], v[4:7]
	v_mfma_f32_16x16x32_bf16 v[0:3], v[170:173], v[204:207], v[0:3]
	v_mfma_f32_16x16x32_bf16 v[48:51], v[166:169], v[182:185], v[48:51]
	v_mfma_f32_16x16x32_bf16 v[40:43], v[174:177], v[182:185], v[40:43]
	v_mfma_f32_16x16x32_bf16 v[32:35], v[166:169], v[190:193], v[32:35]
	v_mfma_f32_16x16x32_bf16 v[24:27], v[174:177], v[190:193], v[24:27]
	v_mfma_f32_16x16x32_bf16 v[16:19], v[166:169], v[198:201], v[16:19]
	v_mfma_f32_16x16x32_bf16 v[8:11], v[174:177], v[198:201], v[8:11]
	v_mfma_f32_16x16x32_bf16 v[4:7], v[166:169], v[208:211], v[4:7]
	v_mfma_f32_16x16x32_bf16 v[0:3], v[174:177], v[208:211], v[0:3]
	s_setprio 0
	s_barrier
	v_add_u32_e32 v145, s74, v140
	ds_read_b128 v[146:149], v145
	ds_read_b128 v[150:153], v145 offset:1024
	ds_read_b128 v[154:157], v145 offset:2048
	ds_read_b128 v[158:161], v145 offset:3072
	v_add_u32_e32 v145, s73, v140
	ds_read_b128 v[162:165], v145
	ds_read_b128 v[166:169], v145 offset:1024
	ds_read_b128 v[170:173], v145 offset:2048
	ds_read_b128 v[174:177], v145 offset:3072
	s_mov_b32 m0, s61
	v_lshl_add_u64 v[218:219], s[46:47], 0, v[128:129]
	ds_read_b128 v[178:181], v141 offset:32768
	ds_read_b128 v[182:185], v141 offset:33792
	ds_read_b128 v[186:189], v141 offset:34816
	ds_read_b128 v[190:193], v141 offset:35840
	ds_read_b128 v[194:197], v141 offset:36864
	ds_read_b128 v[198:201], v141 offset:37888
	ds_read_b128 v[204:207], v141 offset:38912
	ds_read_b128 v[208:211], v141 offset:39936
	global_load_lds_dwordx4 v[218:219], off
	v_lshl_add_u64 v[218:219], s[46:47], 0, v[132:133]
	s_mov_b32 m0, s62
	s_nop 0
	global_load_lds_dwordx4 v[218:219], off
	s_waitcnt vmcnt(8)
	s_waitcnt lgkmcnt(0)
	s_barrier
	s_setprio 1
	s_waitcnt lgkmcnt(0)
	v_mfma_f32_16x16x32_bf16 v[124:127], v[146:149], v[178:181], v[124:127]
	v_mfma_f32_16x16x32_bf16 v[120:123], v[154:157], v[178:181], v[120:123]
	v_mfma_f32_16x16x32_bf16 v[112:115], v[146:149], v[186:189], v[112:115]
	v_mfma_f32_16x16x32_bf16 v[108:111], v[154:157], v[186:189], v[108:111]
	v_mfma_f32_16x16x32_bf16 v[100:103], v[146:149], v[194:197], v[100:103]
	v_mfma_f32_16x16x32_bf16 v[92:95], v[154:157], v[194:197], v[92:95]
	v_mfma_f32_16x16x32_bf16 v[84:87], v[146:149], v[204:207], v[84:87]
	v_mfma_f32_16x16x32_bf16 v[76:79], v[154:157], v[204:207], v[76:79]
	v_mfma_f32_16x16x32_bf16 v[124:127], v[150:153], v[182:185], v[124:127]
	v_mfma_f32_16x16x32_bf16 v[120:123], v[158:161], v[182:185], v[120:123]
	v_mfma_f32_16x16x32_bf16 v[112:115], v[150:153], v[190:193], v[112:115]
	v_mfma_f32_16x16x32_bf16 v[108:111], v[158:161], v[190:193], v[108:111]
	v_mfma_f32_16x16x32_bf16 v[100:103], v[150:153], v[198:201], v[100:103]
	v_mfma_f32_16x16x32_bf16 v[92:95], v[158:161], v[198:201], v[92:95]
	v_mfma_f32_16x16x32_bf16 v[84:87], v[150:153], v[208:211], v[84:87]
	v_mfma_f32_16x16x32_bf16 v[76:79], v[158:161], v[208:211], v[76:79]
	v_mfma_f32_16x16x32_bf16 v[116:119], v[162:165], v[178:181], v[116:119]
	v_mfma_f32_16x16x32_bf16 v[104:107], v[170:173], v[178:181], v[104:107]
	v_mfma_f32_16x16x32_bf16 v[96:99], v[162:165], v[186:189], v[96:99]
	v_mfma_f32_16x16x32_bf16 v[88:91], v[170:173], v[186:189], v[88:91]
	v_mfma_f32_16x16x32_bf16 v[80:83], v[162:165], v[194:197], v[80:83]
	v_mfma_f32_16x16x32_bf16 v[72:75], v[170:173], v[194:197], v[72:75]
	v_mfma_f32_16x16x32_bf16 v[68:71], v[162:165], v[204:207], v[68:71]
	v_mfma_f32_16x16x32_bf16 v[64:67], v[170:173], v[204:207], v[64:67]
	v_mfma_f32_16x16x32_bf16 v[116:119], v[166:169], v[182:185], v[116:119]
	v_mfma_f32_16x16x32_bf16 v[104:107], v[174:177], v[182:185], v[104:107]
	v_mfma_f32_16x16x32_bf16 v[96:99], v[166:169], v[190:193], v[96:99]
	v_mfma_f32_16x16x32_bf16 v[88:91], v[174:177], v[190:193], v[88:91]
	v_mfma_f32_16x16x32_bf16 v[80:83], v[166:169], v[198:201], v[80:83]
	v_mfma_f32_16x16x32_bf16 v[72:75], v[174:177], v[198:201], v[72:75]
	v_mfma_f32_16x16x32_bf16 v[68:71], v[166:169], v[208:211], v[68:71]
	v_mfma_f32_16x16x32_bf16 v[64:67], v[174:177], v[208:211], v[64:67]
	s_setprio 0
	s_barrier
; #define PG8_STAGE(bufoff, gbase, voff) do { _Pragma("unroll") for (int _i = 0; _i < 2; ++_i) \
;         __builtin_amdgcn_global_load_lds((const unsigned*)((const char*)(gbase) + (voff)[_i]), (LAS unsigned*)(lds + (bufoff) + ldsw + _i * 8192), 16, 0, 0); } while (0)
; #define PG8_LDA(dst, b, h) do { _Pragma("unroll") for (int m = 0; m < 4; ++m) _Pragma("unroll") for (int k = 0; k < 2; ++k) dst[m][k] = *(const LAS bf16x8*)(lds + PG8_SA(b, h) + aoff + m * 2048 + k * 1024); } while (0)
; #define PG8_MMA(ai, bj, At, Bt) do { __builtin_amdgcn_s_setprio(1); _Pragma("unroll") for (int m = 0; m < 4; ++m) _Pragma("unroll") for (int n = 0; n < 2; ++n) _Pragma("unroll") for (int k = 0; k < 2; ++k) \
;         acc[ai][bj][m][n] = __builtin_amdgcn_mfma_f32_16x16x32_bf16(Bt[n][k], At[m][k], acc[ai][bj][m][n], 0, 0, 0); __builtin_amdgcn_s_setprio(0); } while (0)
; #define PG8_WAIT_V(n) asm volatile("s_waitcnt vmcnt(" #n ")" ::: "memory")
; #define PG8_WAIT_L(n) asm volatile("s_waitcnt lgkmcnt(" #n ")" ::: "memory")
; #define PG8_BAR __builtin_amdgcn_s_barrier()
; #define PG8_SCHED __builtin_amdgcn_sched_barrier(0)
; template <class Epi>
; __device__ __forceinline__ void gemm_phase(LAS unsigned char* lds, const Gemm g, const Sched& S, const Epi& E) {
;     ...
;             PG8_LDA(At, 1, 1); PG8_STAGE(PG8_SB(1, 0), b3, voffB); PG8_STAGE(PG8_SB(1, 1), b3 + hstepB, voffB); PG8_STAGE(PG8_SA(1, 0), a3, voffA);
;             PG8_WAIT_V(8); PG8_WAIT_L(0); PG8_BAR; PG8_MMA(1, 0, At, B0); PG8_MMA(1, 1, At, B1); PG8_BAR; PG8_SCHED;
;         }
;         if (wr == 0) PG8_BAR;
;         if constexpr (!Epi::AFTER_DRAIN) { E(acc, cur, wr, wc, fr, fq); }
;         if (!has_next) break;
	s_mov_b32 m0, s72
	v_lshl_add_u64 v[142:143], v[142:143], 0, s[24:25]
	ds_read_b128 v[178:181], v141 offset:49152
	ds_read_b128 v[182:185], v141 offset:50176
	ds_read_b128 v[186:189], v141 offset:51200
	ds_read_b128 v[190:193], v141 offset:52224
	ds_read_b128 v[194:197], v141 offset:53248
	ds_read_b128 v[198:201], v141 offset:54272
	ds_read_b128 v[204:207], v141 offset:55296
	ds_read_b128 v[208:211], v141 offset:56320
	global_load_lds_dwordx4 v[142:143], off
	v_lshl_add_u64 v[142:143], v[212:213], 0, s[24:25]
	s_mov_b32 m0, s71
	s_nop 0
	global_load_lds_dwordx4 v[142:143], off
	v_lshl_add_u64 v[142:143], s[44:45], 0, v[130:131]
	s_mov_b32 m0, s80
	s_nop 0
	global_load_lds_dwordx4 v[142:143], off
	v_lshl_add_u64 v[142:143], s[44:45], 0, v[134:135]
	s_mov_b32 m0, s79
	s_nop 0
	global_load_lds_dwordx4 v[142:143], off
	v_lshl_add_u64 v[142:143], v[214:215], 0, s[24:25]
	s_mov_b32 m0, s64
	s_nop 0
	global_load_lds_dwordx4 v[142:143], off
	v_lshl_add_u64 v[142:143], v[216:217], 0, s[24:25]
	s_mov_b32 m0, s65
	s_nop 0
	global_load_lds_dwordx4 v[142:143], off
	s_waitcnt vmcnt(8)
	s_waitcnt lgkmcnt(0)
	s_barrier
	s_setprio 1
	s_waitcnt lgkmcnt(0)
	v_mfma_f32_16x16x32_bf16 v[60:63], v[146:149], v[178:181], v[60:63]
	v_mfma_f32_16x16x32_bf16 v[56:59], v[154:157], v[178:181], v[56:59]
	v_mfma_f32_16x16x32_bf16 v[52:55], v[146:149], v[186:189], v[52:55]
	v_mfma_f32_16x16x32_bf16 v[44:47], v[154:157], v[186:189], v[44:47]
	v_mfma_f32_16x16x32_bf16 v[36:39], v[146:149], v[194:197], v[36:39]
	v_mfma_f32_16x16x32_bf16 v[28:31], v[154:157], v[194:197], v[28:31]
	v_mfma_f32_16x16x32_bf16 v[20:23], v[146:149], v[204:207], v[20:23]
	v_mfma_f32_16x16x32_bf16 v[12:15], v[154:157], v[204:207], v[12:15]
	v_mfma_f32_16x16x32_bf16 v[60:63], v[150:153], v[182:185], v[60:63]
	v_mfma_f32_16x16x32_bf16 v[56:59], v[158:161], v[182:185], v[56:59]
	v_mfma_f32_16x16x32_bf16 v[52:55], v[150:153], v[190:193], v[52:55]
	v_mfma_f32_16x16x32_bf16 v[44:47], v[158:161], v[190:193], v[44:47]
	v_mfma_f32_16x16x32_bf16 v[36:39], v[150:153], v[198:201], v[36:39]
	v_mfma_f32_16x16x32_bf16 v[28:31], v[158:161], v[198:201], v[28:31]
	v_mfma_f32_16x16x32_bf16 v[20:23], v[150:153], v[208:211], v[20:23]
	v_mfma_f32_16x16x32_bf16 v[12:15], v[158:161], v[208:211], v[12:15]
	v_mfma_f32_16x16x32_bf16 v[48:51], v[162:165], v[178:181], v[48:51]
	v_mfma_f32_16x16x32_bf16 v[40:43], v[170:173], v[178:181], v[40:43]
	v_mfma_f32_16x16x32_bf16 v[32:35], v[162:165], v[186:189], v[32:35]
	v_mfma_f32_16x16x32_bf16 v[24:27], v[170:173], v[186:189], v[24:27]
	v_mfma_f32_16x16x32_bf16 v[16:19], v[162:165], v[194:197], v[16:19]
	v_mfma_f32_16x16x32_bf16 v[8:11], v[170:173], v[194:197], v[8:11]
	v_mfma_f32_16x16x32_bf16 v[4:7], v[162:165], v[204:207], v[4:7]
	v_mfma_f32_16x16x32_bf16 v[0:3], v[170:173], v[204:207], v[0:3]
	v_mfma_f32_16x16x32_bf16 v[48:51], v[166:169], v[182:185], v[48:51]
	v_mfma_f32_16x16x32_bf16 v[40:43], v[174:177], v[182:185], v[40:43]
	v_mfma_f32_16x16x32_bf16 v[32:35], v[166:169], v[190:193], v[32:35]
	v_mfma_f32_16x16x32_bf16 v[24:27], v[174:177], v[190:193], v[24:27]
	v_mfma_f32_16x16x32_bf16 v[16:19], v[166:169], v[198:201], v[16:19]
	v_mfma_f32_16x16x32_bf16 v[8:11], v[174:177], v[198:201], v[8:11]
	v_mfma_f32_16x16x32_bf16 v[4:7], v[166:169], v[208:211], v[4:7]
	v_mfma_f32_16x16x32_bf16 v[0:3], v[174:177], v[208:211], v[0:3]
	s_setprio 0
	s_barrier
	s_andn2_b64 vcc, exec, s[42:43]
	s_mov_b64 s[44:45], -1
	s_mov_b64 s[42:43], 0
	s_mov_b64 s[46:47], 0x100
	s_cbranch_vccz .LBB0_1381
	s_and_b64 vcc, exec, s[26:27]
	s_cbranch_vccnz .LBB0_1384
	s_and_b64 vcc, exec, s[4:5]
	s_mov_b32 s81, s12
	s_cbranch_vccnz .LBB0_1371
	s_branch .LBB0_1385

; #define PG8_STAGE(bufoff, gbase, voff) do { _Pragma("unroll") for (int _i = 0; _i < 2; ++_i) \
;         __builtin_amdgcn_global_load_lds((const unsigned*)((const char*)(gbase) + (voff)[_i]), (LAS unsigned*)(lds + (bufoff) + ldsw + _i * 8192), 16, 0, 0); } while (0)
; #define PG8_LDA(dst, b, h) do { _Pragma("unroll") for (int m = 0; m < 4; ++m) _Pragma("unroll") for (int k = 0; k < 2; ++k) dst[m][k] = *(const LAS bf16x8*)(lds + PG8_SA(b, h) + aoff + m * 2048 + k * 1024); } while (0)
; #define PG8_LDB(dst, b, h) do { _Pragma("unroll") for (int n = 0; n < 2; ++n) _Pragma("unroll") for (int k = 0; k < 2; ++k) dst[n][k] = *(const LAS bf16x8*)(lds + PG8_SB(b, h) + boff + n * 2048 + k * 1024); } while (0)
; #define PG8_MMA(ai, bj, At, Bt) do { __builtin_amdgcn_s_setprio(1); _Pragma("unroll") for (int m = 0; m < 4; ++m) _Pragma("unroll") for (int n = 0; n < 2; ++n) _Pragma("unroll") for (int k = 0; k < 2; ++k) \
;         acc[ai][bj][m][n] = __builtin_amdgcn_mfma_f32_16x16x32_bf16(Bt[n][k], At[m][k], acc[ai][bj][m][n], 0, 0, 0); __builtin_amdgcn_s_setprio(0); } while (0)
; #define PG8_WAIT_V(n) asm volatile("s_waitcnt vmcnt(" #n ")" ::: "memory")
; #define PG8_WAIT_L(n) asm volatile("s_waitcnt lgkmcnt(" #n ")" ::: "memory")
; #define PG8_BAR __builtin_amdgcn_s_barrier()
; #define PG8_SCHED __builtin_amdgcn_sched_barrier(0)
; template <class Epi>
; __device__ __forceinline__ void gemm_phase(LAS unsigned char* lds, const Gemm g, const Sched& S, const Epi& E) {
;     ...
;             const bool last = (t == nt - 2);
;             const char* a1 = cA + (size_t)(t + 1) * kstep;
;             const char* a2 = last ? nA : cA + (size_t)(t + 2) * kstep; const char* b2 = last ? nB : cB + (size_t)(t + 2) * kstep;
;             const char* a3 = a2 + kstep; const char* b3 = b2 + kstep;
;             PG8_LDB(B0, 0, 0); PG8_LDB(B1, 0, 1); PG8_SCHED; PG8_LDA(At, 0, 0); PG8_STAGE(PG8_SA(1, 1), a1 + hstepA, voffA);
;             PG8_WAIT_V(8); PG8_WAIT_L(0); PG8_BAR; PG8_MMA(0, 0, At, B0); PG8_MMA(0, 1, At, B1); PG8_BAR; PG8_SCHED;
;             PG8_LDA(At, 0, 1); PG8_STAGE(PG8_SB(0, 0), b2, voffB); PG8_STAGE(PG8_SB(0, 1), b2 + hstepB, voffB); PG8_STAGE(PG8_SA(0, 0), a2, voffA);
;             PG8_WAIT_V(8); PG8_WAIT_L(0); PG8_BAR; PG8_MMA(1, 0, At, B0); PG8_MMA(1, 1, At, B1); PG8_BAR; PG8_SCHED;
.LBB0_1439:
	s_add_u32 s47, s28, s46
	s_addc_u32 s52, s29, 0
	s_add_u32 s50, s47, 0x100
	s_addc_u32 s51, s52, 0
	s_and_b64 s[48:49], s[44:45], exec
	s_cselect_b32 s49, s23, s51
	s_cselect_b32 s48, s25, s50
	s_add_u32 s46, s36, s46
	s_addc_u32 s50, s37, 0
	s_add_u32 s46, s46, 0x100
	s_addc_u32 s50, s50, 0
	s_and_b64 s[44:45], s[44:45], exec
	s_cselect_b32 s51, s39, s50
	s_cselect_b32 s50, s38, s46
	s_add_u32 s54, s47, 0x40080
	ds_read_b128 v[146:149], v139
	ds_read_b128 v[150:153], v139 offset:1024
	ds_read_b128 v[154:157], v139 offset:2048
	ds_read_b128 v[158:161], v139 offset:3072
	ds_read_b128 v[162:165], v140
	ds_read_b128 v[166:169], v140 offset:1024
	ds_read_b128 v[170:173], v140 offset:2048
	ds_read_b128 v[174:177], v140 offset:3072
	s_addc_u32 s55, s52, 0
	s_add_i32 s72, s62, s10
	s_add_i32 m0, s27, 0xc000
	s_add_i32 s75, s27, 0xe000
	s_add_i32 s69, s72, 0x2000
	s_add_u32 s52, s50, 0x80000
	s_addc_u32 s53, s51, 0
	s_add_i32 s71, s63, s10
	s_add_i32 s70, s71, 0x2000
	s_add_i32 s68, 0, 0x18000
	s_add_i32 s67, 0, 0x1c000
	s_add_u32 s46, s48, 0x40000
	s_addc_u32 s47, s49, 0
	s_add_i32 s66, s68, s10
	s_add_i32 s65, s66, 0x2000
	s_add_u32 s44, s50, 0x80080
	s_addc_u32 s45, s51, 0
	s_add_i32 s74, s67, s10
	s_add_i32 s73, s74, 0x2000
	v_lshl_add_u64 v[142:143], s[54:55], 0, v[128:129]
	ds_read_b128 v[178:181], v141
	ds_read_b128 v[182:185], v141 offset:1024
	ds_read_b128 v[186:189], v141 offset:2048
	ds_read_b128 v[190:193], v141 offset:3072
	ds_read_b128 v[194:197], v141 offset:4096
	ds_read_b128 v[198:201], v141 offset:5120
	ds_read_b128 v[204:207], v141 offset:6144
	ds_read_b128 v[208:211], v141 offset:7168
	global_load_lds_dwordx4 v[142:143], off
	v_lshl_add_u64 v[142:143], s[54:55], 0, v[132:133]
	s_mov_b32 m0, s75
	s_nop 0
	global_load_lds_dwordx4 v[142:143], off
	s_waitcnt vmcnt(8)
	s_waitcnt lgkmcnt(0)
	s_barrier
	s_setprio 1
	s_waitcnt lgkmcnt(0)
	v_mfma_f32_16x16x32_bf16 v[124:127], v[146:149], v[178:181], v[124:127]
	v_mfma_f32_16x16x32_bf16 v[120:123], v[154:157], v[178:181], v[120:123]
	v_mfma_f32_16x16x32_bf16 v[116:119], v[146:149], v[186:189], v[116:119]
	v_mfma_f32_16x16x32_bf16 v[112:115], v[154:157], v[186:189], v[112:115]
	v_mfma_f32_16x16x32_bf16 v[100:103], v[146:149], v[194:197], v[100:103]
	v_mfma_f32_16x16x32_bf16 v[96:99], v[154:157], v[194:197], v[96:99]
	v_mfma_f32_16x16x32_bf16 v[84:87], v[146:149], v[204:207], v[84:87]
	v_mfma_f32_16x16x32_bf16 v[80:83], v[154:157], v[204:207], v[80:83]
	v_mfma_f32_16x16x32_bf16 v[124:127], v[150:153], v[182:185], v[124:127]
	v_mfma_f32_16x16x32_bf16 v[120:123], v[158:161], v[182:185], v[120:123]
	v_mfma_f32_16x16x32_bf16 v[116:119], v[150:153], v[190:193], v[116:119]
	v_mfma_f32_16x16x32_bf16 v[112:115], v[158:161], v[190:193], v[112:115]
	v_mfma_f32_16x16x32_bf16 v[100:103], v[150:153], v[198:201], v[100:103]
	v_mfma_f32_16x16x32_bf16 v[96:99], v[158:161], v[198:201], v[96:99]
	v_mfma_f32_16x16x32_bf16 v[84:87], v[150:153], v[208:211], v[84:87]
	v_mfma_f32_16x16x32_bf16 v[80:83], v[158:161], v[208:211], v[80:83]
	v_mfma_f32_16x16x32_bf16 v[108:111], v[162:165], v[178:181], v[108:111]
	v_mfma_f32_16x16x32_bf16 v[104:107], v[170:173], v[178:181], v[104:107]
	v_mfma_f32_16x16x32_bf16 v[92:95], v[162:165], v[186:189], v[92:95]
	v_mfma_f32_16x16x32_bf16 v[88:91], v[170:173], v[186:189], v[88:91]
	v_mfma_f32_16x16x32_bf16 v[76:79], v[162:165], v[194:197], v[76:79]
	v_mfma_f32_16x16x32_bf16 v[72:75], v[170:173], v[194:197], v[72:75]
	v_mfma_f32_16x16x32_bf16 v[68:71], v[162:165], v[204:207], v[68:71]
	v_mfma_f32_16x16x32_bf16 v[64:67], v[170:173], v[204:207], v[64:67]
	v_mfma_f32_16x16x32_bf16 v[108:111], v[166:169], v[182:185], v[108:111]
	v_mfma_f32_16x16x32_bf16 v[104:107], v[174:177], v[182:185], v[104:107]
	v_mfma_f32_16x16x32_bf16 v[92:95], v[166:169], v[190:193], v[92:95]
	v_mfma_f32_16x16x32_bf16 v[88:91], v[174:177], v[190:193], v[88:91]
	v_mfma_f32_16x16x32_bf16 v[76:79], v[166:169], v[198:201], v[76:79]
	v_mfma_f32_16x16x32_bf16 v[72:75], v[174:177], v[198:201], v[72:75]
	v_mfma_f32_16x16x32_bf16 v[68:71], v[166:169], v[208:211], v[68:71]
	v_mfma_f32_16x16x32_bf16 v[64:67], v[174:177], v[208:211], v[64:67]
	s_setprio 0
	s_barrier
	s_mov_b32 m0, s72
	v_lshl_add_u64 v[142:143], s[50:51], 0, v[130:131]
	ds_read_b128 v[178:181], v141 offset:16384
	ds_read_b128 v[182:185], v141 offset:17408
	ds_read_b128 v[186:189], v141 offset:18432
	ds_read_b128 v[190:193], v141 offset:19456
	ds_read_b128 v[194:197], v141 offset:20480
	ds_read_b128 v[198:201], v141 offset:21504
	ds_read_b128 v[204:207], v141 offset:22528
	ds_read_b128 v[208:211], v141 offset:23552
	global_load_lds_dwordx4 v[142:143], off
	v_lshl_add_u64 v[212:213], s[50:51], 0, v[134:135]
	s_mov_b32 m0, s69
	v_lshl_add_u64 v[214:215], s[52:53], 0, v[130:131]
	global_load_lds_dwordx4 v[212:213], off
	s_mov_b32 m0, s71
	v_lshl_add_u64 v[216:217], s[48:49], 0, v[132:133]
	global_load_lds_dwordx4 v[214:215], off
	v_lshl_add_u64 v[214:215], s[52:53], 0, v[134:135]
	s_mov_b32 m0, s70
	s_nop 0
	global_load_lds_dwordx4 v[214:215], off
	v_lshl_add_u64 v[214:215], s[48:49], 0, v[128:129]
	s_mov_b32 m0, s27
	s_nop 0
	global_load_lds_dwordx4 v[214:215], off
	s_mov_b32 m0, s56
	s_nop 0
	global_load_lds_dwordx4 v[216:217], off
	s_waitcnt vmcnt(8)
	s_waitcnt lgkmcnt(0)
	s_barrier
; #define PG8_STAGE(bufoff, gbase, voff) do { _Pragma("unroll") for (int _i = 0; _i < 2; ++_i) \
;         __builtin_amdgcn_global_load_lds((const unsigned*)((const char*)(gbase) + (voff)[_i]), (LAS unsigned*)(lds + (bufoff) + ldsw + _i * 8192), 16, 0, 0); } while (0)
; #define PG8_LDA(dst, b, h) do { _Pragma("unroll") for (int m = 0; m < 4; ++m) _Pragma("unroll") for (int k = 0; k < 2; ++k) dst[m][k] = *(const LAS bf16x8*)(lds + PG8_SA(b, h) + aoff + m * 2048 + k * 1024); } while (0)
; #define PG8_LDB(dst, b, h) do { _Pragma("unroll") for (int n = 0; n < 2; ++n) _Pragma("unroll") for (int k = 0; k < 2; ++k) dst[n][k] = *(const LAS bf16x8*)(lds + PG8_SB(b, h) + boff + n * 2048 + k * 1024); } while (0)
; #define PG8_MMA(ai, bj, At, Bt) do { __builtin_amdgcn_s_setprio(1); _Pragma("unroll") for (int m = 0; m < 4; ++m) _Pragma("unroll") for (int n = 0; n < 2; ++n) _Pragma("unroll") for (int k = 0; k < 2; ++k) \
;         acc[ai][bj][m][n] = __builtin_amdgcn_mfma_f32_16x16x32_bf16(Bt[n][k], At[m][k], acc[ai][bj][m][n], 0, 0, 0); __builtin_amdgcn_s_setprio(0); } while (0)
; #define PG8_WAIT_V(n) asm volatile("s_waitcnt vmcnt(" #n ")" ::: "memory")
; #define PG8_WAIT_L(n) asm volatile("s_waitcnt lgkmcnt(" #n ")" ::: "memory")
; #define PG8_BAR __builtin_amdgcn_s_barrier()
; #define PG8_SCHED __builtin_amdgcn_sched_barrier(0)
; template <class Epi>
; __device__ __forceinline__ void gemm_phase(LAS unsigned char* lds, const Gemm g, const Sched& S, const Epi& E) {
;     ...
;             PG8_WAIT_V(8); PG8_WAIT_L(0); PG8_BAR; PG8_MMA(1, 0, At, B0); PG8_MMA(1, 1, At, B1); PG8_BAR; PG8_SCHED;
;             PG8_LDB(B0, 1, 0); PG8_LDB(B1, 1, 1); PG8_SCHED; PG8_LDA(At, 1, 0); PG8_STAGE(PG8_SA(0, 1), a2 + hstepA, voffA);
;             PG8_WAIT_V(8); PG8_WAIT_L(0); PG8_BAR; PG8_MMA(0, 0, At, B0); PG8_MMA(0, 1, At, B1); PG8_BAR; PG8_SCHED;
	s_setprio 1
	s_waitcnt lgkmcnt(0)
	v_mfma_f32_16x16x32_bf16 v[60:63], v[146:149], v[178:181], v[60:63]
	v_mfma_f32_16x16x32_bf16 v[56:59], v[154:157], v[178:181], v[56:59]
	v_mfma_f32_16x16x32_bf16 v[52:55], v[146:149], v[186:189], v[52:55]
	v_mfma_f32_16x16x32_bf16 v[48:51], v[154:157], v[186:189], v[48:51]
	v_mfma_f32_16x16x32_bf16 v[36:39], v[146:149], v[194:197], v[36:39]
	v_mfma_f32_16x16x32_bf16 v[32:35], v[154:157], v[194:197], v[32:35]
	v_mfma_f32_16x16x32_bf16 v[20:23], v[146:149], v[204:207], v[20:23]
	v_mfma_f32_16x16x32_bf16 v[16:19], v[154:157], v[204:207], v[16:19]
	v_mfma_f32_16x16x32_bf16 v[60:63], v[150:153], v[182:185], v[60:63]
	v_mfma_f32_16x16x32_bf16 v[56:59], v[158:161], v[182:185], v[56:59]
	v_mfma_f32_16x16x32_bf16 v[52:55], v[150:153], v[190:193], v[52:55]
	v_mfma_f32_16x16x32_bf16 v[48:51], v[158:161], v[190:193], v[48:51]
	v_mfma_f32_16x16x32_bf16 v[36:39], v[150:153], v[198:201], v[36:39]
	v_mfma_f32_16x16x32_bf16 v[32:35], v[158:161], v[198:201], v[32:35]
	v_mfma_f32_16x16x32_bf16 v[20:23], v[150:153], v[208:211], v[20:23]
	v_mfma_f32_16x16x32_bf16 v[16:19], v[158:161], v[208:211], v[16:19]
	v_mfma_f32_16x16x32_bf16 v[44:47], v[162:165], v[178:181], v[44:47]
	v_mfma_f32_16x16x32_bf16 v[40:43], v[170:173], v[178:181], v[40:43]
	v_mfma_f32_16x16x32_bf16 v[28:31], v[162:165], v[186:189], v[28:31]
	v_mfma_f32_16x16x32_bf16 v[24:27], v[170:173], v[186:189], v[24:27]
	v_mfma_f32_16x16x32_bf16 v[12:15], v[162:165], v[194:197], v[12:15]
	v_mfma_f32_16x16x32_bf16 v[8:11], v[170:173], v[194:197], v[8:11]
	v_mfma_f32_16x16x32_bf16 v[4:7], v[162:165], v[204:207], v[4:7]
	v_mfma_f32_16x16x32_bf16 v[0:3], v[170:173], v[204:207], v[0:3]
	v_mfma_f32_16x16x32_bf16 v[44:47], v[166:169], v[182:185], v[44:47]
	v_mfma_f32_16x16x32_bf16 v[40:43], v[174:177], v[182:185], v[40:43]
	v_mfma_f32_16x16x32_bf16 v[28:31], v[166:169], v[190:193], v[28:31]
	v_mfma_f32_16x16x32_bf16 v[24:27], v[174:177], v[190:193], v[24:27]
	v_mfma_f32_16x16x32_bf16 v[12:15], v[166:169], v[198:201], v[12:15]
	v_mfma_f32_16x16x32_bf16 v[8:11], v[174:177], v[198:201], v[8:11]
	v_mfma_f32_16x16x32_bf16 v[4:7], v[166:169], v[208:211], v[4:7]
	v_mfma_f32_16x16x32_bf16 v[0:3], v[174:177], v[208:211], v[0:3]
	s_setprio 0
	s_barrier
	v_add_u32_e32 v145, s68, v137
	ds_read_b128 v[146:149], v145
	ds_read_b128 v[150:153], v145 offset:1024
	ds_read_b128 v[154:157], v145 offset:2048
	ds_read_b128 v[158:161], v145 offset:3072
	v_add_u32_e32 v145, s67, v137
	ds_read_b128 v[162:165], v145
	ds_read_b128 v[166:169], v145 offset:1024
	ds_read_b128 v[170:173], v145 offset:2048
	ds_read_b128 v[174:177], v145 offset:3072
	s_mov_b32 m0, s57
	v_lshl_add_u64 v[218:219], s[46:47], 0, v[128:129]
	ds_read_b128 v[178:181], v141 offset:32768
	ds_read_b128 v[182:185], v141 offset:33792
	ds_read_b128 v[186:189], v141 offset:34816
	ds_read_b128 v[190:193], v141 offset:35840
	ds_read_b128 v[194:197], v141 offset:36864
	ds_read_b128 v[198:201], v141 offset:37888
	ds_read_b128 v[204:207], v141 offset:38912
	ds_read_b128 v[208:211], v141 offset:39936
	global_load_lds_dwordx4 v[218:219], off
	v_lshl_add_u64 v[218:219], s[46:47], 0, v[132:133]
	s_mov_b32 m0, s58
	s_nop 0
	global_load_lds_dwordx4 v[218:219], off
	s_waitcnt vmcnt(8)
	s_waitcnt lgkmcnt(0)
	s_barrier
	s_setprio 1
	s_waitcnt lgkmcnt(0)
	v_mfma_f32_16x16x32_bf16 v[124:127], v[146:149], v[178:181], v[124:127]
	v_mfma_f32_16x16x32_bf16 v[120:123], v[154:157], v[178:181], v[120:123]
	v_mfma_f32_16x16x32_bf16 v[116:119], v[146:149], v[186:189], v[116:119]
	v_mfma_f32_16x16x32_bf16 v[112:115], v[154:157], v[186:189], v[112:115]
	v_mfma_f32_16x16x32_bf16 v[100:103], v[146:149], v[194:197], v[100:103]
	v_mfma_f32_16x16x32_bf16 v[96:99], v[154:157], v[194:197], v[96:99]
	v_mfma_f32_16x16x32_bf16 v[84:87], v[146:149], v[204:207], v[84:87]
	v_mfma_f32_16x16x32_bf16 v[80:83], v[154:157], v[204:207], v[80:83]
	v_mfma_f32_16x16x32_bf16 v[124:127], v[150:153], v[182:185], v[124:127]
	v_mfma_f32_16x16x32_bf16 v[120:123], v[158:161], v[182:185], v[120:123]
	v_mfma_f32_16x16x32_bf16 v[116:119], v[150:153], v[190:193], v[116:119]
	v_mfma_f32_16x16x32_bf16 v[112:115], v[158:161], v[190:193], v[112:115]
	v_mfma_f32_16x16x32_bf16 v[100:103], v[150:153], v[198:201], v[100:103]
	v_mfma_f32_16x16x32_bf16 v[96:99], v[158:161], v[198:201], v[96:99]
	v_mfma_f32_16x16x32_bf16 v[84:87], v[150:153], v[208:211], v[84:87]
	v_mfma_f32_16x16x32_bf16 v[80:83], v[158:161], v[208:211], v[80:83]
	v_mfma_f32_16x16x32_bf16 v[108:111], v[162:165], v[178:181], v[108:111]
	v_mfma_f32_16x16x32_bf16 v[104:107], v[170:173], v[178:181], v[104:107]
	v_mfma_f32_16x16x32_bf16 v[92:95], v[162:165], v[186:189], v[92:95]
	v_mfma_f32_16x16x32_bf16 v[88:91], v[170:173], v[186:189], v[88:91]
	v_mfma_f32_16x16x32_bf16 v[76:79], v[162:165], v[194:197], v[76:79]
	v_mfma_f32_16x16x32_bf16 v[72:75], v[170:173], v[194:197], v[72:75]
	v_mfma_f32_16x16x32_bf16 v[68:71], v[162:165], v[204:207], v[68:71]
	v_mfma_f32_16x16x32_bf16 v[64:67], v[170:173], v[204:207], v[64:67]
	v_mfma_f32_16x16x32_bf16 v[108:111], v[166:169], v[182:185], v[108:111]
	v_mfma_f32_16x16x32_bf16 v[104:107], v[174:177], v[182:185], v[104:107]
	v_mfma_f32_16x16x32_bf16 v[92:95], v[166:169], v[190:193], v[92:95]
	v_mfma_f32_16x16x32_bf16 v[88:91], v[174:177], v[190:193], v[88:91]
	v_mfma_f32_16x16x32_bf16 v[76:79], v[166:169], v[198:201], v[76:79]
	v_mfma_f32_16x16x32_bf16 v[72:75], v[174:177], v[198:201], v[72:75]
	v_mfma_f32_16x16x32_bf16 v[68:71], v[166:169], v[208:211], v[68:71]
	v_mfma_f32_16x16x32_bf16 v[64:67], v[174:177], v[208:211], v[64:67]
	s_setprio 0
	s_barrier
; #define PG8_STAGE(bufoff, gbase, voff) do { _Pragma("unroll") for (int _i = 0; _i < 2; ++_i) \
;         __builtin_amdgcn_global_load_lds((const unsigned*)((const char*)(gbase) + (voff)[_i]), (LAS unsigned*)(lds + (bufoff) + ldsw + _i * 8192), 16, 0, 0); } while (0)
; #define PG8_LDA(dst, b, h) do { _Pragma("unroll") for (int m = 0; m < 4; ++m) _Pragma("unroll") for (int k = 0; k < 2; ++k) dst[m][k] = *(const LAS bf16x8*)(lds + PG8_SA(b, h) + aoff + m * 2048 + k * 1024); } while (0)
; #define PG8_MMA(ai, bj, At, Bt) do { __builtin_amdgcn_s_setprio(1); _Pragma("unroll") for (int m = 0; m < 4; ++m) _Pragma("unroll") for (int n = 0; n < 2; ++n) _Pragma("unroll") for (int k = 0; k < 2; ++k) \
;         acc[ai][bj][m][n] = __builtin_amdgcn_mfma_f32_16x16x32_bf16(Bt[n][k], At[m][k], acc[ai][bj][m][n], 0, 0, 0); __builtin_amdgcn_s_setprio(0); } while (0)
; #define PG8_WAIT_V(n) asm volatile("s_waitcnt vmcnt(" #n ")" ::: "memory")
; #define PG8_WAIT_L(n) asm volatile("s_waitcnt lgkmcnt(" #n ")" ::: "memory")
; #define PG8_BAR __builtin_amdgcn_s_barrier()
; #define PG8_SCHED __builtin_amdgcn_sched_barrier(0)
; template <class Epi>
; __device__ __forceinline__ void gemm_phase(LAS unsigned char* lds, const Gemm g, const Sched& S, const Epi& E) {
;     ...
;             PG8_LDA(At, 1, 1); PG8_STAGE(PG8_SB(1, 0), b3, voffB); PG8_STAGE(PG8_SB(1, 1), b3 + hstepB, voffB); PG8_STAGE(PG8_SA(1, 0), a3, voffA);
;             PG8_WAIT_V(8); PG8_WAIT_L(0); PG8_BAR; PG8_MMA(1, 0, At, B0); PG8_MMA(1, 1, At, B1); PG8_BAR; PG8_SCHED;
;         }
;         if (wr == 0) PG8_BAR;
	s_mov_b32 m0, s66
	v_lshl_add_u64 v[142:143], v[142:143], 0, s[18:19]
	ds_read_b128 v[178:181], v141 offset:49152
	ds_read_b128 v[182:185], v141 offset:50176
	ds_read_b128 v[186:189], v141 offset:51200
	ds_read_b128 v[190:193], v141 offset:52224
	ds_read_b128 v[194:197], v141 offset:53248
	ds_read_b128 v[198:201], v141 offset:54272
	ds_read_b128 v[204:207], v141 offset:55296
	ds_read_b128 v[208:211], v141 offset:56320
	global_load_lds_dwordx4 v[142:143], off
	v_lshl_add_u64 v[142:143], v[212:213], 0, s[18:19]
	s_mov_b32 m0, s65
	s_nop 0
	global_load_lds_dwordx4 v[142:143], off
	v_lshl_add_u64 v[142:143], s[44:45], 0, v[130:131]
	s_mov_b32 m0, s74
	s_nop 0
	global_load_lds_dwordx4 v[142:143], off
	v_lshl_add_u64 v[142:143], s[44:45], 0, v[134:135]
	s_mov_b32 m0, s73
	s_nop 0
	global_load_lds_dwordx4 v[142:143], off
	v_lshl_add_u64 v[142:143], v[214:215], 0, s[18:19]
	s_mov_b32 m0, s60
	s_nop 0
	global_load_lds_dwordx4 v[142:143], off
	v_lshl_add_u64 v[142:143], v[216:217], 0, s[18:19]
	s_mov_b32 m0, s61
	s_nop 0
	global_load_lds_dwordx4 v[142:143], off
	s_waitcnt vmcnt(8)
	s_waitcnt lgkmcnt(0)
	s_barrier
	s_setprio 1
	s_waitcnt lgkmcnt(0)
	v_mfma_f32_16x16x32_bf16 v[60:63], v[146:149], v[178:181], v[60:63]
	v_mfma_f32_16x16x32_bf16 v[56:59], v[154:157], v[178:181], v[56:59]
	v_mfma_f32_16x16x32_bf16 v[52:55], v[146:149], v[186:189], v[52:55]
	v_mfma_f32_16x16x32_bf16 v[48:51], v[154:157], v[186:189], v[48:51]
	v_mfma_f32_16x16x32_bf16 v[36:39], v[146:149], v[194:197], v[36:39]
	v_mfma_f32_16x16x32_bf16 v[32:35], v[154:157], v[194:197], v[32:35]
	v_mfma_f32_16x16x32_bf16 v[20:23], v[146:149], v[204:207], v[20:23]
	v_mfma_f32_16x16x32_bf16 v[16:19], v[154:157], v[204:207], v[16:19]
	v_mfma_f32_16x16x32_bf16 v[60:63], v[150:153], v[182:185], v[60:63]
	v_mfma_f32_16x16x32_bf16 v[56:59], v[158:161], v[182:185], v[56:59]
	v_mfma_f32_16x16x32_bf16 v[52:55], v[150:153], v[190:193], v[52:55]
	v_mfma_f32_16x16x32_bf16 v[48:51], v[158:161], v[190:193], v[48:51]
	v_mfma_f32_16x16x32_bf16 v[36:39], v[150:153], v[198:201], v[36:39]
	v_mfma_f32_16x16x32_bf16 v[32:35], v[158:161], v[198:201], v[32:35]
	v_mfma_f32_16x16x32_bf16 v[20:23], v[150:153], v[208:211], v[20:23]
	v_mfma_f32_16x16x32_bf16 v[16:19], v[158:161], v[208:211], v[16:19]
	v_mfma_f32_16x16x32_bf16 v[44:47], v[162:165], v[178:181], v[44:47]
	v_mfma_f32_16x16x32_bf16 v[40:43], v[170:173], v[178:181], v[40:43]
	v_mfma_f32_16x16x32_bf16 v[28:31], v[162:165], v[186:189], v[28:31]
	v_mfma_f32_16x16x32_bf16 v[24:27], v[170:173], v[186:189], v[24:27]
	v_mfma_f32_16x16x32_bf16 v[12:15], v[162:165], v[194:197], v[12:15]
	v_mfma_f32_16x16x32_bf16 v[8:11], v[170:173], v[194:197], v[8:11]
	v_mfma_f32_16x16x32_bf16 v[4:7], v[162:165], v[204:207], v[4:7]
	v_mfma_f32_16x16x32_bf16 v[0:3], v[170:173], v[204:207], v[0:3]
	v_mfma_f32_16x16x32_bf16 v[44:47], v[166:169], v[182:185], v[44:47]
	v_mfma_f32_16x16x32_bf16 v[40:43], v[174:177], v[182:185], v[40:43]
	v_mfma_f32_16x16x32_bf16 v[28:31], v[166:169], v[190:193], v[28:31]
	v_mfma_f32_16x16x32_bf16 v[24:27], v[174:177], v[190:193], v[24:27]
	v_mfma_f32_16x16x32_bf16 v[12:15], v[166:169], v[198:201], v[12:15]
	v_mfma_f32_16x16x32_bf16 v[8:11], v[174:177], v[198:201], v[8:11]
	v_mfma_f32_16x16x32_bf16 v[4:7], v[166:169], v[208:211], v[4:7]
	v_mfma_f32_16x16x32_bf16 v[0:3], v[174:177], v[208:211], v[0:3]
	s_setprio 0
	s_barrier
	s_movk_i32 s46, 0x100
	s_andn2_b64 vcc, exec, s[42:43]
	s_mov_b64 s[44:45], -1
	s_mov_b64 s[42:43], 0
	s_cbranch_vccz .LBB0_1439
	s_and_b64 vcc, exec, s[20:21]
	s_cbranch_vccz .LBB0_1442
	s_barrier

; #define PG8_STAGE(bufoff, gbase, voff) do { _Pragma("unroll") for (int _i = 0; _i < 2; ++_i) \
;         __builtin_amdgcn_global_load_lds((const unsigned*)((const char*)(gbase) + (voff)[_i]), (LAS unsigned*)(lds + (bufoff) + ldsw + _i * 8192), 16, 0, 0); } while (0)
; #define PG8_LDA(dst, b, h) do { _Pragma("unroll") for (int m = 0; m < 4; ++m) _Pragma("unroll") for (int k = 0; k < 2; ++k) dst[m][k] = *(const LAS bf16x8*)(lds + PG8_SA(b, h) + aoff + m * 2048 + k * 1024); } while (0)
; #define PG8_LDB(dst, b, h) do { _Pragma("unroll") for (int n = 0; n < 2; ++n) _Pragma("unroll") for (int k = 0; k < 2; ++k) dst[n][k] = *(const LAS bf16x8*)(lds + PG8_SB(b, h) + boff + n * 2048 + k * 1024); } while (0)
; #define PG8_MMA(ai, bj, At, Bt) do { __builtin_amdgcn_s_setprio(1); _Pragma("unroll") for (int m = 0; m < 4; ++m) _Pragma("unroll") for (int n = 0; n < 2; ++n) _Pragma("unroll") for (int k = 0; k < 2; ++k) \
;         acc[ai][bj][m][n] = __builtin_amdgcn_mfma_f32_16x16x32_bf16(Bt[n][k], At[m][k], acc[ai][bj][m][n], 0, 0, 0); __builtin_amdgcn_s_setprio(0); } while (0)
; #define PG8_WAIT_V(n) asm volatile("s_waitcnt vmcnt(" #n ")" ::: "memory")
; #define PG8_WAIT_L(n) asm volatile("s_waitcnt lgkmcnt(" #n ")" ::: "memory")
; #define PG8_BAR __builtin_amdgcn_s_barrier()
; #define PG8_SCHED __builtin_amdgcn_sched_barrier(0)
; template <class Epi>
; __device__ __forceinline__ void gemm_phase(LAS unsigned char* lds, const Gemm g, const Sched& S, const Epi& E) {
;     ...
;             const bool last = (t == nt - 2);
;             const char* a1 = cA + (size_t)(t + 1) * kstep;
;             const char* a2 = last ? nA : cA + (size_t)(t + 2) * kstep; const char* b2 = last ? nB : cB + (size_t)(t + 2) * kstep;
;             const char* a3 = a2 + kstep; const char* b3 = b2 + kstep;
;             PG8_LDB(B0, 0, 0); PG8_LDB(B1, 0, 1); PG8_SCHED; PG8_LDA(At, 0, 0); PG8_STAGE(PG8_SA(1, 1), a1 + hstepA, voffA);
;             PG8_WAIT_V(8); PG8_WAIT_L(0); PG8_BAR; PG8_MMA(0, 0, At, B0); PG8_MMA(0, 1, At, B1); PG8_BAR; PG8_SCHED;
;             PG8_LDA(At, 0, 1); PG8_STAGE(PG8_SB(0, 0), b2, voffB); PG8_STAGE(PG8_SB(0, 1), b2 + hstepB, voffB); PG8_STAGE(PG8_SA(0, 0), a2, voffA);
;             PG8_WAIT_V(8); PG8_WAIT_L(0); PG8_BAR; PG8_MMA(1, 0, At, B0); PG8_MMA(1, 1, At, B1); PG8_BAR; PG8_SCHED;
.LBB0_1731:
	ds_read_b128 v[148:151], v145
	ds_read_b128 v[152:155], v145 offset:1024
	ds_read_b128 v[156:159], v145 offset:2048
	ds_read_b128 v[160:163], v145 offset:3072
	ds_read_b128 v[164:167], v146
	ds_read_b128 v[168:171], v146 offset:1024
	ds_read_b128 v[172:175], v146 offset:2048
	ds_read_b128 v[176:179], v146 offset:3072
	s_add_u32 s28, s26, 0xfffc0080
	s_addc_u32 s29, s27, -1
	s_cmp_eq_u32 s53, 12
	s_cselect_b32 s37, s17, s29
	s_cselect_b32 s36, s23, s28
	s_cselect_b32 s29, s15, s52
	s_cselect_b32 s28, s50, s51
	v_lshl_add_u64 v[140:141], s[26:27], 0, v[136:137]
	s_add_i32 m0, s25, 0xc000
	ds_read_b128 v[180:183], v147
	ds_read_b128 v[184:187], v147 offset:1024
	ds_read_b128 v[188:191], v147 offset:2048
	ds_read_b128 v[192:195], v147 offset:3072
	ds_read_b128 v[196:199], v147 offset:4096
	ds_read_b128 v[204:207], v147 offset:5120
	ds_read_b128 v[208:211], v147 offset:6144
	ds_read_b128 v[212:215], v147 offset:7168
	global_load_lds_dwordx4 v[140:141], off
	v_lshl_add_u64 v[140:141], s[26:27], 0, v[138:139]
	s_add_i32 m0, s25, 0xe000
	s_nop 0
	global_load_lds_dwordx4 v[140:141], off
	s_waitcnt vmcnt(8)
	s_waitcnt lgkmcnt(0)
	s_barrier
	s_setprio 1
	s_waitcnt lgkmcnt(0)
	v_mfma_f32_16x16x32_bf16 v[116:119], v[148:151], v[180:183], v[116:119]
	v_mfma_f32_16x16x32_bf16 v[124:127], v[156:159], v[180:183], v[124:127]
	v_mfma_f32_16x16x32_bf16 v[100:103], v[148:151], v[188:191], v[100:103]
	v_mfma_f32_16x16x32_bf16 v[108:111], v[156:159], v[188:191], v[108:111]
	v_mfma_f32_16x16x32_bf16 v[84:87], v[148:151], v[196:199], v[84:87]
	v_mfma_f32_16x16x32_bf16 v[92:95], v[156:159], v[196:199], v[92:95]
	v_mfma_f32_16x16x32_bf16 v[68:71], v[148:151], v[208:211], v[68:71]
	v_mfma_f32_16x16x32_bf16 v[76:79], v[156:159], v[208:211], v[76:79]
	v_mfma_f32_16x16x32_bf16 v[116:119], v[152:155], v[184:187], v[116:119]
	v_mfma_f32_16x16x32_bf16 v[124:127], v[160:163], v[184:187], v[124:127]
	v_mfma_f32_16x16x32_bf16 v[100:103], v[152:155], v[192:195], v[100:103]
	v_mfma_f32_16x16x32_bf16 v[108:111], v[160:163], v[192:195], v[108:111]
	v_mfma_f32_16x16x32_bf16 v[84:87], v[152:155], v[204:207], v[84:87]
	v_mfma_f32_16x16x32_bf16 v[92:95], v[160:163], v[204:207], v[92:95]
	v_mfma_f32_16x16x32_bf16 v[68:71], v[152:155], v[212:215], v[68:71]
	v_mfma_f32_16x16x32_bf16 v[76:79], v[160:163], v[212:215], v[76:79]
	v_mfma_f32_16x16x32_bf16 v[112:115], v[164:167], v[180:183], v[112:115]
	v_mfma_f32_16x16x32_bf16 v[120:123], v[172:175], v[180:183], v[120:123]
	v_mfma_f32_16x16x32_bf16 v[96:99], v[164:167], v[188:191], v[96:99]
	v_mfma_f32_16x16x32_bf16 v[104:107], v[172:175], v[188:191], v[104:107]
	v_mfma_f32_16x16x32_bf16 v[80:83], v[164:167], v[196:199], v[80:83]
	v_mfma_f32_16x16x32_bf16 v[88:91], v[172:175], v[196:199], v[88:91]
	v_mfma_f32_16x16x32_bf16 v[64:67], v[164:167], v[208:211], v[64:67]
	v_mfma_f32_16x16x32_bf16 v[72:75], v[172:175], v[208:211], v[72:75]
	v_mfma_f32_16x16x32_bf16 v[112:115], v[168:171], v[184:187], v[112:115]
	v_mfma_f32_16x16x32_bf16 v[120:123], v[176:179], v[184:187], v[120:123]
	v_mfma_f32_16x16x32_bf16 v[96:99], v[168:171], v[192:195], v[96:99]
	v_mfma_f32_16x16x32_bf16 v[104:107], v[176:179], v[192:195], v[104:107]
	v_mfma_f32_16x16x32_bf16 v[80:83], v[168:171], v[204:207], v[80:83]
	v_mfma_f32_16x16x32_bf16 v[88:91], v[176:179], v[204:207], v[88:91]
	v_mfma_f32_16x16x32_bf16 v[64:67], v[168:171], v[212:215], v[64:67]
	v_mfma_f32_16x16x32_bf16 v[72:75], v[176:179], v[212:215], v[72:75]
	s_setprio 0
	s_barrier
	s_add_i32 s54, s46, s39
	v_lshl_add_u64 v[140:141], s[28:29], 0, v[130:131]
	s_mov_b32 m0, s54
	ds_read_b128 v[180:183], v147 offset:16384
	ds_read_b128 v[184:187], v147 offset:17408
	ds_read_b128 v[188:191], v147 offset:18432
	ds_read_b128 v[192:195], v147 offset:19456
	ds_read_b128 v[196:199], v147 offset:20480
	ds_read_b128 v[204:207], v147 offset:21504
	ds_read_b128 v[208:211], v147 offset:22528
	ds_read_b128 v[212:215], v147 offset:23552
	global_load_lds_dwordx4 v[140:141], off
	s_add_i32 m0, s54, 0x2000
	s_add_u32 s54, s28, 0x40000
	v_lshl_add_u64 v[200:201], s[28:29], 0, v[134:135]
	s_addc_u32 s55, s29, 0
	s_add_i32 s56, s47, s39
	global_load_lds_dwordx4 v[200:201], off
	v_lshl_add_u64 v[216:217], s[54:55], 0, v[130:131]
	s_mov_b32 m0, s56
	v_lshl_add_u64 v[218:219], s[36:37], 0, v[132:133]
	global_load_lds_dwordx4 v[216:217], off
	v_lshl_add_u64 v[216:217], s[54:55], 0, v[134:135]
	s_add_i32 m0, s56, 0x2000
	s_nop 0
	global_load_lds_dwordx4 v[216:217], off
	v_lshl_add_u64 v[216:217], s[36:37], 0, v[128:129]
	s_mov_b32 m0, s25
	s_nop 0
	global_load_lds_dwordx4 v[216:217], off
	s_mov_b32 m0, s40
	s_nop 0
	global_load_lds_dwordx4 v[218:219], off
	s_waitcnt vmcnt(8)
	s_waitcnt lgkmcnt(0)
	s_barrier
; #define PG8_STAGE(bufoff, gbase, voff) do { _Pragma("unroll") for (int _i = 0; _i < 2; ++_i) \
;         __builtin_amdgcn_global_load_lds((const unsigned*)((const char*)(gbase) + (voff)[_i]), (LAS unsigned*)(lds + (bufoff) + ldsw + _i * 8192), 16, 0, 0); } while (0)
; #define PG8_LDA(dst, b, h) do { _Pragma("unroll") for (int m = 0; m < 4; ++m) _Pragma("unroll") for (int k = 0; k < 2; ++k) dst[m][k] = *(const LAS bf16x8*)(lds + PG8_SA(b, h) + aoff + m * 2048 + k * 1024); } while (0)
; #define PG8_LDB(dst, b, h) do { _Pragma("unroll") for (int n = 0; n < 2; ++n) _Pragma("unroll") for (int k = 0; k < 2; ++k) dst[n][k] = *(const LAS bf16x8*)(lds + PG8_SB(b, h) + boff + n * 2048 + k * 1024); } while (0)
; #define PG8_MMA(ai, bj, At, Bt) do { __builtin_amdgcn_s_setprio(1); _Pragma("unroll") for (int m = 0; m < 4; ++m) _Pragma("unroll") for (int n = 0; n < 2; ++n) _Pragma("unroll") for (int k = 0; k < 2; ++k) \
;         acc[ai][bj][m][n] = __builtin_amdgcn_mfma_f32_16x16x32_bf16(Bt[n][k], At[m][k], acc[ai][bj][m][n], 0, 0, 0); __builtin_amdgcn_s_setprio(0); } while (0)
; #define PG8_WAIT_V(n) asm volatile("s_waitcnt vmcnt(" #n ")" ::: "memory")
; #define PG8_WAIT_L(n) asm volatile("s_waitcnt lgkmcnt(" #n ")" ::: "memory")
; #define PG8_BAR __builtin_amdgcn_s_barrier()
; #define PG8_SCHED __builtin_amdgcn_sched_barrier(0)
; template <class Epi>
; __device__ __forceinline__ void gemm_phase(LAS unsigned char* lds, const Gemm g, const Sched& S, const Epi& E) {
;     ...
;             PG8_WAIT_V(8); PG8_WAIT_L(0); PG8_BAR; PG8_MMA(1, 0, At, B0); PG8_MMA(1, 1, At, B1); PG8_BAR; PG8_SCHED;
;             PG8_LDB(B0, 1, 0); PG8_LDB(B1, 1, 1); PG8_SCHED; PG8_LDA(At, 1, 0); PG8_STAGE(PG8_SA(0, 1), a2 + hstepA, voffA);
;             PG8_WAIT_V(8); PG8_WAIT_L(0); PG8_BAR; PG8_MMA(0, 0, At, B0); PG8_MMA(0, 1, At, B1); PG8_BAR; PG8_SCHED;
	s_setprio 1
	s_waitcnt lgkmcnt(0)
	v_mfma_f32_16x16x32_bf16 v[52:55], v[148:151], v[180:183], v[52:55]
	v_mfma_f32_16x16x32_bf16 v[60:63], v[156:159], v[180:183], v[60:63]
	v_mfma_f32_16x16x32_bf16 v[36:39], v[148:151], v[188:191], v[36:39]
	v_mfma_f32_16x16x32_bf16 v[44:47], v[156:159], v[188:191], v[44:47]
	v_mfma_f32_16x16x32_bf16 v[20:23], v[148:151], v[196:199], v[20:23]
	v_mfma_f32_16x16x32_bf16 v[28:31], v[156:159], v[196:199], v[28:31]
	v_mfma_f32_16x16x32_bf16 v[4:7], v[148:151], v[208:211], v[4:7]
	v_mfma_f32_16x16x32_bf16 v[12:15], v[156:159], v[208:211], v[12:15]
	v_mfma_f32_16x16x32_bf16 v[52:55], v[152:155], v[184:187], v[52:55]
	v_mfma_f32_16x16x32_bf16 v[60:63], v[160:163], v[184:187], v[60:63]
	v_mfma_f32_16x16x32_bf16 v[36:39], v[152:155], v[192:195], v[36:39]
	v_mfma_f32_16x16x32_bf16 v[44:47], v[160:163], v[192:195], v[44:47]
	v_mfma_f32_16x16x32_bf16 v[20:23], v[152:155], v[204:207], v[20:23]
	v_mfma_f32_16x16x32_bf16 v[28:31], v[160:163], v[204:207], v[28:31]
	v_mfma_f32_16x16x32_bf16 v[4:7], v[152:155], v[212:215], v[4:7]
	v_mfma_f32_16x16x32_bf16 v[12:15], v[160:163], v[212:215], v[12:15]
	v_mfma_f32_16x16x32_bf16 v[48:51], v[164:167], v[180:183], v[48:51]
	v_mfma_f32_16x16x32_bf16 v[56:59], v[172:175], v[180:183], v[56:59]
	v_mfma_f32_16x16x32_bf16 v[32:35], v[164:167], v[188:191], v[32:35]
	v_mfma_f32_16x16x32_bf16 v[40:43], v[172:175], v[188:191], v[40:43]
	v_mfma_f32_16x16x32_bf16 v[16:19], v[164:167], v[196:199], v[16:19]
	v_mfma_f32_16x16x32_bf16 v[24:27], v[172:175], v[196:199], v[24:27]
	v_mfma_f32_16x16x32_bf16 v[0:3], v[164:167], v[208:211], v[0:3]
	v_mfma_f32_16x16x32_bf16 v[8:11], v[172:175], v[208:211], v[8:11]
	v_mfma_f32_16x16x32_bf16 v[48:51], v[168:171], v[184:187], v[48:51]
	v_mfma_f32_16x16x32_bf16 v[56:59], v[176:179], v[184:187], v[56:59]
	v_mfma_f32_16x16x32_bf16 v[32:35], v[168:171], v[192:195], v[32:35]
	v_mfma_f32_16x16x32_bf16 v[40:43], v[176:179], v[192:195], v[40:43]
	v_mfma_f32_16x16x32_bf16 v[16:19], v[168:171], v[204:207], v[16:19]
	v_mfma_f32_16x16x32_bf16 v[24:27], v[176:179], v[204:207], v[24:27]
	v_mfma_f32_16x16x32_bf16 v[0:3], v[168:171], v[212:215], v[0:3]
	v_mfma_f32_16x16x32_bf16 v[8:11], v[176:179], v[212:215], v[8:11]
	s_setprio 0
	s_barrier
	s_add_i32 s54, 0, 0x18000
	s_add_i32 s55, 0, 0x1c000
	v_add_u32_e32 v160, s54, v143
	v_add_u32_e32 v176, s55, v143
	ds_read_b128 v[148:151], v160
	ds_read_b128 v[152:155], v160 offset:1024
	ds_read_b128 v[156:159], v160 offset:2048
	ds_read_b128 v[160:163], v160 offset:3072
	ds_read_b128 v[164:167], v176
	ds_read_b128 v[168:171], v176 offset:1024
	ds_read_b128 v[172:175], v176 offset:2048
	ds_read_b128 v[176:179], v176 offset:3072
	s_add_u32 s36, s36, 0x40000
	s_addc_u32 s37, s37, 0
	s_mov_b32 m0, s41
	v_lshl_add_u64 v[220:221], s[36:37], 0, v[128:129]
	ds_read_b128 v[180:183], v147 offset:32768
	ds_read_b128 v[184:187], v147 offset:33792
	ds_read_b128 v[188:191], v147 offset:34816
	ds_read_b128 v[192:195], v147 offset:35840
	ds_read_b128 v[196:199], v147 offset:36864
	ds_read_b128 v[204:207], v147 offset:37888
	ds_read_b128 v[208:211], v147 offset:38912
	ds_read_b128 v[212:215], v147 offset:39936
	global_load_lds_dwordx4 v[220:221], off
	v_lshl_add_u64 v[220:221], s[36:37], 0, v[132:133]
	s_mov_b32 m0, s42
	s_nop 0
	global_load_lds_dwordx4 v[220:221], off
	s_waitcnt vmcnt(8)
	s_waitcnt lgkmcnt(0)
	s_barrier
	s_setprio 1
	s_waitcnt lgkmcnt(0)
	v_mfma_f32_16x16x32_bf16 v[116:119], v[148:151], v[180:183], v[116:119]
	v_mfma_f32_16x16x32_bf16 v[124:127], v[156:159], v[180:183], v[124:127]
	v_mfma_f32_16x16x32_bf16 v[100:103], v[148:151], v[188:191], v[100:103]
	v_mfma_f32_16x16x32_bf16 v[108:111], v[156:159], v[188:191], v[108:111]
	v_mfma_f32_16x16x32_bf16 v[84:87], v[148:151], v[196:199], v[84:87]
	v_mfma_f32_16x16x32_bf16 v[92:95], v[156:159], v[196:199], v[92:95]
	v_mfma_f32_16x16x32_bf16 v[68:71], v[148:151], v[208:211], v[68:71]
	v_mfma_f32_16x16x32_bf16 v[76:79], v[156:159], v[208:211], v[76:79]
	v_mfma_f32_16x16x32_bf16 v[116:119], v[152:155], v[184:187], v[116:119]
	v_mfma_f32_16x16x32_bf16 v[124:127], v[160:163], v[184:187], v[124:127]
	v_mfma_f32_16x16x32_bf16 v[100:103], v[152:155], v[192:195], v[100:103]
	v_mfma_f32_16x16x32_bf16 v[108:111], v[160:163], v[192:195], v[108:111]
	v_mfma_f32_16x16x32_bf16 v[84:87], v[152:155], v[204:207], v[84:87]
	v_mfma_f32_16x16x32_bf16 v[92:95], v[160:163], v[204:207], v[92:95]
	v_mfma_f32_16x16x32_bf16 v[68:71], v[152:155], v[212:215], v[68:71]
	v_mfma_f32_16x16x32_bf16 v[76:79], v[160:163], v[212:215], v[76:79]
	v_mfma_f32_16x16x32_bf16 v[112:115], v[164:167], v[180:183], v[112:115]
	v_mfma_f32_16x16x32_bf16 v[120:123], v[172:175], v[180:183], v[120:123]
	v_mfma_f32_16x16x32_bf16 v[96:99], v[164:167], v[188:191], v[96:99]
	v_mfma_f32_16x16x32_bf16 v[104:107], v[172:175], v[188:191], v[104:107]
	v_mfma_f32_16x16x32_bf16 v[80:83], v[164:167], v[196:199], v[80:83]
	v_mfma_f32_16x16x32_bf16 v[88:91], v[172:175], v[196:199], v[88:91]
	v_mfma_f32_16x16x32_bf16 v[64:67], v[164:167], v[208:211], v[64:67]
	v_mfma_f32_16x16x32_bf16 v[72:75], v[172:175], v[208:211], v[72:75]
	v_mfma_f32_16x16x32_bf16 v[112:115], v[168:171], v[184:187], v[112:115]
	v_mfma_f32_16x16x32_bf16 v[120:123], v[176:179], v[184:187], v[120:123]
	v_mfma_f32_16x16x32_bf16 v[96:99], v[168:171], v[192:195], v[96:99]
	v_mfma_f32_16x16x32_bf16 v[104:107], v[176:179], v[192:195], v[104:107]
	v_mfma_f32_16x16x32_bf16 v[80:83], v[168:171], v[204:207], v[80:83]
	v_mfma_f32_16x16x32_bf16 v[88:91], v[176:179], v[204:207], v[88:91]
	v_mfma_f32_16x16x32_bf16 v[64:67], v[168:171], v[212:215], v[64:67]
	v_mfma_f32_16x16x32_bf16 v[72:75], v[176:179], v[212:215], v[72:75]
	s_setprio 0
	s_barrier
; #define PG8_STAGE(bufoff, gbase, voff) do { _Pragma("unroll") for (int _i = 0; _i < 2; ++_i) \
;         __builtin_amdgcn_global_load_lds((const unsigned*)((const char*)(gbase) + (voff)[_i]), (LAS unsigned*)(lds + (bufoff) + ldsw + _i * 8192), 16, 0, 0); } while (0)
; #define PG8_LDA(dst, b, h) do { _Pragma("unroll") for (int m = 0; m < 4; ++m) _Pragma("unroll") for (int k = 0; k < 2; ++k) dst[m][k] = *(const LAS bf16x8*)(lds + PG8_SA(b, h) + aoff + m * 2048 + k * 1024); } while (0)
; #define PG8_MMA(ai, bj, At, Bt) do { __builtin_amdgcn_s_setprio(1); _Pragma("unroll") for (int m = 0; m < 4; ++m) _Pragma("unroll") for (int n = 0; n < 2; ++n) _Pragma("unroll") for (int k = 0; k < 2; ++k) \
;         acc[ai][bj][m][n] = __builtin_amdgcn_mfma_f32_16x16x32_bf16(Bt[n][k], At[m][k], acc[ai][bj][m][n], 0, 0, 0); __builtin_amdgcn_s_setprio(0); } while (0)
; #define PG8_WAIT_V(n) asm volatile("s_waitcnt vmcnt(" #n ")" ::: "memory")
; #define PG8_WAIT_L(n) asm volatile("s_waitcnt lgkmcnt(" #n ")" ::: "memory")
; #define PG8_BAR __builtin_amdgcn_s_barrier()
; #define PG8_SCHED __builtin_amdgcn_sched_barrier(0)
; template <class Epi>
; __device__ __forceinline__ void gemm_phase(LAS unsigned char* lds, const Gemm g, const Sched& S, const Epi& E) {
;     ...
;             PG8_LDA(At, 1, 1); PG8_STAGE(PG8_SB(1, 0), b3, voffB); PG8_STAGE(PG8_SB(1, 1), b3 + hstepB, voffB); PG8_STAGE(PG8_SA(1, 0), a3, voffA);
;             PG8_WAIT_V(8); PG8_WAIT_L(0); PG8_BAR; PG8_MMA(1, 0, At, B0); PG8_MMA(1, 1, At, B1); PG8_BAR; PG8_SCHED;
;         }
;         if (wr == 0) PG8_BAR;
	s_add_i32 s36, s54, s39
	v_lshl_add_u64 v[140:141], v[140:141], 0, s[4:5]
	s_mov_b32 m0, s36
	ds_read_b128 v[180:183], v147 offset:49152
	ds_read_b128 v[184:187], v147 offset:50176
	ds_read_b128 v[188:191], v147 offset:51200
	ds_read_b128 v[192:195], v147 offset:52224
	ds_read_b128 v[196:199], v147 offset:53248
	ds_read_b128 v[204:207], v147 offset:54272
	ds_read_b128 v[208:211], v147 offset:55296
	ds_read_b128 v[212:215], v147 offset:56320
	global_load_lds_dwordx4 v[140:141], off
	s_add_i32 m0, s36, 0x2000
	s_add_u32 s28, s28, 0x40080
	v_lshl_add_u64 v[140:141], v[200:201], 0, s[4:5]
	s_addc_u32 s29, s29, 0
	s_add_i32 s36, s55, s39
	global_load_lds_dwordx4 v[140:141], off
	v_lshl_add_u64 v[140:141], s[28:29], 0, v[130:131]
	s_mov_b32 m0, s36
	s_nop 0
	global_load_lds_dwordx4 v[140:141], off
	v_lshl_add_u64 v[140:141], s[28:29], 0, v[134:135]
	s_add_i32 m0, s36, 0x2000
	s_nop 0
	global_load_lds_dwordx4 v[140:141], off
	v_lshl_add_u64 v[140:141], v[216:217], 0, s[4:5]
	s_mov_b32 m0, s44
	s_nop 0
	global_load_lds_dwordx4 v[140:141], off
	v_lshl_add_u64 v[140:141], v[218:219], 0, s[4:5]
	s_mov_b32 m0, s45
	s_nop 0
	global_load_lds_dwordx4 v[140:141], off
	s_waitcnt vmcnt(8)
	s_waitcnt lgkmcnt(0)
	s_barrier
	s_setprio 1
	s_waitcnt lgkmcnt(0)
	v_mfma_f32_16x16x32_bf16 v[52:55], v[148:151], v[180:183], v[52:55]
	v_mfma_f32_16x16x32_bf16 v[60:63], v[156:159], v[180:183], v[60:63]
	v_mfma_f32_16x16x32_bf16 v[36:39], v[148:151], v[188:191], v[36:39]
	v_mfma_f32_16x16x32_bf16 v[44:47], v[156:159], v[188:191], v[44:47]
	v_mfma_f32_16x16x32_bf16 v[20:23], v[148:151], v[196:199], v[20:23]
	v_mfma_f32_16x16x32_bf16 v[28:31], v[156:159], v[196:199], v[28:31]
	v_mfma_f32_16x16x32_bf16 v[4:7], v[148:151], v[208:211], v[4:7]
	v_mfma_f32_16x16x32_bf16 v[12:15], v[156:159], v[208:211], v[12:15]
	v_mfma_f32_16x16x32_bf16 v[52:55], v[152:155], v[184:187], v[52:55]
	v_mfma_f32_16x16x32_bf16 v[60:63], v[160:163], v[184:187], v[60:63]
	v_mfma_f32_16x16x32_bf16 v[36:39], v[152:155], v[192:195], v[36:39]
	v_mfma_f32_16x16x32_bf16 v[44:47], v[160:163], v[192:195], v[44:47]
	v_mfma_f32_16x16x32_bf16 v[20:23], v[152:155], v[204:207], v[20:23]
	v_mfma_f32_16x16x32_bf16 v[28:31], v[160:163], v[204:207], v[28:31]
	v_mfma_f32_16x16x32_bf16 v[4:7], v[152:155], v[212:215], v[4:7]
	v_mfma_f32_16x16x32_bf16 v[12:15], v[160:163], v[212:215], v[12:15]
	v_mfma_f32_16x16x32_bf16 v[48:51], v[164:167], v[180:183], v[48:51]
	v_mfma_f32_16x16x32_bf16 v[56:59], v[172:175], v[180:183], v[56:59]
	v_mfma_f32_16x16x32_bf16 v[32:35], v[164:167], v[188:191], v[32:35]
	v_mfma_f32_16x16x32_bf16 v[40:43], v[172:175], v[188:191], v[40:43]
	v_mfma_f32_16x16x32_bf16 v[16:19], v[164:167], v[196:199], v[16:19]
	v_mfma_f32_16x16x32_bf16 v[24:27], v[172:175], v[196:199], v[24:27]
	v_mfma_f32_16x16x32_bf16 v[0:3], v[164:167], v[208:211], v[0:3]
	v_mfma_f32_16x16x32_bf16 v[8:11], v[172:175], v[208:211], v[8:11]
	v_mfma_f32_16x16x32_bf16 v[48:51], v[168:171], v[184:187], v[48:51]
	v_mfma_f32_16x16x32_bf16 v[56:59], v[176:179], v[184:187], v[56:59]
	v_mfma_f32_16x16x32_bf16 v[32:35], v[168:171], v[192:195], v[32:35]
	v_mfma_f32_16x16x32_bf16 v[40:43], v[176:179], v[192:195], v[40:43]
	v_mfma_f32_16x16x32_bf16 v[16:19], v[168:171], v[204:207], v[16:19]
	v_mfma_f32_16x16x32_bf16 v[24:27], v[176:179], v[204:207], v[24:27]
	v_mfma_f32_16x16x32_bf16 v[0:3], v[168:171], v[212:215], v[0:3]
	v_mfma_f32_16x16x32_bf16 v[8:11], v[176:179], v[212:215], v[8:11]
	s_setprio 0
	s_barrier
	s_add_i32 s53, s53, 2
	s_add_u32 s26, s26, 0x100
	s_addc_u32 s27, s27, 0
	s_add_u32 s51, s51, 0x100
	s_addc_u32 s52, s52, 0
	s_cmp_gt_u32 s53, 13
	s_cbranch_scc0 .LBB0_1731
	s_and_b64 vcc, exec, s[6:7]
	s_cbranch_vccz .LBB0_1734
	s_barrier

; #define PG8_STAGE(bufoff, gbase, voff) do { _Pragma("unroll") for (int _i = 0; _i < 2; ++_i) \
;         __builtin_amdgcn_global_load_lds((const unsigned*)((const char*)(gbase) + (voff)[_i]), (LAS unsigned*)(lds + (bufoff) + ldsw + _i * 8192), 16, 0, 0); } while (0)
; #define PG8_LDA(dst, b, h) do { _Pragma("unroll") for (int m = 0; m < 4; ++m) _Pragma("unroll") for (int k = 0; k < 2; ++k) dst[m][k] = *(const LAS bf16x8*)(lds + PG8_SA(b, h) + aoff + m * 2048 + k * 1024); } while (0)
; #define PG8_LDB(dst, b, h) do { _Pragma("unroll") for (int n = 0; n < 2; ++n) _Pragma("unroll") for (int k = 0; k < 2; ++k) dst[n][k] = *(const LAS bf16x8*)(lds + PG8_SB(b, h) + boff + n * 2048 + k * 1024); } while (0)
; #define PG8_MMA(ai, bj, At, Bt) do { __builtin_amdgcn_s_setprio(1); _Pragma("unroll") for (int m = 0; m < 4; ++m) _Pragma("unroll") for (int n = 0; n < 2; ++n) _Pragma("unroll") for (int k = 0; k < 2; ++k) \
;         acc[ai][bj][m][n] = __builtin_amdgcn_mfma_f32_16x16x32_bf16(Bt[n][k], At[m][k], acc[ai][bj][m][n], 0, 0, 0); __builtin_amdgcn_s_setprio(0); } while (0)
; #define PG8_WAIT_V(n) asm volatile("s_waitcnt vmcnt(" #n ")" ::: "memory")
; #define PG8_WAIT_L(n) asm volatile("s_waitcnt lgkmcnt(" #n ")" ::: "memory")
; #define PG8_BAR __builtin_amdgcn_s_barrier()
; #define PG8_SCHED __builtin_amdgcn_sched_barrier(0)
; template <class Epi>
; __device__ __forceinline__ void gemm_phase(LAS unsigned char* lds, const Gemm g, const Sched& S, const Epi& E) {
;     ...
;             const bool last = (t == nt - 2);
;             const char* a1 = cA + (size_t)(t + 1) * kstep;
;             const char* a2 = last ? nA : cA + (size_t)(t + 2) * kstep; const char* b2 = last ? nB : cB + (size_t)(t + 2) * kstep;
;             const char* a3 = a2 + kstep; const char* b3 = b2 + kstep;
;             PG8_LDB(B0, 0, 0); PG8_LDB(B1, 0, 1); PG8_SCHED; PG8_LDA(At, 0, 0); PG8_STAGE(PG8_SA(1, 1), a1 + hstepA, voffA);
;             PG8_WAIT_V(8); PG8_WAIT_L(0); PG8_BAR; PG8_MMA(0, 0, At, B0); PG8_MMA(0, 1, At, B1); PG8_BAR; PG8_SCHED;
;             PG8_LDA(At, 0, 1); PG8_STAGE(PG8_SB(0, 0), b2, voffB); PG8_STAGE(PG8_SB(0, 1), b2 + hstepB, voffB); PG8_STAGE(PG8_SA(0, 0), a2, voffA);
;             PG8_WAIT_V(8); PG8_WAIT_L(0); PG8_BAR; PG8_MMA(1, 0, At, B0); PG8_MMA(1, 1, At, B1); PG8_BAR; PG8_SCHED;
.LBB0_1827:
	v_add_u32_e32 v158, s54, v144
	v_add_u32_e32 v174, s55, v144
	s_add_u32 s36, s26, s28
	ds_read_b128 v[146:149], v158
	ds_read_b128 v[150:153], v158 offset:1024
	ds_read_b128 v[154:157], v158 offset:2048
	ds_read_b128 v[158:161], v158 offset:3072
	ds_read_b128 v[162:165], v174
	ds_read_b128 v[166:169], v174 offset:1024
	ds_read_b128 v[170:173], v174 offset:2048
	ds_read_b128 v[174:177], v174 offset:3072
	s_addc_u32 s37, s27, s29
	s_add_u32 s36, s36, 0x100
	s_addc_u32 s37, s37, 0
	s_add_u32 s66, s63, s28
	s_addc_u32 s67, s64, s29
	s_cmpk_eq_i32 s28, 0x1500
	s_cselect_b32 s39, s23, s37
	s_cselect_b32 s38, s22, s36
	s_cselect_b32 s37, s25, s67
	s_cselect_b32 s36, s24, s66
	s_mov_b32 m0, s56
	v_lshl_add_u64 v[214:215], v[140:141], 0, s[28:29]
	ds_read_b128 v[178:181], v145
	ds_read_b128 v[182:185], v145 offset:1024
	ds_read_b128 v[186:189], v145 offset:2048
	ds_read_b128 v[190:193], v145 offset:3072
	ds_read_b128 v[194:197], v145 offset:4096
	ds_read_b128 v[198:201], v145 offset:5120
	ds_read_b128 v[206:209], v145 offset:6144
	ds_read_b128 v[210:213], v145 offset:7168
	global_load_lds_dwordx4 v[214:215], off
	v_lshl_add_u64 v[214:215], v[142:143], 0, s[28:29]
	s_mov_b32 m0, s57
	s_nop 0
	global_load_lds_dwordx4 v[214:215], off
	s_waitcnt vmcnt(8)
	s_waitcnt lgkmcnt(0)
	s_barrier
	s_setprio 1
	s_waitcnt lgkmcnt(0)
	v_mfma_f32_16x16x32_bf16 v[124:127], v[146:149], v[178:181], v[124:127]
	v_mfma_f32_16x16x32_bf16 v[120:123], v[154:157], v[178:181], v[120:123]
	v_mfma_f32_16x16x32_bf16 v[108:111], v[146:149], v[186:189], v[108:111]
	v_mfma_f32_16x16x32_bf16 v[104:107], v[154:157], v[186:189], v[104:107]
	v_mfma_f32_16x16x32_bf16 v[92:95], v[146:149], v[194:197], v[92:95]
	v_mfma_f32_16x16x32_bf16 v[88:91], v[154:157], v[194:197], v[88:91]
	v_mfma_f32_16x16x32_bf16 v[76:79], v[146:149], v[206:209], v[76:79]
	v_mfma_f32_16x16x32_bf16 v[72:75], v[154:157], v[206:209], v[72:75]
	v_mfma_f32_16x16x32_bf16 v[124:127], v[150:153], v[182:185], v[124:127]
	v_mfma_f32_16x16x32_bf16 v[120:123], v[158:161], v[182:185], v[120:123]
	v_mfma_f32_16x16x32_bf16 v[108:111], v[150:153], v[190:193], v[108:111]
	v_mfma_f32_16x16x32_bf16 v[104:107], v[158:161], v[190:193], v[104:107]
	v_mfma_f32_16x16x32_bf16 v[92:95], v[150:153], v[198:201], v[92:95]
	v_mfma_f32_16x16x32_bf16 v[88:91], v[158:161], v[198:201], v[88:91]
	v_mfma_f32_16x16x32_bf16 v[76:79], v[150:153], v[210:213], v[76:79]
	v_mfma_f32_16x16x32_bf16 v[72:75], v[158:161], v[210:213], v[72:75]
	v_mfma_f32_16x16x32_bf16 v[116:119], v[162:165], v[178:181], v[116:119]
	v_mfma_f32_16x16x32_bf16 v[112:115], v[170:173], v[178:181], v[112:115]
	v_mfma_f32_16x16x32_bf16 v[100:103], v[162:165], v[186:189], v[100:103]
	v_mfma_f32_16x16x32_bf16 v[96:99], v[170:173], v[186:189], v[96:99]
	v_mfma_f32_16x16x32_bf16 v[84:87], v[162:165], v[194:197], v[84:87]
	v_mfma_f32_16x16x32_bf16 v[80:83], v[170:173], v[194:197], v[80:83]
	v_mfma_f32_16x16x32_bf16 v[68:71], v[162:165], v[206:209], v[68:71]
	v_mfma_f32_16x16x32_bf16 v[64:67], v[170:173], v[206:209], v[64:67]
	v_mfma_f32_16x16x32_bf16 v[116:119], v[166:169], v[182:185], v[116:119]
	v_mfma_f32_16x16x32_bf16 v[112:115], v[174:177], v[182:185], v[112:115]
	v_mfma_f32_16x16x32_bf16 v[100:103], v[166:169], v[190:193], v[100:103]
	v_mfma_f32_16x16x32_bf16 v[96:99], v[174:177], v[190:193], v[96:99]
	v_mfma_f32_16x16x32_bf16 v[84:87], v[166:169], v[198:201], v[84:87]
	v_mfma_f32_16x16x32_bf16 v[80:83], v[174:177], v[198:201], v[80:83]
	v_mfma_f32_16x16x32_bf16 v[68:71], v[166:169], v[210:213], v[68:71]
	v_mfma_f32_16x16x32_bf16 v[64:67], v[174:177], v[210:213], v[64:67]
	s_setprio 0
	s_barrier
	s_mov_b32 m0, s58
	v_lshl_add_u64 v[214:215], s[36:37], 0, v[130:131]
	ds_read_b128 v[178:181], v145 offset:16384
	ds_read_b128 v[182:185], v145 offset:17408
	ds_read_b128 v[186:189], v145 offset:18432
	ds_read_b128 v[190:193], v145 offset:19456
	ds_read_b128 v[194:197], v145 offset:20480
	ds_read_b128 v[198:201], v145 offset:21504
	ds_read_b128 v[206:209], v145 offset:22528
	ds_read_b128 v[210:213], v145 offset:23552
	global_load_lds_dwordx4 v[214:215], off
	s_add_i32 m0, s58, 0x2000
	s_add_u32 s66, s36, 0xb0000
	v_lshl_add_u64 v[216:217], s[36:37], 0, v[134:135]
	s_addc_u32 s67, s37, 0
	s_add_i32 s68, s55, s46
	global_load_lds_dwordx4 v[216:217], off
	v_lshl_add_u64 v[218:219], s[66:67], 0, v[130:131]
	s_mov_b32 m0, s68
	v_lshl_add_u64 v[220:221], s[38:39], 0, v[132:133]
	global_load_lds_dwordx4 v[218:219], off
	v_lshl_add_u64 v[218:219], s[66:67], 0, v[134:135]
	s_add_i32 m0, s68, 0x2000
	s_nop 0
	global_load_lds_dwordx4 v[218:219], off
	v_lshl_add_u64 v[218:219], s[38:39], 0, v[128:129]
	s_mov_b32 m0, s47
	s_nop 0
	global_load_lds_dwordx4 v[218:219], off
	s_mov_b32 m0, s48
	s_nop 0
	global_load_lds_dwordx4 v[220:221], off
	s_waitcnt vmcnt(8)
	s_waitcnt lgkmcnt(0)
	s_barrier
; #define PG8_STAGE(bufoff, gbase, voff) do { _Pragma("unroll") for (int _i = 0; _i < 2; ++_i) \
;         __builtin_amdgcn_global_load_lds((const unsigned*)((const char*)(gbase) + (voff)[_i]), (LAS unsigned*)(lds + (bufoff) + ldsw + _i * 8192), 16, 0, 0); } while (0)
; #define PG8_LDA(dst, b, h) do { _Pragma("unroll") for (int m = 0; m < 4; ++m) _Pragma("unroll") for (int k = 0; k < 2; ++k) dst[m][k] = *(const LAS bf16x8*)(lds + PG8_SA(b, h) + aoff + m * 2048 + k * 1024); } while (0)
; #define PG8_LDB(dst, b, h) do { _Pragma("unroll") for (int n = 0; n < 2; ++n) _Pragma("unroll") for (int k = 0; k < 2; ++k) dst[n][k] = *(const LAS bf16x8*)(lds + PG8_SB(b, h) + boff + n * 2048 + k * 1024); } while (0)
; #define PG8_MMA(ai, bj, At, Bt) do { __builtin_amdgcn_s_setprio(1); _Pragma("unroll") for (int m = 0; m < 4; ++m) _Pragma("unroll") for (int n = 0; n < 2; ++n) _Pragma("unroll") for (int k = 0; k < 2; ++k) \
;         acc[ai][bj][m][n] = __builtin_amdgcn_mfma_f32_16x16x32_bf16(Bt[n][k], At[m][k], acc[ai][bj][m][n], 0, 0, 0); __builtin_amdgcn_s_setprio(0); } while (0)
; #define PG8_WAIT_V(n) asm volatile("s_waitcnt vmcnt(" #n ")" ::: "memory")
; #define PG8_WAIT_L(n) asm volatile("s_waitcnt lgkmcnt(" #n ")" ::: "memory")
; #define PG8_BAR __builtin_amdgcn_s_barrier()
; #define PG8_SCHED __builtin_amdgcn_sched_barrier(0)
; template <class Epi>
; __device__ __forceinline__ void gemm_phase(LAS unsigned char* lds, const Gemm g, const Sched& S, const Epi& E) {
;     ...
;             PG8_WAIT_V(8); PG8_WAIT_L(0); PG8_BAR; PG8_MMA(1, 0, At, B0); PG8_MMA(1, 1, At, B1); PG8_BAR; PG8_SCHED;
;             PG8_LDB(B0, 1, 0); PG8_LDB(B1, 1, 1); PG8_SCHED; PG8_LDA(At, 1, 0); PG8_STAGE(PG8_SA(0, 1), a2 + hstepA, voffA);
;             PG8_WAIT_V(8); PG8_WAIT_L(0); PG8_BAR; PG8_MMA(0, 0, At, B0); PG8_MMA(0, 1, At, B1); PG8_BAR; PG8_SCHED;
	s_setprio 1
	s_waitcnt lgkmcnt(0)
	v_mfma_f32_16x16x32_bf16 v[60:63], v[146:149], v[178:181], v[60:63]
	v_mfma_f32_16x16x32_bf16 v[56:59], v[154:157], v[178:181], v[56:59]
	v_mfma_f32_16x16x32_bf16 v[44:47], v[146:149], v[186:189], v[44:47]
	v_mfma_f32_16x16x32_bf16 v[40:43], v[154:157], v[186:189], v[40:43]
	v_mfma_f32_16x16x32_bf16 v[28:31], v[146:149], v[194:197], v[28:31]
	v_mfma_f32_16x16x32_bf16 v[24:27], v[154:157], v[194:197], v[24:27]
	v_mfma_f32_16x16x32_bf16 v[12:15], v[146:149], v[206:209], v[12:15]
	v_mfma_f32_16x16x32_bf16 v[8:11], v[154:157], v[206:209], v[8:11]
	v_mfma_f32_16x16x32_bf16 v[60:63], v[150:153], v[182:185], v[60:63]
	v_mfma_f32_16x16x32_bf16 v[56:59], v[158:161], v[182:185], v[56:59]
	v_mfma_f32_16x16x32_bf16 v[44:47], v[150:153], v[190:193], v[44:47]
	v_mfma_f32_16x16x32_bf16 v[40:43], v[158:161], v[190:193], v[40:43]
	v_mfma_f32_16x16x32_bf16 v[28:31], v[150:153], v[198:201], v[28:31]
	v_mfma_f32_16x16x32_bf16 v[24:27], v[158:161], v[198:201], v[24:27]
	v_mfma_f32_16x16x32_bf16 v[12:15], v[150:153], v[210:213], v[12:15]
	v_mfma_f32_16x16x32_bf16 v[8:11], v[158:161], v[210:213], v[8:11]
	v_mfma_f32_16x16x32_bf16 v[52:55], v[162:165], v[178:181], v[52:55]
	v_mfma_f32_16x16x32_bf16 v[48:51], v[170:173], v[178:181], v[48:51]
	v_mfma_f32_16x16x32_bf16 v[36:39], v[162:165], v[186:189], v[36:39]
	v_mfma_f32_16x16x32_bf16 v[32:35], v[170:173], v[186:189], v[32:35]
	v_mfma_f32_16x16x32_bf16 v[20:23], v[162:165], v[194:197], v[20:23]
	v_mfma_f32_16x16x32_bf16 v[16:19], v[170:173], v[194:197], v[16:19]
	v_mfma_f32_16x16x32_bf16 v[4:7], v[162:165], v[206:209], v[4:7]
	v_mfma_f32_16x16x32_bf16 v[0:3], v[170:173], v[206:209], v[0:3]
	v_mfma_f32_16x16x32_bf16 v[52:55], v[166:169], v[182:185], v[52:55]
	v_mfma_f32_16x16x32_bf16 v[48:51], v[174:177], v[182:185], v[48:51]
	v_mfma_f32_16x16x32_bf16 v[36:39], v[166:169], v[190:193], v[36:39]
	v_mfma_f32_16x16x32_bf16 v[32:35], v[174:177], v[190:193], v[32:35]
	v_mfma_f32_16x16x32_bf16 v[20:23], v[166:169], v[198:201], v[20:23]
	v_mfma_f32_16x16x32_bf16 v[16:19], v[174:177], v[198:201], v[16:19]
	v_mfma_f32_16x16x32_bf16 v[4:7], v[166:169], v[210:213], v[4:7]
	v_mfma_f32_16x16x32_bf16 v[0:3], v[174:177], v[210:213], v[0:3]
	s_setprio 0
	s_barrier
	s_add_i32 s66, 0, 0x18000
	s_add_i32 s67, 0, 0x1c000
	v_add_u32_e32 v158, s66, v144
	v_add_u32_e32 v174, s67, v144
	ds_read_b128 v[146:149], v158
	ds_read_b128 v[150:153], v158 offset:1024
	ds_read_b128 v[154:157], v158 offset:2048
	ds_read_b128 v[158:161], v158 offset:3072
	ds_read_b128 v[162:165], v174
	ds_read_b128 v[166:169], v174 offset:1024
	ds_read_b128 v[170:173], v174 offset:2048
	ds_read_b128 v[174:177], v174 offset:3072
	s_add_u32 s38, s38, 0xb0000
	s_addc_u32 s39, s39, 0
	s_mov_b32 m0, s49
	v_lshl_add_u64 v[222:223], s[38:39], 0, v[128:129]
	ds_read_b128 v[178:181], v145 offset:32768
	ds_read_b128 v[182:185], v145 offset:33792
	ds_read_b128 v[186:189], v145 offset:34816
	ds_read_b128 v[190:193], v145 offset:35840
	ds_read_b128 v[194:197], v145 offset:36864
	ds_read_b128 v[198:201], v145 offset:37888
	ds_read_b128 v[206:209], v145 offset:38912
	ds_read_b128 v[210:213], v145 offset:39936
	global_load_lds_dwordx4 v[222:223], off
	v_lshl_add_u64 v[222:223], s[38:39], 0, v[132:133]
	s_mov_b32 m0, s50
	s_nop 0
	global_load_lds_dwordx4 v[222:223], off
	s_waitcnt vmcnt(8)
	s_waitcnt lgkmcnt(0)
	s_barrier
	s_setprio 1
	s_waitcnt lgkmcnt(0)
	v_mfma_f32_16x16x32_bf16 v[124:127], v[146:149], v[178:181], v[124:127]
	v_mfma_f32_16x16x32_bf16 v[120:123], v[154:157], v[178:181], v[120:123]
	v_mfma_f32_16x16x32_bf16 v[108:111], v[146:149], v[186:189], v[108:111]
	v_mfma_f32_16x16x32_bf16 v[104:107], v[154:157], v[186:189], v[104:107]
	v_mfma_f32_16x16x32_bf16 v[92:95], v[146:149], v[194:197], v[92:95]
	v_mfma_f32_16x16x32_bf16 v[88:91], v[154:157], v[194:197], v[88:91]
	v_mfma_f32_16x16x32_bf16 v[76:79], v[146:149], v[206:209], v[76:79]
	v_mfma_f32_16x16x32_bf16 v[72:75], v[154:157], v[206:209], v[72:75]
	v_mfma_f32_16x16x32_bf16 v[124:127], v[150:153], v[182:185], v[124:127]
	v_mfma_f32_16x16x32_bf16 v[120:123], v[158:161], v[182:185], v[120:123]
	v_mfma_f32_16x16x32_bf16 v[108:111], v[150:153], v[190:193], v[108:111]
	v_mfma_f32_16x16x32_bf16 v[104:107], v[158:161], v[190:193], v[104:107]
	v_mfma_f32_16x16x32_bf16 v[92:95], v[150:153], v[198:201], v[92:95]
	v_mfma_f32_16x16x32_bf16 v[88:91], v[158:161], v[198:201], v[88:91]
	v_mfma_f32_16x16x32_bf16 v[76:79], v[150:153], v[210:213], v[76:79]
	v_mfma_f32_16x16x32_bf16 v[72:75], v[158:161], v[210:213], v[72:75]
	v_mfma_f32_16x16x32_bf16 v[116:119], v[162:165], v[178:181], v[116:119]
	v_mfma_f32_16x16x32_bf16 v[112:115], v[170:173], v[178:181], v[112:115]
	v_mfma_f32_16x16x32_bf16 v[100:103], v[162:165], v[186:189], v[100:103]
	v_mfma_f32_16x16x32_bf16 v[96:99], v[170:173], v[186:189], v[96:99]
	v_mfma_f32_16x16x32_bf16 v[84:87], v[162:165], v[194:197], v[84:87]
	v_mfma_f32_16x16x32_bf16 v[80:83], v[170:173], v[194:197], v[80:83]
	v_mfma_f32_16x16x32_bf16 v[68:71], v[162:165], v[206:209], v[68:71]
	v_mfma_f32_16x16x32_bf16 v[64:67], v[170:173], v[206:209], v[64:67]
	v_mfma_f32_16x16x32_bf16 v[116:119], v[166:169], v[182:185], v[116:119]
	v_mfma_f32_16x16x32_bf16 v[112:115], v[174:177], v[182:185], v[112:115]
	v_mfma_f32_16x16x32_bf16 v[100:103], v[166:169], v[190:193], v[100:103]
	v_mfma_f32_16x16x32_bf16 v[96:99], v[174:177], v[190:193], v[96:99]
	v_mfma_f32_16x16x32_bf16 v[84:87], v[166:169], v[198:201], v[84:87]
	v_mfma_f32_16x16x32_bf16 v[80:83], v[174:177], v[198:201], v[80:83]
	v_mfma_f32_16x16x32_bf16 v[68:71], v[166:169], v[210:213], v[68:71]
	v_mfma_f32_16x16x32_bf16 v[64:67], v[174:177], v[210:213], v[64:67]
	s_setprio 0
	s_barrier
; #define PG8_STAGE(bufoff, gbase, voff) do { _Pragma("unroll") for (int _i = 0; _i < 2; ++_i) \
;         __builtin_amdgcn_global_load_lds((const unsigned*)((const char*)(gbase) + (voff)[_i]), (LAS unsigned*)(lds + (bufoff) + ldsw + _i * 8192), 16, 0, 0); } while (0)
; #define PG8_LDA(dst, b, h) do { _Pragma("unroll") for (int m = 0; m < 4; ++m) _Pragma("unroll") for (int k = 0; k < 2; ++k) dst[m][k] = *(const LAS bf16x8*)(lds + PG8_SA(b, h) + aoff + m * 2048 + k * 1024); } while (0)
; #define PG8_MMA(ai, bj, At, Bt) do { __builtin_amdgcn_s_setprio(1); _Pragma("unroll") for (int m = 0; m < 4; ++m) _Pragma("unroll") for (int n = 0; n < 2; ++n) _Pragma("unroll") for (int k = 0; k < 2; ++k) \
;         acc[ai][bj][m][n] = __builtin_amdgcn_mfma_f32_16x16x32_bf16(Bt[n][k], At[m][k], acc[ai][bj][m][n], 0, 0, 0); __builtin_amdgcn_s_setprio(0); } while (0)
; #define PG8_WAIT_V(n) asm volatile("s_waitcnt vmcnt(" #n ")" ::: "memory")
; #define PG8_WAIT_L(n) asm volatile("s_waitcnt lgkmcnt(" #n ")" ::: "memory")
; #define PG8_BAR __builtin_amdgcn_s_barrier()
; #define PG8_SCHED __builtin_amdgcn_sched_barrier(0)
; template <class Epi>
; __device__ __forceinline__ void gemm_phase(LAS unsigned char* lds, const Gemm g, const Sched& S, const Epi& E) {
;     ...
;             PG8_LDA(At, 1, 1); PG8_STAGE(PG8_SB(1, 0), b3, voffB); PG8_STAGE(PG8_SB(1, 1), b3 + hstepB, voffB); PG8_STAGE(PG8_SA(1, 0), a3, voffA);
;             PG8_WAIT_V(8); PG8_WAIT_L(0); PG8_BAR; PG8_MMA(1, 0, At, B0); PG8_MMA(1, 1, At, B1); PG8_BAR; PG8_SCHED;
;         }
;         if (wr == 0) PG8_BAR;
	s_add_i32 s38, s66, s46
	v_lshl_add_u64 v[214:215], v[214:215], 0, s[16:17]
	s_mov_b32 m0, s38
	ds_read_b128 v[178:181], v145 offset:49152
	ds_read_b128 v[182:185], v145 offset:50176
	ds_read_b128 v[186:189], v145 offset:51200
	ds_read_b128 v[190:193], v145 offset:52224
	ds_read_b128 v[194:197], v145 offset:53248
	ds_read_b128 v[198:201], v145 offset:54272
	ds_read_b128 v[206:209], v145 offset:55296
	ds_read_b128 v[210:213], v145 offset:56320
	global_load_lds_dwordx4 v[214:215], off
	s_add_i32 m0, s38, 0x2000
	s_add_u32 s36, s36, 0xb0080
	v_lshl_add_u64 v[214:215], v[216:217], 0, s[16:17]
	s_addc_u32 s37, s37, 0
	s_add_i32 s38, s67, s46
	global_load_lds_dwordx4 v[214:215], off
	v_lshl_add_u64 v[214:215], s[36:37], 0, v[130:131]
	s_mov_b32 m0, s38
	s_nop 0
	global_load_lds_dwordx4 v[214:215], off
	v_lshl_add_u64 v[214:215], s[36:37], 0, v[134:135]
	s_add_i32 m0, s38, 0x2000
	s_nop 0
	global_load_lds_dwordx4 v[214:215], off
	v_lshl_add_u64 v[214:215], v[218:219], 0, s[16:17]
	s_mov_b32 m0, s52
	s_nop 0
	global_load_lds_dwordx4 v[214:215], off
	v_lshl_add_u64 v[214:215], v[220:221], 0, s[16:17]
	s_mov_b32 m0, s53
	s_nop 0
	global_load_lds_dwordx4 v[214:215], off
	s_waitcnt vmcnt(8)
	s_waitcnt lgkmcnt(0)
	s_barrier
	s_setprio 1
	s_waitcnt lgkmcnt(0)
	v_mfma_f32_16x16x32_bf16 v[60:63], v[146:149], v[178:181], v[60:63]
	v_mfma_f32_16x16x32_bf16 v[56:59], v[154:157], v[178:181], v[56:59]
	v_mfma_f32_16x16x32_bf16 v[44:47], v[146:149], v[186:189], v[44:47]
	v_mfma_f32_16x16x32_bf16 v[40:43], v[154:157], v[186:189], v[40:43]
	v_mfma_f32_16x16x32_bf16 v[28:31], v[146:149], v[194:197], v[28:31]
	v_mfma_f32_16x16x32_bf16 v[24:27], v[154:157], v[194:197], v[24:27]
	v_mfma_f32_16x16x32_bf16 v[12:15], v[146:149], v[206:209], v[12:15]
	v_mfma_f32_16x16x32_bf16 v[8:11], v[154:157], v[206:209], v[8:11]
	v_mfma_f32_16x16x32_bf16 v[60:63], v[150:153], v[182:185], v[60:63]
	v_mfma_f32_16x16x32_bf16 v[56:59], v[158:161], v[182:185], v[56:59]
	v_mfma_f32_16x16x32_bf16 v[44:47], v[150:153], v[190:193], v[44:47]
	v_mfma_f32_16x16x32_bf16 v[40:43], v[158:161], v[190:193], v[40:43]
	v_mfma_f32_16x16x32_bf16 v[28:31], v[150:153], v[198:201], v[28:31]
	v_mfma_f32_16x16x32_bf16 v[24:27], v[158:161], v[198:201], v[24:27]
	v_mfma_f32_16x16x32_bf16 v[12:15], v[150:153], v[210:213], v[12:15]
	v_mfma_f32_16x16x32_bf16 v[8:11], v[158:161], v[210:213], v[8:11]
	v_mfma_f32_16x16x32_bf16 v[52:55], v[162:165], v[178:181], v[52:55]
	v_mfma_f32_16x16x32_bf16 v[48:51], v[170:173], v[178:181], v[48:51]
	v_mfma_f32_16x16x32_bf16 v[36:39], v[162:165], v[186:189], v[36:39]
	v_mfma_f32_16x16x32_bf16 v[32:35], v[170:173], v[186:189], v[32:35]
	v_mfma_f32_16x16x32_bf16 v[20:23], v[162:165], v[194:197], v[20:23]
	v_mfma_f32_16x16x32_bf16 v[16:19], v[170:173], v[194:197], v[16:19]
	v_mfma_f32_16x16x32_bf16 v[4:7], v[162:165], v[206:209], v[4:7]
	v_mfma_f32_16x16x32_bf16 v[0:3], v[170:173], v[206:209], v[0:3]
	v_mfma_f32_16x16x32_bf16 v[52:55], v[166:169], v[182:185], v[52:55]
	v_mfma_f32_16x16x32_bf16 v[48:51], v[174:177], v[182:185], v[48:51]
	v_mfma_f32_16x16x32_bf16 v[36:39], v[166:169], v[190:193], v[36:39]
	v_mfma_f32_16x16x32_bf16 v[32:35], v[174:177], v[190:193], v[32:35]
	v_mfma_f32_16x16x32_bf16 v[20:23], v[166:169], v[198:201], v[20:23]
	v_mfma_f32_16x16x32_bf16 v[16:19], v[174:177], v[198:201], v[16:19]
	v_mfma_f32_16x16x32_bf16 v[4:7], v[166:169], v[210:213], v[4:7]
	v_mfma_f32_16x16x32_bf16 v[0:3], v[174:177], v[210:213], v[0:3]
	s_setprio 0
	s_barrier
	s_add_i32 s65, s65, 2
	s_add_u32 s28, s28, 0x100
	s_addc_u32 s29, s29, 0
	s_cmp_gt_u32 s65, 41
	s_cbranch_scc0 .LBB0_1827
	s_and_b64 vcc, exec, s[18:19]
	s_cbranch_vccz .LBB0_1830
	s_barrier
